# v57 + P12 top-k: second compaction loop (keys == T) skipped when the first loop already produced 256 entries
# speedup vs baseline: 1.0018x; 1.0018x over previous
; DI unsigned mbcnt64(unsigned long long m) { return __builtin_amdgcn_mbcnt_hi((unsigned)(m >> 32), __builtin_amdgcn_mbcnt_lo((unsigned)m, 0u)); }
; template <int NV>
; DI void topk_row(const float* row, int s, LAS int* lst, int lane) {
;     ...
;     int bgt = 0;
; #pragma unroll
;     for (int j = 0; j < NV; ++j) { const bool sg = key[j] > T; const unsigned long long mg = __ballot(sg); if (sg) lst[bgt + (int)mbcnt64(mg)] = j * 64 + lane; bgt += __builtin_popcountll(mg); }
; #pragma unroll
;     for (int j = 0; j < NV; ++j) { const bool se = key[j] == T; const unsigned long long me = __ballot(se); const int pe = bgt + (int)mbcnt64(me); if (se && pe < 256) lst[pe] = j * 64 + lane; bgt += __builtin_popcountll(me); }
.LBB0_2226:
	s_or_b64 exec, exec, s[0:1]
	s_bcnt1_i32_b64 s0, vcc
	v_cmp_eq_u32_e32 vcc, v141, v34
	s_add_i32 s2, s2, s0
	s_cmpk_eq_i32 s2, 0x100
	s_cbranch_scc1 .Lp12_skip2_0
	s_nop 0
	v_mbcnt_lo_u32_b32 v53, vcc_lo, 0
	v_mbcnt_hi_u32_b32 v53, vcc_hi, v53
	v_add_u32_e32 v53, s2, v53
	v_cmp_gt_i32_e64 s[4:5], s21, v53
	s_and_b64 s[4:5], vcc, s[4:5]
	s_and_saveexec_b64 s[0:1], s[4:5]
	v_lshl_add_u32 v53, v53, 2, s20
	ds_write_b32 v53, v2
	s_or_b64 exec, exec, s[0:1]
	s_bcnt1_i32_b64 s0, vcc
	v_cmp_eq_u32_e32 vcc, v140, v34
	s_add_i32 s2, s2, s0
	s_nop 0
	v_mbcnt_lo_u32_b32 v53, vcc_lo, 0
	v_mbcnt_hi_u32_b32 v53, vcc_hi, v53
	v_add_u32_e32 v53, s2, v53
	v_cmp_gt_i32_e64 s[4:5], s21, v53
	s_and_b64 s[4:5], vcc, s[4:5]
	s_and_saveexec_b64 s[0:1], s[4:5]
	v_lshl_add_u32 v53, v53, 2, s20
	ds_write_b32 v53, v4
	s_or_b64 exec, exec, s[0:1]
	s_bcnt1_i32_b64 s0, vcc
	v_cmp_eq_u32_e32 vcc, v139, v34
	s_add_i32 s2, s2, s0
	s_nop 0
	v_mbcnt_lo_u32_b32 v53, vcc_lo, 0
	v_mbcnt_hi_u32_b32 v53, vcc_hi, v53
	v_add_u32_e32 v53, s2, v53
	v_cmp_gt_i32_e64 s[4:5], s21, v53
	s_and_b64 s[4:5], vcc, s[4:5]
	s_and_saveexec_b64 s[0:1], s[4:5]
	v_lshl_add_u32 v53, v53, 2, s20
	ds_write_b32 v53, v6
	s_or_b64 exec, exec, s[0:1]
	s_bcnt1_i32_b64 s0, vcc
	v_cmp_eq_u32_e32 vcc, v138, v34
	s_add_i32 s2, s2, s0
	s_nop 0
	v_mbcnt_lo_u32_b32 v53, vcc_lo, 0
	v_mbcnt_hi_u32_b32 v53, vcc_hi, v53
	v_add_u32_e32 v53, s2, v53
	v_cmp_gt_i32_e64 s[4:5], s21, v53
	s_and_b64 s[4:5], vcc, s[4:5]
	s_and_saveexec_b64 s[0:1], s[4:5]
	v_lshl_add_u32 v53, v53, 2, s20
	ds_write_b32 v53, v8
	s_or_b64 exec, exec, s[0:1]
	s_bcnt1_i32_b64 s0, vcc
	v_cmp_eq_u32_e32 vcc, v137, v34
	s_add_i32 s2, s2, s0
	s_nop 0
	v_mbcnt_lo_u32_b32 v53, vcc_lo, 0
	v_mbcnt_hi_u32_b32 v53, vcc_hi, v53
	v_add_u32_e32 v53, s2, v53
	v_cmp_gt_i32_e64 s[4:5], s21, v53
	s_and_b64 s[4:5], vcc, s[4:5]
	s_and_saveexec_b64 s[0:1], s[4:5]
	v_lshl_add_u32 v53, v53, 2, s20
	ds_write_b32 v53, v10
	s_or_b64 exec, exec, s[0:1]
	s_bcnt1_i32_b64 s0, vcc
	v_cmp_eq_u32_e32 vcc, v136, v34
	s_add_i32 s2, s2, s0
	s_nop 0
	v_mbcnt_lo_u32_b32 v53, vcc_lo, 0
	v_mbcnt_hi_u32_b32 v53, vcc_hi, v53
	v_add_u32_e32 v53, s2, v53
	v_cmp_gt_i32_e64 s[4:5], s21, v53
	s_and_b64 s[4:5], vcc, s[4:5]
	s_and_saveexec_b64 s[0:1], s[4:5]
	v_lshl_add_u32 v53, v53, 2, s20
	ds_write_b32 v53, v12
	s_or_b64 exec, exec, s[0:1]
	s_bcnt1_i32_b64 s0, vcc
	v_cmp_eq_u32_e32 vcc, v135, v34
	s_add_i32 s2, s2, s0
	s_nop 0
	v_mbcnt_lo_u32_b32 v53, vcc_lo, 0
	v_mbcnt_hi_u32_b32 v53, vcc_hi, v53
	v_add_u32_e32 v53, s2, v53
	v_cmp_gt_i32_e64 s[4:5], s21, v53
	s_and_b64 s[4:5], vcc, s[4:5]
	s_and_saveexec_b64 s[0:1], s[4:5]
	v_lshl_add_u32 v53, v53, 2, s20
	ds_write_b32 v53, v14
	s_or_b64 exec, exec, s[0:1]
	s_bcnt1_i32_b64 s0, vcc
	v_cmp_eq_u32_e32 vcc, v134, v34
	s_add_i32 s2, s2, s0
	s_nop 0
	v_mbcnt_lo_u32_b32 v53, vcc_lo, 0
	v_mbcnt_hi_u32_b32 v53, vcc_hi, v53
	v_add_u32_e32 v53, s2, v53
	v_cmp_gt_i32_e64 s[4:5], s21, v53
	s_and_b64 s[4:5], vcc, s[4:5]
	s_and_saveexec_b64 s[0:1], s[4:5]
	v_lshl_add_u32 v53, v53, 2, s20
	ds_write_b32 v53, v16
	s_or_b64 exec, exec, s[0:1]
	s_bcnt1_i32_b64 s0, vcc
	v_cmp_eq_u32_e32 vcc, v133, v34
	s_add_i32 s2, s2, s0
	s_nop 0
	v_mbcnt_lo_u32_b32 v53, vcc_lo, 0
	v_mbcnt_hi_u32_b32 v53, vcc_hi, v53
	v_add_u32_e32 v53, s2, v53
	v_cmp_gt_i32_e64 s[4:5], s21, v53
	s_and_b64 s[4:5], vcc, s[4:5]
	s_and_saveexec_b64 s[0:1], s[4:5]
	v_lshl_add_u32 v53, v53, 2, s20
	ds_write_b32 v53, v18
	s_or_b64 exec, exec, s[0:1]
	s_bcnt1_i32_b64 s0, vcc
	v_cmp_eq_u32_e32 vcc, v132, v34
	s_add_i32 s2, s2, s0
	s_nop 0
	v_mbcnt_lo_u32_b32 v53, vcc_lo, 0
	v_mbcnt_hi_u32_b32 v53, vcc_hi, v53
	v_add_u32_e32 v53, s2, v53
	v_cmp_gt_i32_e64 s[4:5], s21, v53
	s_and_b64 s[4:5], vcc, s[4:5]
	s_and_saveexec_b64 s[0:1], s[4:5]
	v_lshl_add_u32 v53, v53, 2, s20
	ds_write_b32 v53, v20
	s_or_b64 exec, exec, s[0:1]
	s_bcnt1_i32_b64 s0, vcc
	v_cmp_eq_u32_e32 vcc, v251, v34
	s_add_i32 s2, s2, s0
	s_nop 0
	v_mbcnt_lo_u32_b32 v53, vcc_lo, 0
	v_mbcnt_hi_u32_b32 v53, vcc_hi, v53
	v_add_u32_e32 v53, s2, v53
	v_cmp_gt_i32_e64 s[4:5], s21, v53
	s_and_b64 s[4:5], vcc, s[4:5]
	s_and_saveexec_b64 s[0:1], s[4:5]
	v_lshl_add_u32 v53, v53, 2, s20
	ds_write_b32 v53, v22
	s_or_b64 exec, exec, s[0:1]
	s_bcnt1_i32_b64 s0, vcc
	v_cmp_eq_u32_e32 vcc, v248, v34
	s_add_i32 s2, s2, s0
	s_nop 0
	v_mbcnt_lo_u32_b32 v53, vcc_lo, 0
	v_mbcnt_hi_u32_b32 v53, vcc_hi, v53
	v_add_u32_e32 v53, s2, v53
	v_cmp_gt_i32_e64 s[4:5], s21, v53
	s_and_b64 s[4:5], vcc, s[4:5]
	s_and_saveexec_b64 s[0:1], s[4:5]
	v_lshl_add_u32 v53, v53, 2, s20
	ds_write_b32 v53, v24
	s_or_b64 exec, exec, s[0:1]
	s_bcnt1_i32_b64 s0, vcc
	v_cmp_eq_u32_e32 vcc, v247, v34
	s_add_i32 s2, s2, s0
	s_nop 0
	v_mbcnt_lo_u32_b32 v53, vcc_lo, 0
	v_mbcnt_hi_u32_b32 v53, vcc_hi, v53
	v_add_u32_e32 v53, s2, v53
	v_cmp_gt_i32_e64 s[4:5], s21, v53
	s_and_b64 s[4:5], vcc, s[4:5]
	s_and_saveexec_b64 s[0:1], s[4:5]
	v_lshl_add_u32 v53, v53, 2, s20
	ds_write_b32 v53, v26
	s_or_b64 exec, exec, s[0:1]
	s_bcnt1_i32_b64 s0, vcc
	v_cmp_eq_u32_e32 vcc, v253, v34
	s_add_i32 s2, s2, s0
	s_nop 0
	v_mbcnt_lo_u32_b32 v53, vcc_lo, 0
	v_mbcnt_hi_u32_b32 v53, vcc_hi, v53
	v_add_u32_e32 v53, s2, v53
	v_cmp_gt_i32_e64 s[4:5], s21, v53
	s_and_b64 s[4:5], vcc, s[4:5]
	s_and_saveexec_b64 s[0:1], s[4:5]
	v_lshl_add_u32 v53, v53, 2, s20
	ds_write_b32 v53, v28
	s_or_b64 exec, exec, s[0:1]
	s_bcnt1_i32_b64 s0, vcc
	v_cmp_eq_u32_e32 vcc, v249, v34
	s_add_i32 s2, s2, s0
	s_nop 0
	v_mbcnt_lo_u32_b32 v53, vcc_lo, 0
	v_mbcnt_hi_u32_b32 v53, vcc_hi, v53
	v_add_u32_e32 v53, s2, v53
	v_cmp_gt_i32_e64 s[4:5], s21, v53
	s_and_b64 s[4:5], vcc, s[4:5]
	s_and_saveexec_b64 s[0:1], s[4:5]
; DI unsigned mbcnt64(unsigned long long m) { return __builtin_amdgcn_mbcnt_hi((unsigned)(m >> 32), __builtin_amdgcn_mbcnt_lo((unsigned)m, 0u)); }
; template <int NV>
; DI void topk_row(const float* row, int s, LAS int* lst, int lane) {
;     ...
;     for (int j = 0; j < NV; ++j) { const bool sg = key[j] > T; const unsigned long long mg = __ballot(sg); if (sg) lst[bgt + (int)mbcnt64(mg)] = j * 64 + lane; bgt += __builtin_popcountll(mg); }
; #pragma unroll
;     for (int j = 0; j < NV; ++j) { const bool se = key[j] == T; const unsigned long long me = __ballot(se); const int pe = bgt + (int)mbcnt64(me); if (se && pe < 256) lst[pe] = j * 64 + lane; bgt += __builtin_popcountll(me); }
	v_lshl_add_u32 v53, v53, 2, s20
	ds_write_b32 v53, v30
	s_or_b64 exec, exec, s[0:1]
	s_bcnt1_i32_b64 s0, vcc
	v_cmp_eq_u32_e32 vcc, v252, v34
	s_add_i32 s2, s2, s0
	s_nop 0
	v_mbcnt_lo_u32_b32 v53, vcc_lo, 0
	v_mbcnt_hi_u32_b32 v53, vcc_hi, v53
	v_add_u32_e32 v53, s2, v53
	v_cmp_gt_i32_e64 s[4:5], s21, v53
	s_and_b64 s[4:5], vcc, s[4:5]
	s_and_saveexec_b64 s[0:1], s[4:5]
	v_lshl_add_u32 v53, v53, 2, s20
	ds_write_b32 v53, v32
	s_or_b64 exec, exec, s[0:1]
	s_bcnt1_i32_b64 s0, vcc
	v_cmp_eq_u32_e32 vcc, v128, v34
	s_add_i32 s2, s2, s0
	s_nop 0
	v_mbcnt_lo_u32_b32 v53, vcc_lo, 0
	v_mbcnt_hi_u32_b32 v53, vcc_hi, v53
	v_add_u32_e32 v53, s2, v53
	v_cmp_gt_i32_e64 s[4:5], s21, v53
	s_and_b64 s[4:5], vcc, s[4:5]
	s_and_saveexec_b64 s[0:1], s[4:5]
	v_lshl_add_u32 v53, v53, 2, s20
	ds_write_b32 v53, v3
	s_or_b64 exec, exec, s[0:1]
	s_bcnt1_i32_b64 s0, vcc
	v_cmp_eq_u32_e32 vcc, v130, v34
	s_add_i32 s2, s2, s0
	s_nop 0
	v_mbcnt_lo_u32_b32 v53, vcc_lo, 0
	v_mbcnt_hi_u32_b32 v53, vcc_hi, v53
	v_add_u32_e32 v53, s2, v53
	v_cmp_gt_i32_e64 s[4:5], s21, v53
	s_and_b64 s[4:5], vcc, s[4:5]
	s_and_saveexec_b64 s[0:1], s[4:5]
	v_lshl_add_u32 v53, v53, 2, s20
	ds_write_b32 v53, v5
	s_or_b64 exec, exec, s[0:1]
	s_bcnt1_i32_b64 s0, vcc
	v_cmp_eq_u32_e32 vcc, v131, v34
	s_add_i32 s2, s2, s0
	s_nop 0
	v_mbcnt_lo_u32_b32 v53, vcc_lo, 0
	v_mbcnt_hi_u32_b32 v53, vcc_hi, v53
	v_add_u32_e32 v53, s2, v53
	v_cmp_gt_i32_e64 s[4:5], s21, v53
	s_and_b64 s[4:5], vcc, s[4:5]
	s_and_saveexec_b64 s[0:1], s[4:5]
	v_lshl_add_u32 v53, v53, 2, s20
	ds_write_b32 v53, v7
	s_or_b64 exec, exec, s[0:1]
	s_bcnt1_i32_b64 s0, vcc
	v_cmp_eq_u32_e32 vcc, v129, v34
	s_add_i32 s2, s2, s0
	s_nop 0
	v_mbcnt_lo_u32_b32 v53, vcc_lo, 0
	v_mbcnt_hi_u32_b32 v53, vcc_hi, v53
	v_add_u32_e32 v53, s2, v53
	v_cmp_gt_i32_e64 s[4:5], s21, v53
	s_and_b64 s[4:5], vcc, s[4:5]
	s_and_saveexec_b64 s[0:1], s[4:5]
	v_lshl_add_u32 v53, v53, 2, s20
	ds_write_b32 v53, v9
	s_or_b64 exec, exec, s[0:1]
	s_bcnt1_i32_b64 s0, vcc
	v_cmp_eq_u32_e32 vcc, v250, v34
	s_add_i32 s2, s2, s0
	s_nop 0
	v_mbcnt_lo_u32_b32 v53, vcc_lo, 0
	v_mbcnt_hi_u32_b32 v53, vcc_hi, v53
	v_add_u32_e32 v53, s2, v53
	v_cmp_gt_i32_e64 s[4:5], s21, v53
	s_and_b64 s[4:5], vcc, s[4:5]
	s_and_saveexec_b64 s[0:1], s[4:5]
	v_lshl_add_u32 v53, v53, 2, s20
	ds_write_b32 v53, v11
	s_or_b64 exec, exec, s[0:1]
	s_bcnt1_i32_b64 s0, vcc
	v_cmp_eq_u32_e32 vcc, v246, v34
	s_add_i32 s2, s2, s0
	s_nop 0
	v_mbcnt_lo_u32_b32 v53, vcc_lo, 0
	v_mbcnt_hi_u32_b32 v53, vcc_hi, v53
	v_add_u32_e32 v53, s2, v53
	v_cmp_gt_i32_e64 s[4:5], s21, v53
	s_and_b64 s[4:5], vcc, s[4:5]
	s_and_saveexec_b64 s[0:1], s[4:5]
	v_lshl_add_u32 v53, v53, 2, s20
	ds_write_b32 v53, v13
	s_or_b64 exec, exec, s[0:1]
	s_bcnt1_i32_b64 s0, vcc
	v_cmp_eq_u32_e32 vcc, v245, v34
	s_add_i32 s2, s2, s0
	s_nop 0
	v_mbcnt_lo_u32_b32 v53, vcc_lo, 0
	v_mbcnt_hi_u32_b32 v53, vcc_hi, v53
	v_add_u32_e32 v53, s2, v53
	v_cmp_gt_i32_e64 s[4:5], s21, v53
	s_and_b64 s[4:5], vcc, s[4:5]
	s_and_saveexec_b64 s[0:1], s[4:5]
	v_lshl_add_u32 v53, v53, 2, s20
	ds_write_b32 v53, v15
	s_or_b64 exec, exec, s[0:1]
	s_bcnt1_i32_b64 s0, vcc
	v_cmp_eq_u32_e32 vcc, v244, v34
	s_add_i32 s2, s2, s0
	s_nop 0
	v_mbcnt_lo_u32_b32 v53, vcc_lo, 0
	v_mbcnt_hi_u32_b32 v53, vcc_hi, v53
	v_add_u32_e32 v53, s2, v53
	v_cmp_gt_i32_e64 s[4:5], s21, v53
	s_and_b64 s[4:5], vcc, s[4:5]
	s_and_saveexec_b64 s[0:1], s[4:5]
	v_lshl_add_u32 v53, v53, 2, s20
	ds_write_b32 v53, v17
	s_or_b64 exec, exec, s[0:1]
	s_bcnt1_i32_b64 s0, vcc
	v_cmp_eq_u32_e32 vcc, v243, v34
	s_add_i32 s2, s2, s0
	s_nop 0
	v_mbcnt_lo_u32_b32 v53, vcc_lo, 0
	v_mbcnt_hi_u32_b32 v53, vcc_hi, v53
	v_add_u32_e32 v53, s2, v53
	v_cmp_gt_i32_e64 s[4:5], s21, v53
	s_and_b64 s[4:5], vcc, s[4:5]
	s_and_saveexec_b64 s[0:1], s[4:5]
	v_lshl_add_u32 v53, v53, 2, s20
	ds_write_b32 v53, v19
	s_or_b64 exec, exec, s[0:1]
	s_bcnt1_i32_b64 s0, vcc
	v_cmp_eq_u32_e32 vcc, v242, v34
	s_add_i32 s2, s2, s0
	s_nop 0
	v_mbcnt_lo_u32_b32 v53, vcc_lo, 0
	v_mbcnt_hi_u32_b32 v53, vcc_hi, v53
	v_add_u32_e32 v53, s2, v53
	v_cmp_gt_i32_e64 s[4:5], s21, v53
	s_and_b64 s[4:5], vcc, s[4:5]
	s_and_saveexec_b64 s[0:1], s[4:5]
	v_lshl_add_u32 v53, v53, 2, s20
	ds_write_b32 v53, v21
	s_or_b64 exec, exec, s[0:1]
	s_bcnt1_i32_b64 s0, vcc
	v_cmp_eq_u32_e32 vcc, v241, v34
	s_add_i32 s2, s2, s0
	s_nop 0
	v_mbcnt_lo_u32_b32 v53, vcc_lo, 0
	v_mbcnt_hi_u32_b32 v53, vcc_hi, v53
	v_add_u32_e32 v53, s2, v53
	v_cmp_gt_i32_e64 s[4:5], s21, v53
	s_and_b64 s[4:5], vcc, s[4:5]
	s_and_saveexec_b64 s[0:1], s[4:5]
	v_lshl_add_u32 v53, v53, 2, s20
	ds_write_b32 v53, v23
	s_or_b64 exec, exec, s[0:1]
	s_bcnt1_i32_b64 s0, vcc
	v_cmp_eq_u32_e32 vcc, v240, v34
	s_add_i32 s2, s2, s0
	s_nop 0
	v_mbcnt_lo_u32_b32 v53, vcc_lo, 0
	v_mbcnt_hi_u32_b32 v53, vcc_hi, v53
	v_add_u32_e32 v53, s2, v53
	v_cmp_gt_i32_e64 s[4:5], s21, v53
	s_and_b64 s[4:5], vcc, s[4:5]
	s_and_saveexec_b64 s[0:1], s[4:5]
	v_lshl_add_u32 v53, v53, 2, s20
	ds_write_b32 v53, v25
	s_or_b64 exec, exec, s[0:1]
	s_bcnt1_i32_b64 s0, vcc
	v_cmp_eq_u32_e32 vcc, v239, v34
	s_add_i32 s2, s2, s0
	s_nop 0
	v_mbcnt_lo_u32_b32 v53, vcc_lo, 0
	v_mbcnt_hi_u32_b32 v53, vcc_hi, v53
	v_add_u32_e32 v53, s2, v53
	v_cmp_gt_i32_e64 s[4:5], s21, v53
	s_and_b64 s[4:5], vcc, s[4:5]
	s_and_saveexec_b64 s[0:1], s[4:5]
	v_lshl_add_u32 v53, v53, 2, s20
	ds_write_b32 v53, v27
	s_or_b64 exec, exec, s[0:1]
	s_bcnt1_i32_b64 s0, vcc
	v_cmp_eq_u32_e32 vcc, v238, v34
	s_add_i32 s2, s2, s0
	s_nop 0
	v_mbcnt_lo_u32_b32 v53, vcc_lo, 0
	v_mbcnt_hi_u32_b32 v53, vcc_hi, v53
	v_add_u32_e32 v53, s2, v53
	v_cmp_gt_i32_e64 s[4:5], s21, v53
	s_and_b64 s[4:5], vcc, s[4:5]
	s_and_saveexec_b64 s[0:1], s[4:5]
	v_lshl_add_u32 v53, v53, 2, s20
; DI unsigned mbcnt64(unsigned long long m) { return __builtin_amdgcn_mbcnt_hi((unsigned)(m >> 32), __builtin_amdgcn_mbcnt_lo((unsigned)m, 0u)); }
; template <int NV>
; DI void topk_row(const float* row, int s, LAS int* lst, int lane) {
;     ...
;     for (int j = 0; j < NV; ++j) { const bool sg = key[j] > T; const unsigned long long mg = __ballot(sg); if (sg) lst[bgt + (int)mbcnt64(mg)] = j * 64 + lane; bgt += __builtin_popcountll(mg); }
; #pragma unroll
;     for (int j = 0; j < NV; ++j) { const bool se = key[j] == T; const unsigned long long me = __ballot(se); const int pe = bgt + (int)mbcnt64(me); if (se && pe < 256) lst[pe] = j * 64 + lane; bgt += __builtin_popcountll(me); }
	ds_write_b32 v53, v29
	s_or_b64 exec, exec, s[0:1]
	s_bcnt1_i32_b64 s0, vcc
	v_cmp_eq_u32_e32 vcc, v237, v34
	s_add_i32 s2, s2, s0
	s_nop 0
	v_mbcnt_lo_u32_b32 v53, vcc_lo, 0
	v_mbcnt_hi_u32_b32 v53, vcc_hi, v53
	v_add_u32_e32 v53, s2, v53
	v_cmp_gt_i32_e64 s[4:5], s21, v53
	s_and_b64 s[4:5], vcc, s[4:5]
	s_and_saveexec_b64 s[0:1], s[4:5]
	v_lshl_add_u32 v53, v53, 2, s20
	ds_write_b32 v53, v31
	s_or_b64 exec, exec, s[0:1]
	s_bcnt1_i32_b64 s0, vcc
	v_cmp_eq_u32_e32 vcc, v236, v34
	s_add_i32 s2, s2, s0
	s_nop 0
	v_mbcnt_lo_u32_b32 v53, vcc_lo, 0
	v_mbcnt_hi_u32_b32 v53, vcc_hi, v53
	v_add_u32_e32 v53, s2, v53
	v_cmp_gt_i32_e64 s[4:5], s21, v53
	s_and_b64 s[4:5], vcc, s[4:5]
	s_and_saveexec_b64 s[0:1], s[4:5]
	v_lshl_add_u32 v53, v53, 2, s20
	ds_write_b32 v53, v33
	s_or_b64 exec, exec, s[0:1]
	s_bcnt1_i32_b64 s0, vcc
	v_cmp_eq_u32_e32 vcc, v235, v34
	s_add_i32 s2, s2, s0
	s_nop 0
	v_mbcnt_lo_u32_b32 v53, vcc_lo, 0
	v_mbcnt_hi_u32_b32 v53, vcc_hi, v53
	v_add_u32_e32 v53, s2, v53
	v_cmp_gt_i32_e64 s[4:5], s21, v53
	s_and_b64 s[4:5], vcc, s[4:5]
	s_and_saveexec_b64 s[0:1], s[4:5]
	v_lshl_add_u32 v53, v53, 2, s20
	ds_write_b32 v53, v64
	s_or_b64 exec, exec, s[0:1]
	s_bcnt1_i32_b64 s0, vcc
	v_cmp_eq_u32_e32 vcc, v234, v34
	s_add_i32 s2, s2, s0
	s_nop 0
	v_mbcnt_lo_u32_b32 v53, vcc_lo, 0
	v_mbcnt_hi_u32_b32 v53, vcc_hi, v53
	v_add_u32_e32 v53, s2, v53
	v_cmp_gt_i32_e64 s[4:5], s21, v53
	s_and_b64 s[4:5], vcc, s[4:5]
	s_and_saveexec_b64 s[0:1], s[4:5]
	v_lshl_add_u32 v53, v53, 2, s20
	ds_write_b32 v53, v65
	s_or_b64 exec, exec, s[0:1]
	s_bcnt1_i32_b64 s0, vcc
	v_cmp_eq_u32_e32 vcc, v233, v34
	s_add_i32 s2, s2, s0
	s_nop 0
	v_mbcnt_lo_u32_b32 v53, vcc_lo, 0
	v_mbcnt_hi_u32_b32 v53, vcc_hi, v53
	v_add_u32_e32 v53, s2, v53
	v_cmp_gt_i32_e64 s[4:5], s21, v53
	s_and_b64 s[4:5], vcc, s[4:5]
	s_and_saveexec_b64 s[0:1], s[4:5]
	v_lshl_add_u32 v53, v53, 2, s20
	ds_write_b32 v53, v66
	s_or_b64 exec, exec, s[0:1]
	s_bcnt1_i32_b64 s0, vcc
	v_cmp_eq_u32_e32 vcc, v232, v34
	s_add_i32 s2, s2, s0
	s_nop 0
	v_mbcnt_lo_u32_b32 v53, vcc_lo, 0
	v_mbcnt_hi_u32_b32 v53, vcc_hi, v53
	v_add_u32_e32 v53, s2, v53
	v_cmp_gt_i32_e64 s[4:5], s21, v53
	s_and_b64 s[4:5], vcc, s[4:5]
	s_and_saveexec_b64 s[0:1], s[4:5]
	v_lshl_add_u32 v53, v53, 2, s20
	ds_write_b32 v53, v67
	s_or_b64 exec, exec, s[0:1]
	s_bcnt1_i32_b64 s0, vcc
	v_cmp_eq_u32_e32 vcc, v231, v34
	s_add_i32 s2, s2, s0
	s_nop 0
	v_mbcnt_lo_u32_b32 v53, vcc_lo, 0
	v_mbcnt_hi_u32_b32 v53, vcc_hi, v53
	v_add_u32_e32 v53, s2, v53
	v_cmp_gt_i32_e64 s[4:5], s21, v53
	s_and_b64 s[4:5], vcc, s[4:5]
	s_and_saveexec_b64 s[0:1], s[4:5]
	v_lshl_add_u32 v53, v53, 2, s20
	ds_write_b32 v53, v68
	s_or_b64 exec, exec, s[0:1]
	s_bcnt1_i32_b64 s0, vcc
	v_cmp_eq_u32_e32 vcc, v230, v34
	s_add_i32 s2, s2, s0
	s_nop 0
	v_mbcnt_lo_u32_b32 v53, vcc_lo, 0
	v_mbcnt_hi_u32_b32 v53, vcc_hi, v53
	v_add_u32_e32 v53, s2, v53
	v_cmp_gt_i32_e64 s[4:5], s21, v53
	s_and_b64 s[4:5], vcc, s[4:5]
	s_and_saveexec_b64 s[0:1], s[4:5]
	v_lshl_add_u32 v53, v53, 2, s20
	ds_write_b32 v53, v69
	s_or_b64 exec, exec, s[0:1]
	s_bcnt1_i32_b64 s0, vcc
	v_cmp_eq_u32_e32 vcc, v229, v34
	s_add_i32 s2, s2, s0
	s_nop 0
	v_mbcnt_lo_u32_b32 v53, vcc_lo, 0
	v_mbcnt_hi_u32_b32 v53, vcc_hi, v53
	v_add_u32_e32 v53, s2, v53
	v_cmp_gt_i32_e64 s[4:5], s21, v53
	s_and_b64 s[4:5], vcc, s[4:5]
	s_and_saveexec_b64 s[0:1], s[4:5]
	v_lshl_add_u32 v53, v53, 2, s20
	ds_write_b32 v53, v70
	s_or_b64 exec, exec, s[0:1]
	s_bcnt1_i32_b64 s0, vcc
	v_cmp_eq_u32_e32 vcc, v228, v34
	s_add_i32 s2, s2, s0
	s_nop 0
	v_mbcnt_lo_u32_b32 v53, vcc_lo, 0
	v_mbcnt_hi_u32_b32 v53, vcc_hi, v53
	v_add_u32_e32 v53, s2, v53
	v_cmp_gt_i32_e64 s[4:5], s21, v53
	s_and_b64 s[4:5], vcc, s[4:5]
	s_and_saveexec_b64 s[0:1], s[4:5]
	v_lshl_add_u32 v53, v53, 2, s20
	ds_write_b32 v53, v71
	s_or_b64 exec, exec, s[0:1]
	s_bcnt1_i32_b64 s0, vcc
	v_cmp_eq_u32_e32 vcc, v227, v34
	s_add_i32 s2, s2, s0
	s_nop 0
	v_mbcnt_lo_u32_b32 v53, vcc_lo, 0
	v_mbcnt_hi_u32_b32 v53, vcc_hi, v53
	v_add_u32_e32 v53, s2, v53
	v_cmp_gt_i32_e64 s[4:5], s21, v53
	s_and_b64 s[4:5], vcc, s[4:5]
	s_and_saveexec_b64 s[0:1], s[4:5]
	v_lshl_add_u32 v53, v53, 2, s20
	ds_write_b32 v53, v72
	s_or_b64 exec, exec, s[0:1]
	s_bcnt1_i32_b64 s0, vcc
	v_cmp_eq_u32_e32 vcc, v226, v34
	s_add_i32 s2, s2, s0
	s_nop 0
	v_mbcnt_lo_u32_b32 v53, vcc_lo, 0
	v_mbcnt_hi_u32_b32 v53, vcc_hi, v53
	v_add_u32_e32 v53, s2, v53
	v_cmp_gt_i32_e64 s[4:5], s21, v53
	s_and_b64 s[4:5], vcc, s[4:5]
	s_and_saveexec_b64 s[0:1], s[4:5]
	v_lshl_add_u32 v53, v53, 2, s20
	ds_write_b32 v53, v73
	s_or_b64 exec, exec, s[0:1]
	s_bcnt1_i32_b64 s0, vcc
	v_cmp_eq_u32_e32 vcc, v225, v34
	s_add_i32 s2, s2, s0
	s_nop 0
	v_mbcnt_lo_u32_b32 v53, vcc_lo, 0
	v_mbcnt_hi_u32_b32 v53, vcc_hi, v53
	v_add_u32_e32 v53, s2, v53
	v_cmp_gt_i32_e64 s[4:5], s21, v53
	s_and_b64 s[4:5], vcc, s[4:5]
	s_and_saveexec_b64 s[0:1], s[4:5]
	v_lshl_add_u32 v53, v53, 2, s20
	ds_write_b32 v53, v74
	s_or_b64 exec, exec, s[0:1]
	s_bcnt1_i32_b64 s0, vcc
	v_cmp_eq_u32_e32 vcc, v224, v34
	s_add_i32 s2, s2, s0
	s_nop 0
	v_mbcnt_lo_u32_b32 v53, vcc_lo, 0
	v_mbcnt_hi_u32_b32 v53, vcc_hi, v53
	v_add_u32_e32 v53, s2, v53
	v_cmp_gt_i32_e64 s[4:5], s21, v53
	s_and_b64 s[4:5], vcc, s[4:5]
	s_and_saveexec_b64 s[0:1], s[4:5]
	v_lshl_add_u32 v53, v53, 2, s20
	ds_write_b32 v53, v75
	s_or_b64 exec, exec, s[0:1]
	s_bcnt1_i32_b64 s0, vcc
	v_cmp_eq_u32_e32 vcc, v223, v34
	s_add_i32 s2, s2, s0
	s_nop 0
	v_mbcnt_lo_u32_b32 v53, vcc_lo, 0
	v_mbcnt_hi_u32_b32 v53, vcc_hi, v53
	v_add_u32_e32 v53, s2, v53
	v_cmp_gt_i32_e64 s[4:5], s21, v53
	s_and_b64 s[4:5], vcc, s[4:5]
	s_and_saveexec_b64 s[0:1], s[4:5]
	v_lshl_add_u32 v53, v53, 2, s20
	ds_write_b32 v53, v76
; DI unsigned mbcnt64(unsigned long long m) { return __builtin_amdgcn_mbcnt_hi((unsigned)(m >> 32), __builtin_amdgcn_mbcnt_lo((unsigned)m, 0u)); }
; template <int NV>
; DI void topk_row(const float* row, int s, LAS int* lst, int lane) {
;     ...
;     for (int j = 0; j < NV; ++j) { const bool sg = key[j] > T; const unsigned long long mg = __ballot(sg); if (sg) lst[bgt + (int)mbcnt64(mg)] = j * 64 + lane; bgt += __builtin_popcountll(mg); }
; #pragma unroll
;     for (int j = 0; j < NV; ++j) { const bool se = key[j] == T; const unsigned long long me = __ballot(se); const int pe = bgt + (int)mbcnt64(me); if (se && pe < 256) lst[pe] = j * 64 + lane; bgt += __builtin_popcountll(me); }
	s_or_b64 exec, exec, s[0:1]
	s_bcnt1_i32_b64 s0, vcc
	v_cmp_eq_u32_e32 vcc, v222, v34
	s_add_i32 s2, s2, s0
	s_nop 0
	v_mbcnt_lo_u32_b32 v53, vcc_lo, 0
	v_mbcnt_hi_u32_b32 v53, vcc_hi, v53
	v_add_u32_e32 v53, s2, v53
	v_cmp_gt_i32_e64 s[4:5], s21, v53
	s_and_b64 s[4:5], vcc, s[4:5]
	s_and_saveexec_b64 s[0:1], s[4:5]
	v_lshl_add_u32 v53, v53, 2, s20
	ds_write_b32 v53, v77
	s_or_b64 exec, exec, s[0:1]
	s_bcnt1_i32_b64 s0, vcc
	v_cmp_eq_u32_e32 vcc, v221, v34
	s_add_i32 s2, s2, s0
	s_nop 0
	v_mbcnt_lo_u32_b32 v53, vcc_lo, 0
	v_mbcnt_hi_u32_b32 v53, vcc_hi, v53
	v_add_u32_e32 v53, s2, v53
	v_cmp_gt_i32_e64 s[4:5], s21, v53
	s_and_b64 s[4:5], vcc, s[4:5]
	s_and_saveexec_b64 s[0:1], s[4:5]
	v_lshl_add_u32 v53, v53, 2, s20
	ds_write_b32 v53, v78
	s_or_b64 exec, exec, s[0:1]
	s_bcnt1_i32_b64 s0, vcc
	v_cmp_eq_u32_e32 vcc, v220, v34
	s_add_i32 s2, s2, s0
	s_nop 0
	v_mbcnt_lo_u32_b32 v53, vcc_lo, 0
	v_mbcnt_hi_u32_b32 v53, vcc_hi, v53
	v_add_u32_e32 v53, s2, v53
	v_cmp_gt_i32_e64 s[4:5], s21, v53
	s_and_b64 s[4:5], vcc, s[4:5]
	s_and_saveexec_b64 s[0:1], s[4:5]
	v_lshl_add_u32 v53, v53, 2, s20
	ds_write_b32 v53, v79
	s_or_b64 exec, exec, s[0:1]
	s_bcnt1_i32_b64 s0, vcc
	v_cmp_eq_u32_e32 vcc, v219, v34
	s_add_i32 s2, s2, s0
	s_nop 0
	v_mbcnt_lo_u32_b32 v53, vcc_lo, 0
	v_mbcnt_hi_u32_b32 v53, vcc_hi, v53
	v_add_u32_e32 v53, s2, v53
	v_cmp_gt_i32_e64 s[4:5], s21, v53
	s_and_b64 s[4:5], vcc, s[4:5]
	s_and_saveexec_b64 s[0:1], s[4:5]
	v_lshl_add_u32 v53, v53, 2, s20
	ds_write_b32 v53, v80
	s_or_b64 exec, exec, s[0:1]
	s_bcnt1_i32_b64 s0, vcc
	v_cmp_eq_u32_e32 vcc, v218, v34
	s_add_i32 s2, s2, s0
	s_nop 0
	v_mbcnt_lo_u32_b32 v53, vcc_lo, 0
	v_mbcnt_hi_u32_b32 v53, vcc_hi, v53
	v_add_u32_e32 v53, s2, v53
	v_cmp_gt_i32_e64 s[4:5], s21, v53
	s_and_b64 s[4:5], vcc, s[4:5]
	s_and_saveexec_b64 s[0:1], s[4:5]
	v_lshl_add_u32 v53, v53, 2, s20
	ds_write_b32 v53, v81
	s_or_b64 exec, exec, s[0:1]
	s_bcnt1_i32_b64 s0, vcc
	v_cmp_eq_u32_e32 vcc, v217, v34
	s_add_i32 s2, s2, s0
	s_nop 0
	v_mbcnt_lo_u32_b32 v53, vcc_lo, 0
	v_mbcnt_hi_u32_b32 v53, vcc_hi, v53
	v_add_u32_e32 v53, s2, v53
	v_cmp_gt_i32_e64 s[4:5], s21, v53
	s_and_b64 s[4:5], vcc, s[4:5]
	s_and_saveexec_b64 s[0:1], s[4:5]
	v_lshl_add_u32 v53, v53, 2, s20
	ds_write_b32 v53, v82
	s_or_b64 exec, exec, s[0:1]
	s_bcnt1_i32_b64 s0, vcc
	v_cmp_eq_u32_e32 vcc, v216, v34
	s_add_i32 s2, s2, s0
	s_nop 0
	v_mbcnt_lo_u32_b32 v53, vcc_lo, 0
	v_mbcnt_hi_u32_b32 v53, vcc_hi, v53
	v_add_u32_e32 v53, s2, v53
	v_cmp_gt_i32_e64 s[4:5], s21, v53
	s_and_b64 s[4:5], vcc, s[4:5]
	s_and_saveexec_b64 s[0:1], s[4:5]
	v_lshl_add_u32 v53, v53, 2, s20
	ds_write_b32 v53, v83
	s_or_b64 exec, exec, s[0:1]
	s_bcnt1_i32_b64 s0, vcc
	v_cmp_eq_u32_e32 vcc, v215, v34
	s_add_i32 s2, s2, s0
	s_nop 0
	v_mbcnt_lo_u32_b32 v53, vcc_lo, 0
	v_mbcnt_hi_u32_b32 v53, vcc_hi, v53
	v_add_u32_e32 v53, s2, v53
	v_cmp_gt_i32_e64 s[4:5], s21, v53
	s_and_b64 s[4:5], vcc, s[4:5]
	s_and_saveexec_b64 s[0:1], s[4:5]
	v_lshl_add_u32 v53, v53, 2, s20
	ds_write_b32 v53, v84
	s_or_b64 exec, exec, s[0:1]
	s_bcnt1_i32_b64 s0, vcc
	v_cmp_eq_u32_e32 vcc, v214, v34
	s_add_i32 s2, s2, s0
	s_nop 0
	v_mbcnt_lo_u32_b32 v53, vcc_lo, 0
	v_mbcnt_hi_u32_b32 v53, vcc_hi, v53
	v_add_u32_e32 v53, s2, v53
	v_cmp_gt_i32_e64 s[4:5], s21, v53
	s_and_b64 s[4:5], vcc, s[4:5]
	s_and_saveexec_b64 s[0:1], s[4:5]
	v_lshl_add_u32 v53, v53, 2, s20
	ds_write_b32 v53, v85
	s_or_b64 exec, exec, s[0:1]
	s_bcnt1_i32_b64 s0, vcc
	v_cmp_eq_u32_e32 vcc, v213, v34
	s_add_i32 s2, s2, s0
	s_nop 0
	v_mbcnt_lo_u32_b32 v53, vcc_lo, 0
	v_mbcnt_hi_u32_b32 v53, vcc_hi, v53
	v_add_u32_e32 v53, s2, v53
	v_cmp_gt_i32_e64 s[4:5], s21, v53
	s_and_b64 s[4:5], vcc, s[4:5]
	s_and_saveexec_b64 s[0:1], s[4:5]
	v_lshl_add_u32 v53, v53, 2, s20
	ds_write_b32 v53, v86
	s_or_b64 exec, exec, s[0:1]
	s_bcnt1_i32_b64 s0, vcc
	v_cmp_eq_u32_e32 vcc, v212, v34
	s_add_i32 s2, s2, s0
	s_nop 0
	v_mbcnt_lo_u32_b32 v53, vcc_lo, 0
	v_mbcnt_hi_u32_b32 v53, vcc_hi, v53
	v_add_u32_e32 v53, s2, v53
	v_cmp_gt_i32_e64 s[4:5], s21, v53
	s_and_b64 s[4:5], vcc, s[4:5]
	s_and_saveexec_b64 s[0:1], s[4:5]
	v_lshl_add_u32 v53, v53, 2, s20
	ds_write_b32 v53, v87
	s_or_b64 exec, exec, s[0:1]
	s_bcnt1_i32_b64 s0, vcc
	v_cmp_eq_u32_e32 vcc, v211, v34
	s_add_i32 s2, s2, s0
	s_nop 0
	v_mbcnt_lo_u32_b32 v53, vcc_lo, 0
	v_mbcnt_hi_u32_b32 v53, vcc_hi, v53
	v_add_u32_e32 v53, s2, v53
	v_cmp_gt_i32_e64 s[4:5], s21, v53
	s_and_b64 s[4:5], vcc, s[4:5]
	s_and_saveexec_b64 s[0:1], s[4:5]
	v_lshl_add_u32 v53, v53, 2, s20
	ds_write_b32 v53, v88
	s_or_b64 exec, exec, s[0:1]
	s_bcnt1_i32_b64 s0, vcc
	v_cmp_eq_u32_e32 vcc, v210, v34
	s_add_i32 s2, s2, s0
	s_nop 0
	v_mbcnt_lo_u32_b32 v53, vcc_lo, 0
	v_mbcnt_hi_u32_b32 v53, vcc_hi, v53
	v_add_u32_e32 v53, s2, v53
	v_cmp_gt_i32_e64 s[4:5], s21, v53
	s_and_b64 s[4:5], vcc, s[4:5]
	s_and_saveexec_b64 s[0:1], s[4:5]
	v_lshl_add_u32 v53, v53, 2, s20
	ds_write_b32 v53, v89
	s_or_b64 exec, exec, s[0:1]
	s_bcnt1_i32_b64 s0, vcc
	v_cmp_eq_u32_e32 vcc, v209, v34
	s_add_i32 s2, s2, s0
	s_nop 0
	v_mbcnt_lo_u32_b32 v53, vcc_lo, 0
	v_mbcnt_hi_u32_b32 v53, vcc_hi, v53
	v_add_u32_e32 v53, s2, v53
	v_cmp_gt_i32_e64 s[4:5], s21, v53
	s_and_b64 s[4:5], vcc, s[4:5]
	s_and_saveexec_b64 s[0:1], s[4:5]
	v_lshl_add_u32 v53, v53, 2, s20
	ds_write_b32 v53, v90
	s_or_b64 exec, exec, s[0:1]
	s_bcnt1_i32_b64 s0, vcc
	v_cmp_eq_u32_e32 vcc, v208, v34
	s_add_i32 s2, s2, s0
	s_nop 0
	v_mbcnt_lo_u32_b32 v53, vcc_lo, 0
	v_mbcnt_hi_u32_b32 v53, vcc_hi, v53
	v_add_u32_e32 v53, s2, v53
	v_cmp_gt_i32_e64 s[4:5], s21, v53
	s_and_b64 s[4:5], vcc, s[4:5]
	s_and_saveexec_b64 s[0:1], s[4:5]
	v_lshl_add_u32 v53, v53, 2, s20
	ds_write_b32 v53, v91
	s_or_b64 exec, exec, s[0:1]
; DI unsigned mbcnt64(unsigned long long m) { return __builtin_amdgcn_mbcnt_hi((unsigned)(m >> 32), __builtin_amdgcn_mbcnt_lo((unsigned)m, 0u)); }
; template <int NV>
; DI void topk_row(const float* row, int s, LAS int* lst, int lane) {
;     ...
;     for (int j = 0; j < NV; ++j) { const bool sg = key[j] > T; const unsigned long long mg = __ballot(sg); if (sg) lst[bgt + (int)mbcnt64(mg)] = j * 64 + lane; bgt += __builtin_popcountll(mg); }
; #pragma unroll
;     for (int j = 0; j < NV; ++j) { const bool se = key[j] == T; const unsigned long long me = __ballot(se); const int pe = bgt + (int)mbcnt64(me); if (se && pe < 256) lst[pe] = j * 64 + lane; bgt += __builtin_popcountll(me); }
	s_bcnt1_i32_b64 s0, vcc
	v_cmp_eq_u32_e32 vcc, v207, v34
	s_add_i32 s2, s2, s0
	s_nop 0
	v_mbcnt_lo_u32_b32 v53, vcc_lo, 0
	v_mbcnt_hi_u32_b32 v53, vcc_hi, v53
	v_add_u32_e32 v53, s2, v53
	v_cmp_gt_i32_e64 s[4:5], s21, v53
	s_and_b64 s[4:5], vcc, s[4:5]
	s_and_saveexec_b64 s[0:1], s[4:5]
	v_lshl_add_u32 v53, v53, 2, s20
	ds_write_b32 v53, v92
	s_or_b64 exec, exec, s[0:1]
	s_bcnt1_i32_b64 s0, vcc
	v_cmp_eq_u32_e32 vcc, v206, v34
	s_add_i32 s2, s2, s0
	s_nop 0
	v_mbcnt_lo_u32_b32 v53, vcc_lo, 0
	v_mbcnt_hi_u32_b32 v53, vcc_hi, v53
	v_add_u32_e32 v53, s2, v53
	v_cmp_gt_i32_e64 s[4:5], s21, v53
	s_and_b64 s[4:5], vcc, s[4:5]
	s_and_saveexec_b64 s[0:1], s[4:5]
	v_lshl_add_u32 v53, v53, 2, s20
	ds_write_b32 v53, v93
	s_or_b64 exec, exec, s[0:1]
	s_bcnt1_i32_b64 s0, vcc
	v_cmp_eq_u32_e32 vcc, v205, v34
	s_add_i32 s2, s2, s0
	s_nop 0
	v_mbcnt_lo_u32_b32 v53, vcc_lo, 0
	v_mbcnt_hi_u32_b32 v53, vcc_hi, v53
	v_add_u32_e32 v53, s2, v53
	v_cmp_gt_i32_e64 s[4:5], s21, v53
	s_and_b64 s[4:5], vcc, s[4:5]
	s_and_saveexec_b64 s[0:1], s[4:5]
	v_lshl_add_u32 v53, v53, 2, s20
	ds_write_b32 v53, v94
	s_or_b64 exec, exec, s[0:1]
	s_bcnt1_i32_b64 s0, vcc
	v_cmp_eq_u32_e32 vcc, v204, v34
	s_add_i32 s2, s2, s0
	s_nop 0
	v_mbcnt_lo_u32_b32 v53, vcc_lo, 0
	v_mbcnt_hi_u32_b32 v53, vcc_hi, v53
	v_add_u32_e32 v53, s2, v53
	v_cmp_gt_i32_e64 s[4:5], s21, v53
	s_and_b64 s[4:5], vcc, s[4:5]
	s_and_saveexec_b64 s[0:1], s[4:5]
	v_lshl_add_u32 v53, v53, 2, s20
	ds_write_b32 v53, v95
	s_or_b64 exec, exec, s[0:1]
	s_bcnt1_i32_b64 s0, vcc
	v_cmp_eq_u32_e32 vcc, v203, v34
	s_add_i32 s2, s2, s0
	s_nop 0
	v_mbcnt_lo_u32_b32 v53, vcc_lo, 0
	v_mbcnt_hi_u32_b32 v53, vcc_hi, v53
	v_add_u32_e32 v53, s2, v53
	v_cmp_gt_i32_e64 s[4:5], s21, v53
	s_and_b64 s[4:5], vcc, s[4:5]
	s_and_saveexec_b64 s[0:1], s[4:5]
	v_lshl_add_u32 v53, v53, 2, s20
	ds_write_b32 v53, v96
	s_or_b64 exec, exec, s[0:1]
	s_bcnt1_i32_b64 s0, vcc
	v_cmp_eq_u32_e32 vcc, v202, v34
	s_add_i32 s2, s2, s0
	s_nop 0
	v_mbcnt_lo_u32_b32 v53, vcc_lo, 0
	v_mbcnt_hi_u32_b32 v53, vcc_hi, v53
	v_add_u32_e32 v53, s2, v53
	v_cmp_gt_i32_e64 s[4:5], s21, v53
	s_and_b64 s[4:5], vcc, s[4:5]
	s_and_saveexec_b64 s[0:1], s[4:5]
	v_lshl_add_u32 v53, v53, 2, s20
	ds_write_b32 v53, v97
	s_or_b64 exec, exec, s[0:1]
	s_bcnt1_i32_b64 s0, vcc
	v_cmp_eq_u32_e32 vcc, v201, v34
	s_add_i32 s2, s2, s0
	s_nop 0
	v_mbcnt_lo_u32_b32 v53, vcc_lo, 0
	v_mbcnt_hi_u32_b32 v53, vcc_hi, v53
	v_add_u32_e32 v53, s2, v53
	v_cmp_gt_i32_e64 s[4:5], s21, v53
	s_and_b64 s[4:5], vcc, s[4:5]
	s_and_saveexec_b64 s[0:1], s[4:5]
	v_lshl_add_u32 v53, v53, 2, s20
	ds_write_b32 v53, v98
	s_or_b64 exec, exec, s[0:1]
	s_bcnt1_i32_b64 s0, vcc
	v_cmp_eq_u32_e32 vcc, v200, v34
	s_add_i32 s2, s2, s0
	s_nop 0
	v_mbcnt_lo_u32_b32 v53, vcc_lo, 0
	v_mbcnt_hi_u32_b32 v53, vcc_hi, v53
	v_add_u32_e32 v53, s2, v53
	v_cmp_gt_i32_e64 s[4:5], s21, v53
	s_and_b64 s[4:5], vcc, s[4:5]
	s_and_saveexec_b64 s[0:1], s[4:5]
	v_lshl_add_u32 v53, v53, 2, s20
	ds_write_b32 v53, v99
	s_or_b64 exec, exec, s[0:1]
	s_bcnt1_i32_b64 s0, vcc
	v_cmp_eq_u32_e32 vcc, v199, v34
	s_add_i32 s2, s2, s0
	s_nop 0
	v_mbcnt_lo_u32_b32 v53, vcc_lo, 0
	v_mbcnt_hi_u32_b32 v53, vcc_hi, v53
	v_add_u32_e32 v53, s2, v53
	v_cmp_gt_i32_e64 s[4:5], s21, v53
	s_and_b64 s[4:5], vcc, s[4:5]
	s_and_saveexec_b64 s[0:1], s[4:5]
	v_lshl_add_u32 v53, v53, 2, s20
	ds_write_b32 v53, v100
	s_or_b64 exec, exec, s[0:1]
	s_bcnt1_i32_b64 s0, vcc
	v_cmp_eq_u32_e32 vcc, v198, v34
	s_add_i32 s2, s2, s0
	s_nop 0
	v_mbcnt_lo_u32_b32 v53, vcc_lo, 0
	v_mbcnt_hi_u32_b32 v53, vcc_hi, v53
	v_add_u32_e32 v53, s2, v53
	v_cmp_gt_i32_e64 s[4:5], s21, v53
	s_and_b64 s[4:5], vcc, s[4:5]
	s_and_saveexec_b64 s[0:1], s[4:5]
	v_lshl_add_u32 v53, v53, 2, s20
	ds_write_b32 v53, v101
	s_or_b64 exec, exec, s[0:1]
	s_bcnt1_i32_b64 s0, vcc
	v_cmp_eq_u32_e32 vcc, v197, v34
	s_add_i32 s2, s2, s0
	s_nop 0
	v_mbcnt_lo_u32_b32 v53, vcc_lo, 0
	v_mbcnt_hi_u32_b32 v53, vcc_hi, v53
	v_add_u32_e32 v53, s2, v53
	v_cmp_gt_i32_e64 s[4:5], s21, v53
	s_and_b64 s[4:5], vcc, s[4:5]
	s_and_saveexec_b64 s[0:1], s[4:5]
	v_lshl_add_u32 v53, v53, 2, s20
	ds_write_b32 v53, v102
	s_or_b64 exec, exec, s[0:1]
	s_bcnt1_i32_b64 s0, vcc
	v_cmp_eq_u32_e32 vcc, v196, v34
	s_add_i32 s2, s2, s0
	s_nop 0
	v_mbcnt_lo_u32_b32 v53, vcc_lo, 0
	v_mbcnt_hi_u32_b32 v53, vcc_hi, v53
	v_add_u32_e32 v53, s2, v53
	v_cmp_gt_i32_e64 s[4:5], s21, v53
	s_and_b64 s[4:5], vcc, s[4:5]
	s_and_saveexec_b64 s[0:1], s[4:5]
	v_lshl_add_u32 v53, v53, 2, s20
	ds_write_b32 v53, v103
	s_or_b64 exec, exec, s[0:1]
	s_bcnt1_i32_b64 s0, vcc
	v_cmp_eq_u32_e32 vcc, v195, v34
	s_add_i32 s2, s2, s0
	s_nop 0
	v_mbcnt_lo_u32_b32 v53, vcc_lo, 0
	v_mbcnt_hi_u32_b32 v53, vcc_hi, v53
	v_add_u32_e32 v53, s2, v53
	v_cmp_gt_i32_e64 s[4:5], s21, v53
	s_and_b64 s[4:5], vcc, s[4:5]
	s_and_saveexec_b64 s[0:1], s[4:5]
	v_lshl_add_u32 v53, v53, 2, s20
	ds_write_b32 v53, v104
	s_or_b64 exec, exec, s[0:1]
	s_bcnt1_i32_b64 s0, vcc
	v_cmp_eq_u32_e32 vcc, v194, v34
	s_add_i32 s2, s2, s0
	s_nop 0
	v_mbcnt_lo_u32_b32 v53, vcc_lo, 0
	v_mbcnt_hi_u32_b32 v53, vcc_hi, v53
	v_add_u32_e32 v53, s2, v53
	v_cmp_gt_i32_e64 s[4:5], s21, v53
	s_and_b64 s[4:5], vcc, s[4:5]
	s_and_saveexec_b64 s[0:1], s[4:5]
	v_lshl_add_u32 v53, v53, 2, s20
	ds_write_b32 v53, v105
	s_or_b64 exec, exec, s[0:1]
	s_bcnt1_i32_b64 s0, vcc
	v_cmp_eq_u32_e32 vcc, v193, v34
	s_add_i32 s2, s2, s0
	s_nop 0
	v_mbcnt_lo_u32_b32 v53, vcc_lo, 0
	v_mbcnt_hi_u32_b32 v53, vcc_hi, v53
	v_add_u32_e32 v53, s2, v53
	v_cmp_gt_i32_e64 s[4:5], s21, v53
	s_and_b64 s[4:5], vcc, s[4:5]
	s_and_saveexec_b64 s[0:1], s[4:5]
	v_lshl_add_u32 v53, v53, 2, s20
	ds_write_b32 v53, v106
	s_or_b64 exec, exec, s[0:1]
; DI unsigned mbcnt64(unsigned long long m) { return __builtin_amdgcn_mbcnt_hi((unsigned)(m >> 32), __builtin_amdgcn_mbcnt_lo((unsigned)m, 0u)); }
; template <int NV>
; DI void topk_row(const float* row, int s, LAS int* lst, int lane) {
;     ...
;     for (int j = 0; j < NV; ++j) { const bool sg = key[j] > T; const unsigned long long mg = __ballot(sg); if (sg) lst[bgt + (int)mbcnt64(mg)] = j * 64 + lane; bgt += __builtin_popcountll(mg); }
; #pragma unroll
;     for (int j = 0; j < NV; ++j) { const bool se = key[j] == T; const unsigned long long me = __ballot(se); const int pe = bgt + (int)mbcnt64(me); if (se && pe < 256) lst[pe] = j * 64 + lane; bgt += __builtin_popcountll(me); }
	s_bcnt1_i32_b64 s0, vcc
	v_cmp_eq_u32_e32 vcc, v192, v34
	s_add_i32 s2, s2, s0
	s_nop 0
	v_mbcnt_lo_u32_b32 v53, vcc_lo, 0
	v_mbcnt_hi_u32_b32 v53, vcc_hi, v53
	v_add_u32_e32 v53, s2, v53
	v_cmp_gt_i32_e64 s[4:5], s21, v53
	s_and_b64 s[4:5], vcc, s[4:5]
	s_and_saveexec_b64 s[0:1], s[4:5]
	v_lshl_add_u32 v53, v53, 2, s20
	ds_write_b32 v53, v107
	s_or_b64 exec, exec, s[0:1]
	s_bcnt1_i32_b64 s0, vcc
	v_cmp_eq_u32_e32 vcc, v191, v34
	s_add_i32 s2, s2, s0
	s_nop 0
	v_mbcnt_lo_u32_b32 v53, vcc_lo, 0
	v_mbcnt_hi_u32_b32 v53, vcc_hi, v53
	v_add_u32_e32 v53, s2, v53
	v_cmp_gt_i32_e64 s[4:5], s21, v53
	s_and_b64 s[4:5], vcc, s[4:5]
	s_and_saveexec_b64 s[0:1], s[4:5]
	v_lshl_add_u32 v53, v53, 2, s20
	ds_write_b32 v53, v108
	s_or_b64 exec, exec, s[0:1]
	s_bcnt1_i32_b64 s0, vcc
	v_cmp_eq_u32_e32 vcc, v190, v34
	s_add_i32 s2, s2, s0
	s_nop 0
	v_mbcnt_lo_u32_b32 v53, vcc_lo, 0
	v_mbcnt_hi_u32_b32 v53, vcc_hi, v53
	v_add_u32_e32 v53, s2, v53
	v_cmp_gt_i32_e64 s[4:5], s21, v53
	s_and_b64 s[4:5], vcc, s[4:5]
	s_and_saveexec_b64 s[0:1], s[4:5]
	v_lshl_add_u32 v53, v53, 2, s20
	ds_write_b32 v53, v109
	s_or_b64 exec, exec, s[0:1]
	s_bcnt1_i32_b64 s0, vcc
	v_cmp_eq_u32_e32 vcc, v189, v34
	s_add_i32 s2, s2, s0
	s_nop 0
	v_mbcnt_lo_u32_b32 v53, vcc_lo, 0
	v_mbcnt_hi_u32_b32 v53, vcc_hi, v53
	v_add_u32_e32 v53, s2, v53
	v_cmp_gt_i32_e64 s[4:5], s21, v53
	s_and_b64 s[4:5], vcc, s[4:5]
	s_and_saveexec_b64 s[0:1], s[4:5]
	v_lshl_add_u32 v53, v53, 2, s20
	ds_write_b32 v53, v110
	s_or_b64 exec, exec, s[0:1]
	s_bcnt1_i32_b64 s0, vcc
	v_cmp_eq_u32_e32 vcc, v187, v34
	s_add_i32 s2, s2, s0
	s_nop 0
	v_mbcnt_lo_u32_b32 v53, vcc_lo, 0
	v_mbcnt_hi_u32_b32 v53, vcc_hi, v53
	v_add_u32_e32 v53, s2, v53
	v_cmp_gt_i32_e64 s[4:5], s21, v53
	s_and_b64 s[4:5], vcc, s[4:5]
	s_and_saveexec_b64 s[0:1], s[4:5]
	v_lshl_add_u32 v53, v53, 2, s20
	ds_write_b32 v53, v111
	s_or_b64 exec, exec, s[0:1]
	s_bcnt1_i32_b64 s0, vcc
	v_cmp_eq_u32_e32 vcc, v188, v34
	s_add_i32 s2, s2, s0
	s_nop 0
	v_mbcnt_lo_u32_b32 v53, vcc_lo, 0
	v_mbcnt_hi_u32_b32 v53, vcc_hi, v53
	v_add_u32_e32 v53, s2, v53
	v_cmp_gt_i32_e64 s[4:5], s21, v53
	s_and_b64 s[4:5], vcc, s[4:5]
	s_and_saveexec_b64 s[0:1], s[4:5]
	v_lshl_add_u32 v53, v53, 2, s20
	ds_write_b32 v53, v112
	s_or_b64 exec, exec, s[0:1]
	s_bcnt1_i32_b64 s0, vcc
	v_cmp_eq_u32_e32 vcc, v186, v34
	s_add_i32 s2, s2, s0
	s_nop 0
	v_mbcnt_lo_u32_b32 v53, vcc_lo, 0
	v_mbcnt_hi_u32_b32 v53, vcc_hi, v53
	v_add_u32_e32 v53, s2, v53
	v_cmp_gt_i32_e64 s[4:5], s21, v53
	s_and_b64 s[4:5], vcc, s[4:5]
	s_and_saveexec_b64 s[0:1], s[4:5]
	v_lshl_add_u32 v53, v53, 2, s20
	ds_write_b32 v53, v113
	s_or_b64 exec, exec, s[0:1]
	s_bcnt1_i32_b64 s0, vcc
	v_cmp_eq_u32_e32 vcc, v185, v34
	s_add_i32 s2, s2, s0
	s_nop 0
	v_mbcnt_lo_u32_b32 v53, vcc_lo, 0
	v_mbcnt_hi_u32_b32 v53, vcc_hi, v53
	v_add_u32_e32 v53, s2, v53
	v_cmp_gt_i32_e64 s[4:5], s21, v53
	s_and_b64 s[4:5], vcc, s[4:5]
	s_and_saveexec_b64 s[0:1], s[4:5]
	v_lshl_add_u32 v53, v53, 2, s20
	ds_write_b32 v53, v114
	s_or_b64 exec, exec, s[0:1]
	s_bcnt1_i32_b64 s0, vcc
	v_cmp_eq_u32_e32 vcc, v184, v34
	s_add_i32 s2, s2, s0
	s_nop 0
	v_mbcnt_lo_u32_b32 v53, vcc_lo, 0
	v_mbcnt_hi_u32_b32 v53, vcc_hi, v53
	v_add_u32_e32 v53, s2, v53
	v_cmp_gt_i32_e64 s[4:5], s21, v53
	s_and_b64 s[4:5], vcc, s[4:5]
	s_and_saveexec_b64 s[0:1], s[4:5]
	v_lshl_add_u32 v53, v53, 2, s20
	ds_write_b32 v53, v115
	s_or_b64 exec, exec, s[0:1]
	s_bcnt1_i32_b64 s0, vcc
	v_cmp_eq_u32_e32 vcc, v183, v34
	s_add_i32 s2, s2, s0
	s_nop 0
	v_mbcnt_lo_u32_b32 v53, vcc_lo, 0
	v_mbcnt_hi_u32_b32 v53, vcc_hi, v53
	v_add_u32_e32 v53, s2, v53
	v_cmp_gt_i32_e64 s[4:5], s21, v53
	s_and_b64 s[4:5], vcc, s[4:5]
	s_and_saveexec_b64 s[0:1], s[4:5]
	v_lshl_add_u32 v53, v53, 2, s20
	ds_write_b32 v53, v116
	s_or_b64 exec, exec, s[0:1]
	s_bcnt1_i32_b64 s0, vcc
	v_cmp_eq_u32_e32 vcc, v182, v34
	s_add_i32 s2, s2, s0
	s_nop 0
	v_mbcnt_lo_u32_b32 v53, vcc_lo, 0
	v_mbcnt_hi_u32_b32 v53, vcc_hi, v53
	v_add_u32_e32 v53, s2, v53
	v_cmp_gt_i32_e64 s[4:5], s21, v53
	s_and_b64 s[4:5], vcc, s[4:5]
	s_and_saveexec_b64 s[0:1], s[4:5]
	v_lshl_add_u32 v53, v53, 2, s20
	ds_write_b32 v53, v117
	s_or_b64 exec, exec, s[0:1]
	s_bcnt1_i32_b64 s0, vcc
	v_cmp_eq_u32_e32 vcc, v181, v34
	s_add_i32 s2, s2, s0
	s_nop 0
	v_mbcnt_lo_u32_b32 v53, vcc_lo, 0
	v_mbcnt_hi_u32_b32 v53, vcc_hi, v53
	v_add_u32_e32 v53, s2, v53
	v_cmp_gt_i32_e64 s[4:5], s21, v53
	s_and_b64 s[4:5], vcc, s[4:5]
	s_and_saveexec_b64 s[0:1], s[4:5]
	v_lshl_add_u32 v53, v53, 2, s20
	ds_write_b32 v53, v118
	s_or_b64 exec, exec, s[0:1]
	s_bcnt1_i32_b64 s0, vcc
	v_cmp_eq_u32_e32 vcc, v180, v34
	s_add_i32 s2, s2, s0
	s_nop 0
	v_mbcnt_lo_u32_b32 v53, vcc_lo, 0
	v_mbcnt_hi_u32_b32 v53, vcc_hi, v53
	v_add_u32_e32 v53, s2, v53
	v_cmp_gt_i32_e64 s[4:5], s21, v53
	s_and_b64 s[4:5], vcc, s[4:5]
	s_and_saveexec_b64 s[0:1], s[4:5]
	v_lshl_add_u32 v53, v53, 2, s20
	ds_write_b32 v53, v119
	s_or_b64 exec, exec, s[0:1]
	s_bcnt1_i32_b64 s0, vcc
	v_cmp_eq_u32_e32 vcc, v179, v34
	s_add_i32 s2, s2, s0
	s_nop 0
	v_mbcnt_lo_u32_b32 v53, vcc_lo, 0
	v_mbcnt_hi_u32_b32 v53, vcc_hi, v53
	v_add_u32_e32 v53, s2, v53
	v_cmp_gt_i32_e64 s[4:5], s21, v53
	s_and_b64 s[4:5], vcc, s[4:5]
	s_and_saveexec_b64 s[0:1], s[4:5]
	v_lshl_add_u32 v53, v53, 2, s20
	ds_write_b32 v53, v120
	s_or_b64 exec, exec, s[0:1]
	s_bcnt1_i32_b64 s0, vcc
	v_cmp_eq_u32_e32 vcc, v178, v34
	s_add_i32 s2, s2, s0
	s_nop 0
	v_mbcnt_lo_u32_b32 v53, vcc_lo, 0
	v_mbcnt_hi_u32_b32 v53, vcc_hi, v53
	v_add_u32_e32 v53, s2, v53
	v_cmp_gt_i32_e64 s[4:5], s21, v53
	s_and_b64 s[4:5], vcc, s[4:5]
	s_and_saveexec_b64 s[0:1], s[4:5]
	v_lshl_add_u32 v53, v53, 2, s20
	ds_write_b32 v53, v121
	s_or_b64 exec, exec, s[0:1]
; DI unsigned mbcnt64(unsigned long long m) { return __builtin_amdgcn_mbcnt_hi((unsigned)(m >> 32), __builtin_amdgcn_mbcnt_lo((unsigned)m, 0u)); }
; template <int NV>
; DI void topk_row(const float* row, int s, LAS int* lst, int lane) {
;     ...
;     for (int j = 0; j < NV; ++j) { const bool sg = key[j] > T; const unsigned long long mg = __ballot(sg); if (sg) lst[bgt + (int)mbcnt64(mg)] = j * 64 + lane; bgt += __builtin_popcountll(mg); }
; #pragma unroll
;     for (int j = 0; j < NV; ++j) { const bool se = key[j] == T; const unsigned long long me = __ballot(se); const int pe = bgt + (int)mbcnt64(me); if (se && pe < 256) lst[pe] = j * 64 + lane; bgt += __builtin_popcountll(me); }
	s_bcnt1_i32_b64 s0, vcc
	v_cmp_eq_u32_e32 vcc, v177, v34
	s_add_i32 s2, s2, s0
	s_nop 0
	v_mbcnt_lo_u32_b32 v53, vcc_lo, 0
	v_mbcnt_hi_u32_b32 v53, vcc_hi, v53
	v_add_u32_e32 v53, s2, v53
	v_cmp_gt_i32_e64 s[4:5], s21, v53
	s_and_b64 s[4:5], vcc, s[4:5]
	s_and_saveexec_b64 s[0:1], s[4:5]
	v_lshl_add_u32 v53, v53, 2, s20
	ds_write_b32 v53, v122
	s_or_b64 exec, exec, s[0:1]
	s_bcnt1_i32_b64 s0, vcc
	v_cmp_eq_u32_e32 vcc, v176, v34
	s_add_i32 s2, s2, s0
	s_nop 0
	v_mbcnt_lo_u32_b32 v53, vcc_lo, 0
	v_mbcnt_hi_u32_b32 v53, vcc_hi, v53
	v_add_u32_e32 v53, s2, v53
	v_cmp_gt_i32_e64 s[4:5], s21, v53
	s_and_b64 s[4:5], vcc, s[4:5]
	s_and_saveexec_b64 s[0:1], s[4:5]
	v_lshl_add_u32 v53, v53, 2, s20
	ds_write_b32 v53, v123
	s_or_b64 exec, exec, s[0:1]
	s_bcnt1_i32_b64 s0, vcc
	v_cmp_eq_u32_e32 vcc, v175, v34
	s_add_i32 s2, s2, s0
	s_nop 0
	v_mbcnt_lo_u32_b32 v53, vcc_lo, 0
	v_mbcnt_hi_u32_b32 v53, vcc_hi, v53
	v_add_u32_e32 v53, s2, v53
	v_cmp_gt_i32_e64 s[4:5], s21, v53
	s_and_b64 s[4:5], vcc, s[4:5]
	s_and_saveexec_b64 s[0:1], s[4:5]
	v_lshl_add_u32 v53, v53, 2, s20
	ds_write_b32 v53, v124
	s_or_b64 exec, exec, s[0:1]
	s_bcnt1_i32_b64 s0, vcc
	v_cmp_eq_u32_e32 vcc, v174, v34
	s_add_i32 s2, s2, s0
	s_nop 0
	v_mbcnt_lo_u32_b32 v53, vcc_lo, 0
	v_mbcnt_hi_u32_b32 v53, vcc_hi, v53
	v_add_u32_e32 v53, s2, v53
	v_cmp_gt_i32_e64 s[4:5], s21, v53
	s_and_b64 s[4:5], vcc, s[4:5]
	s_and_saveexec_b64 s[0:1], s[4:5]
	v_lshl_add_u32 v53, v53, 2, s20
	ds_write_b32 v53, v125
	s_or_b64 exec, exec, s[0:1]
	s_bcnt1_i32_b64 s0, vcc
	v_cmp_eq_u32_e32 vcc, v173, v34
	s_add_i32 s2, s2, s0
	s_nop 0
	v_mbcnt_lo_u32_b32 v53, vcc_lo, 0
	v_mbcnt_hi_u32_b32 v53, vcc_hi, v53
	v_add_u32_e32 v53, s2, v53
	v_cmp_gt_i32_e64 s[4:5], s21, v53
	s_and_b64 s[4:5], vcc, s[4:5]
	s_and_saveexec_b64 s[0:1], s[4:5]
	v_lshl_add_u32 v53, v53, 2, s20
	ds_write_b32 v53, v126
	s_or_b64 exec, exec, s[0:1]
	s_bcnt1_i32_b64 s0, vcc
	v_cmp_eq_u32_e32 vcc, v172, v34
	s_add_i32 s2, s2, s0
	s_nop 0
	v_mbcnt_lo_u32_b32 v53, vcc_lo, 0
	v_mbcnt_hi_u32_b32 v53, vcc_hi, v53
	v_add_u32_e32 v53, s2, v53
	v_cmp_gt_i32_e64 s[4:5], s21, v53
	s_and_b64 s[4:5], vcc, s[4:5]
	s_and_saveexec_b64 s[0:1], s[4:5]
	v_lshl_add_u32 v53, v53, 2, s20
	ds_write_b32 v53, v127
	s_or_b64 exec, exec, s[0:1]
	s_bcnt1_i32_b64 s0, vcc
	v_cmp_eq_u32_e32 vcc, v171, v34
	s_add_i32 s2, s2, s0
	s_nop 0
	v_mbcnt_lo_u32_b32 v53, vcc_lo, 0
	v_mbcnt_hi_u32_b32 v53, vcc_hi, v53
	v_add_u32_e32 v53, s2, v53
	v_cmp_gt_i32_e64 s[4:5], s21, v53
	s_and_b64 s[4:5], vcc, s[4:5]
	s_and_saveexec_b64 s[0:1], s[4:5]
	v_lshl_add_u32 v53, v53, 2, s20
	v_or_b32_e32 v54, 0x1800, v2
	ds_write_b32 v53, v54
	s_or_b64 exec, exec, s[0:1]
	s_bcnt1_i32_b64 s0, vcc
	v_cmp_eq_u32_e32 vcc, v170, v34
	s_add_i32 s2, s2, s0
	s_nop 0
	v_mbcnt_lo_u32_b32 v53, vcc_lo, 0
	v_mbcnt_hi_u32_b32 v53, vcc_hi, v53
	v_add_u32_e32 v53, s2, v53
	v_cmp_gt_i32_e64 s[4:5], s21, v53
	s_and_b64 s[4:5], vcc, s[4:5]
	s_and_saveexec_b64 s[0:1], s[4:5]
	v_lshl_add_u32 v53, v53, 2, s20
	v_or_b32_e32 v54, 0x1840, v2
	ds_write_b32 v53, v54
	s_or_b64 exec, exec, s[0:1]
	s_bcnt1_i32_b64 s0, vcc
	v_cmp_eq_u32_e32 vcc, v169, v34
	s_add_i32 s2, s2, s0
	s_nop 0
	v_mbcnt_lo_u32_b32 v53, vcc_lo, 0
	v_mbcnt_hi_u32_b32 v53, vcc_hi, v53
	v_add_u32_e32 v53, s2, v53
	v_cmp_gt_i32_e64 s[4:5], s21, v53
	s_and_b64 s[4:5], vcc, s[4:5]
	s_and_saveexec_b64 s[0:1], s[4:5]
	v_lshl_add_u32 v53, v53, 2, s20
	v_or_b32_e32 v54, 0x1880, v2
	ds_write_b32 v53, v54
	s_or_b64 exec, exec, s[0:1]
	s_bcnt1_i32_b64 s0, vcc
	v_cmp_eq_u32_e32 vcc, v168, v34
	s_add_i32 s2, s2, s0
	s_nop 0
	v_mbcnt_lo_u32_b32 v53, vcc_lo, 0
	v_mbcnt_hi_u32_b32 v53, vcc_hi, v53
	v_add_u32_e32 v53, s2, v53
	v_cmp_gt_i32_e64 s[4:5], s21, v53
	s_and_b64 s[4:5], vcc, s[4:5]
	s_and_saveexec_b64 s[0:1], s[4:5]
	v_lshl_add_u32 v53, v53, 2, s20
	v_or_b32_e32 v54, 0x18c0, v2
	ds_write_b32 v53, v54
	s_or_b64 exec, exec, s[0:1]
	s_bcnt1_i32_b64 s0, vcc
	v_cmp_eq_u32_e32 vcc, v166, v34
	s_add_i32 s2, s2, s0
	s_nop 0
	v_mbcnt_lo_u32_b32 v53, vcc_lo, 0
	v_mbcnt_hi_u32_b32 v53, vcc_hi, v53
	v_add_u32_e32 v53, s2, v53
	v_cmp_gt_i32_e64 s[4:5], s21, v53
	s_and_b64 s[4:5], vcc, s[4:5]
	s_and_saveexec_b64 s[0:1], s[4:5]
	v_lshl_add_u32 v53, v53, 2, s20
	v_or_b32_e32 v54, 0x1900, v2
	ds_write_b32 v53, v54
	s_or_b64 exec, exec, s[0:1]
	s_bcnt1_i32_b64 s0, vcc
	v_cmp_eq_u32_e32 vcc, v164, v34
	s_add_i32 s2, s2, s0
	s_nop 0
	v_mbcnt_lo_u32_b32 v53, vcc_lo, 0
	v_mbcnt_hi_u32_b32 v53, vcc_hi, v53
	v_add_u32_e32 v53, s2, v53
	v_cmp_gt_i32_e64 s[4:5], s21, v53
	s_and_b64 s[4:5], vcc, s[4:5]
	s_and_saveexec_b64 s[0:1], s[4:5]
	v_lshl_add_u32 v53, v53, 2, s20
	v_or_b32_e32 v54, 0x1940, v2
	ds_write_b32 v53, v54
	s_or_b64 exec, exec, s[0:1]
	s_bcnt1_i32_b64 s0, vcc
	v_cmp_eq_u32_e32 vcc, v167, v34
	s_add_i32 s2, s2, s0
	s_nop 0
	v_mbcnt_lo_u32_b32 v53, vcc_lo, 0
	v_mbcnt_hi_u32_b32 v53, vcc_hi, v53
	v_add_u32_e32 v53, s2, v53
	v_cmp_gt_i32_e64 s[4:5], s21, v53
	s_and_b64 s[4:5], vcc, s[4:5]
	s_and_saveexec_b64 s[0:1], s[4:5]
	v_lshl_add_u32 v53, v53, 2, s20
	v_or_b32_e32 v54, 0x1980, v2
	ds_write_b32 v53, v54
	s_or_b64 exec, exec, s[0:1]
	s_bcnt1_i32_b64 s0, vcc
	v_cmp_eq_u32_e32 vcc, v165, v34
	s_add_i32 s2, s2, s0
	s_nop 0
	v_mbcnt_lo_u32_b32 v53, vcc_lo, 0
	v_mbcnt_hi_u32_b32 v53, vcc_hi, v53
	v_add_u32_e32 v53, s2, v53
	v_cmp_gt_i32_e64 s[4:5], s21, v53
	s_and_b64 s[4:5], vcc, s[4:5]
	s_and_saveexec_b64 s[0:1], s[4:5]
	v_lshl_add_u32 v53, v53, 2, s20
	v_or_b32_e32 v54, 0x19c0, v2
	ds_write_b32 v53, v54
	s_or_b64 exec, exec, s[0:1]
	s_bcnt1_i32_b64 s0, vcc
	v_cmp_eq_u32_e32 vcc, v162, v34
	s_add_i32 s2, s2, s0
	s_nop 0
	v_mbcnt_lo_u32_b32 v53, vcc_lo, 0
	v_mbcnt_hi_u32_b32 v53, vcc_hi, v53
; DI unsigned mbcnt64(unsigned long long m) { return __builtin_amdgcn_mbcnt_hi((unsigned)(m >> 32), __builtin_amdgcn_mbcnt_lo((unsigned)m, 0u)); }
; template <int NV>
; DI void topk_row(const float* row, int s, LAS int* lst, int lane) {
;     ...
;     for (int j = 0; j < NV; ++j) { const bool sg = key[j] > T; const unsigned long long mg = __ballot(sg); if (sg) lst[bgt + (int)mbcnt64(mg)] = j * 64 + lane; bgt += __builtin_popcountll(mg); }
; #pragma unroll
;     for (int j = 0; j < NV; ++j) { const bool se = key[j] == T; const unsigned long long me = __ballot(se); const int pe = bgt + (int)mbcnt64(me); if (se && pe < 256) lst[pe] = j * 64 + lane; bgt += __builtin_popcountll(me); }
	v_add_u32_e32 v53, s2, v53
	v_cmp_gt_i32_e64 s[4:5], s21, v53
	s_and_b64 s[4:5], vcc, s[4:5]
	s_and_saveexec_b64 s[0:1], s[4:5]
	v_lshl_add_u32 v53, v53, 2, s20
	v_or_b32_e32 v54, 0x1a00, v2
	ds_write_b32 v53, v54
	s_or_b64 exec, exec, s[0:1]
	s_bcnt1_i32_b64 s0, vcc
	v_cmp_eq_u32_e32 vcc, v163, v34
	s_add_i32 s2, s2, s0
	s_nop 0
	v_mbcnt_lo_u32_b32 v53, vcc_lo, 0
	v_mbcnt_hi_u32_b32 v53, vcc_hi, v53
	v_add_u32_e32 v53, s2, v53
	v_cmp_gt_i32_e64 s[4:5], s21, v53
	s_and_b64 s[4:5], vcc, s[4:5]
	s_and_saveexec_b64 s[0:1], s[4:5]
	v_lshl_add_u32 v53, v53, 2, s20
	v_or_b32_e32 v54, 0x1a40, v2
	ds_write_b32 v53, v54
	s_or_b64 exec, exec, s[0:1]
	s_bcnt1_i32_b64 s0, vcc
	v_cmp_eq_u32_e32 vcc, v62, v34
	s_add_i32 s2, s2, s0
	s_nop 0
	v_mbcnt_lo_u32_b32 v53, vcc_lo, 0
	v_mbcnt_hi_u32_b32 v53, vcc_hi, v53
	v_add_u32_e32 v53, s2, v53
	v_cmp_gt_i32_e64 s[4:5], s21, v53
	s_and_b64 s[4:5], vcc, s[4:5]
	s_and_saveexec_b64 s[0:1], s[4:5]
	v_lshl_add_u32 v53, v53, 2, s20
	v_or_b32_e32 v54, 0x1a80, v2
	ds_write_b32 v53, v54
	s_or_b64 exec, exec, s[0:1]
	s_bcnt1_i32_b64 s0, vcc
	v_cmp_eq_u32_e32 vcc, v58, v34
	s_add_i32 s2, s2, s0
	s_nop 0
	v_mbcnt_lo_u32_b32 v53, vcc_lo, 0
	v_mbcnt_hi_u32_b32 v53, vcc_hi, v53
	v_add_u32_e32 v53, s2, v53
	v_cmp_gt_i32_e64 s[4:5], s21, v53
	s_and_b64 s[4:5], vcc, s[4:5]
	s_and_saveexec_b64 s[0:1], s[4:5]
	v_lshl_add_u32 v53, v53, 2, s20
	v_or_b32_e32 v54, 0x1ac0, v2
	ds_write_b32 v53, v54
	s_or_b64 exec, exec, s[0:1]
	s_bcnt1_i32_b64 s0, vcc
	v_cmp_eq_u32_e32 vcc, v56, v34
	s_add_i32 s2, s2, s0
	s_nop 0
	v_mbcnt_lo_u32_b32 v53, vcc_lo, 0
	v_mbcnt_hi_u32_b32 v53, vcc_hi, v53
	v_add_u32_e32 v53, s2, v53
	v_cmp_gt_i32_e64 s[4:5], s21, v53
	s_and_b64 s[4:5], vcc, s[4:5]
	s_and_saveexec_b64 s[0:1], s[4:5]
	v_lshl_add_u32 v53, v53, 2, s20
	v_or_b32_e32 v54, 0x1b00, v2
	ds_write_b32 v53, v54
	s_or_b64 exec, exec, s[0:1]
	s_bcnt1_i32_b64 s0, vcc
	v_cmp_eq_u32_e32 vcc, v52, v34
	s_add_i32 s2, s2, s0
	s_nop 0
	v_mbcnt_lo_u32_b32 v52, vcc_lo, 0
	v_mbcnt_hi_u32_b32 v52, vcc_hi, v52
	v_add_u32_e32 v52, s2, v52
	v_cmp_gt_i32_e64 s[4:5], s21, v52
	s_and_b64 s[4:5], vcc, s[4:5]
	s_and_saveexec_b64 s[0:1], s[4:5]
	v_lshl_add_u32 v52, v52, 2, s20
	v_or_b32_e32 v53, 0x1b40, v2
	ds_write_b32 v52, v53
	s_or_b64 exec, exec, s[0:1]
	s_bcnt1_i32_b64 s0, vcc
	v_cmp_eq_u32_e32 vcc, v50, v34
	s_add_i32 s2, s2, s0
	s_nop 0
	v_mbcnt_lo_u32_b32 v50, vcc_lo, 0
	v_mbcnt_hi_u32_b32 v50, vcc_hi, v50
	v_add_u32_e32 v50, s2, v50
	v_cmp_gt_i32_e64 s[4:5], s21, v50
	s_and_b64 s[4:5], vcc, s[4:5]
	s_and_saveexec_b64 s[0:1], s[4:5]
	v_lshl_add_u32 v50, v50, 2, s20
	v_or_b32_e32 v52, 0x1b80, v2
	ds_write_b32 v50, v52
	s_or_b64 exec, exec, s[0:1]
	s_bcnt1_i32_b64 s0, vcc
	v_cmp_eq_u32_e32 vcc, v49, v34
	s_add_i32 s2, s2, s0
	s_nop 0
	v_mbcnt_lo_u32_b32 v49, vcc_lo, 0
	v_mbcnt_hi_u32_b32 v49, vcc_hi, v49
	v_add_u32_e32 v49, s2, v49
	v_cmp_gt_i32_e64 s[4:5], s21, v49
	s_and_b64 s[4:5], vcc, s[4:5]
	s_and_saveexec_b64 s[0:1], s[4:5]
	v_lshl_add_u32 v49, v49, 2, s20
	v_or_b32_e32 v50, 0x1bc0, v2
	ds_write_b32 v49, v50
	s_or_b64 exec, exec, s[0:1]
	s_bcnt1_i32_b64 s0, vcc
	v_cmp_eq_u32_e32 vcc, v48, v34
	s_add_i32 s2, s2, s0
	s_nop 0
	v_mbcnt_lo_u32_b32 v48, vcc_lo, 0
	v_mbcnt_hi_u32_b32 v48, vcc_hi, v48
	v_add_u32_e32 v48, s2, v48
	v_cmp_gt_i32_e64 s[4:5], s21, v48
	s_and_b64 s[4:5], vcc, s[4:5]
	s_and_saveexec_b64 s[0:1], s[4:5]
	v_lshl_add_u32 v48, v48, 2, s20
	v_or_b32_e32 v49, 0x1c00, v2
	ds_write_b32 v48, v49
	s_or_b64 exec, exec, s[0:1]
	s_bcnt1_i32_b64 s0, vcc
	v_cmp_eq_u32_e32 vcc, v51, v34
	s_add_i32 s2, s2, s0
	s_nop 0
	v_mbcnt_lo_u32_b32 v48, vcc_lo, 0
	v_mbcnt_hi_u32_b32 v48, vcc_hi, v48
	v_add_u32_e32 v48, s2, v48
	v_cmp_gt_i32_e64 s[4:5], s21, v48
	s_and_b64 s[4:5], vcc, s[4:5]
	s_and_saveexec_b64 s[0:1], s[4:5]
	v_lshl_add_u32 v48, v48, 2, s20
	v_or_b32_e32 v49, 0x1c40, v2
	ds_write_b32 v48, v49
	s_or_b64 exec, exec, s[0:1]
	s_bcnt1_i32_b64 s0, vcc
	v_cmp_eq_u32_e32 vcc, v47, v34
	s_add_i32 s2, s2, s0
	s_nop 0
	v_mbcnt_lo_u32_b32 v47, vcc_lo, 0
	v_mbcnt_hi_u32_b32 v47, vcc_hi, v47
	v_add_u32_e32 v47, s2, v47
	v_cmp_gt_i32_e64 s[4:5], s21, v47
	s_and_b64 s[4:5], vcc, s[4:5]
	s_and_saveexec_b64 s[0:1], s[4:5]
	v_lshl_add_u32 v47, v47, 2, s20
	v_or_b32_e32 v48, 0x1c80, v2
	ds_write_b32 v47, v48
	s_or_b64 exec, exec, s[0:1]
	s_bcnt1_i32_b64 s0, vcc
	v_cmp_eq_u32_e32 vcc, v46, v34
	s_add_i32 s2, s2, s0
	s_nop 0
	v_mbcnt_lo_u32_b32 v46, vcc_lo, 0
	v_mbcnt_hi_u32_b32 v46, vcc_hi, v46
	v_add_u32_e32 v46, s2, v46
	v_cmp_gt_i32_e64 s[4:5], s21, v46
	s_and_b64 s[4:5], vcc, s[4:5]
	s_and_saveexec_b64 s[0:1], s[4:5]
	v_lshl_add_u32 v46, v46, 2, s20
	v_or_b32_e32 v47, 0x1cc0, v2
	ds_write_b32 v46, v47
; DI unsigned mbcnt64(unsigned long long m) { return __builtin_amdgcn_mbcnt_hi((unsigned)(m >> 32), __builtin_amdgcn_mbcnt_lo((unsigned)m, 0u)); }
; template <int NV>
; DI void topk_row(const float* row, int s, LAS int* lst, int lane) {
;     ...
;     for (int j = 0; j < NV; ++j) { const bool sg = key[j] > T; const unsigned long long mg = __ballot(sg); if (sg) lst[bgt + (int)mbcnt64(mg)] = j * 64 + lane; bgt += __builtin_popcountll(mg); }
; #pragma unroll
;     for (int j = 0; j < NV; ++j) { const bool se = key[j] == T; const unsigned long long me = __ballot(se); const int pe = bgt + (int)mbcnt64(me); if (se && pe < 256) lst[pe] = j * 64 + lane; bgt += __builtin_popcountll(me); }
	s_or_b64 exec, exec, s[0:1]
	s_bcnt1_i32_b64 s0, vcc
	v_cmp_eq_u32_e32 vcc, v45, v34
	s_add_i32 s2, s2, s0
	s_nop 0
	v_mbcnt_lo_u32_b32 v45, vcc_lo, 0
	v_mbcnt_hi_u32_b32 v45, vcc_hi, v45
	v_add_u32_e32 v45, s2, v45
	v_cmp_gt_i32_e64 s[4:5], s21, v45
	s_and_b64 s[4:5], vcc, s[4:5]
	s_and_saveexec_b64 s[0:1], s[4:5]
	v_lshl_add_u32 v45, v45, 2, s20
	v_or_b32_e32 v46, 0x1d00, v2
	ds_write_b32 v45, v46
	s_or_b64 exec, exec, s[0:1]
	s_bcnt1_i32_b64 s0, vcc
	v_cmp_eq_u32_e32 vcc, v44, v34
	s_add_i32 s2, s2, s0
	s_nop 0
	v_mbcnt_lo_u32_b32 v44, vcc_lo, 0
	v_mbcnt_hi_u32_b32 v44, vcc_hi, v44
	v_add_u32_e32 v44, s2, v44
	v_cmp_gt_i32_e64 s[4:5], s21, v44
	s_and_b64 s[4:5], vcc, s[4:5]
	s_and_saveexec_b64 s[0:1], s[4:5]
	v_lshl_add_u32 v44, v44, 2, s20
	v_or_b32_e32 v45, 0x1d40, v2
	ds_write_b32 v44, v45
	s_or_b64 exec, exec, s[0:1]
	s_bcnt1_i32_b64 s0, vcc
	v_cmp_eq_u32_e32 vcc, v43, v34
	s_add_i32 s2, s2, s0
	s_nop 0
	v_mbcnt_lo_u32_b32 v43, vcc_lo, 0
	v_mbcnt_hi_u32_b32 v43, vcc_hi, v43
	v_add_u32_e32 v43, s2, v43
	v_cmp_gt_i32_e64 s[4:5], s21, v43
	s_and_b64 s[4:5], vcc, s[4:5]
	s_and_saveexec_b64 s[0:1], s[4:5]
	v_lshl_add_u32 v43, v43, 2, s20
	v_or_b32_e32 v44, 0x1d80, v2
	ds_write_b32 v43, v44
	s_or_b64 exec, exec, s[0:1]
	s_bcnt1_i32_b64 s0, vcc
	v_cmp_eq_u32_e32 vcc, v42, v34
	s_add_i32 s2, s2, s0
	s_nop 0
	v_mbcnt_lo_u32_b32 v42, vcc_lo, 0
	v_mbcnt_hi_u32_b32 v42, vcc_hi, v42
	v_add_u32_e32 v42, s2, v42
	v_cmp_gt_i32_e64 s[4:5], s21, v42
	s_and_b64 s[4:5], vcc, s[4:5]
	s_and_saveexec_b64 s[0:1], s[4:5]
	v_lshl_add_u32 v42, v42, 2, s20
	v_or_b32_e32 v43, 0x1dc0, v2
	ds_write_b32 v42, v43
	s_or_b64 exec, exec, s[0:1]
	s_bcnt1_i32_b64 s0, vcc
	v_cmp_eq_u32_e32 vcc, v41, v34
	s_add_i32 s2, s2, s0
	s_nop 0
	v_mbcnt_lo_u32_b32 v41, vcc_lo, 0
	v_mbcnt_hi_u32_b32 v41, vcc_hi, v41
	v_add_u32_e32 v41, s2, v41
	v_cmp_gt_i32_e64 s[4:5], s21, v41
	s_and_b64 s[4:5], vcc, s[4:5]
	s_and_saveexec_b64 s[0:1], s[4:5]
	v_lshl_add_u32 v41, v41, 2, s20
	v_or_b32_e32 v42, 0x1e00, v2
	ds_write_b32 v41, v42
	s_or_b64 exec, exec, s[0:1]
	s_bcnt1_i32_b64 s0, vcc
	v_cmp_eq_u32_e32 vcc, v40, v34
	s_add_i32 s2, s2, s0
	s_nop 0
	v_mbcnt_lo_u32_b32 v40, vcc_lo, 0
	v_mbcnt_hi_u32_b32 v40, vcc_hi, v40
	v_add_u32_e32 v40, s2, v40
	v_cmp_gt_i32_e64 s[4:5], s21, v40
	s_and_b64 s[4:5], vcc, s[4:5]
	s_and_saveexec_b64 s[0:1], s[4:5]
	v_lshl_add_u32 v40, v40, 2, s20
	ds_write_b32 v40, v153
	s_or_b64 exec, exec, s[0:1]
	s_bcnt1_i32_b64 s0, vcc
	v_cmp_eq_u32_e32 vcc, v39, v34
	s_add_i32 s2, s2, s0
	s_nop 0
	v_mbcnt_lo_u32_b32 v39, vcc_lo, 0
	v_mbcnt_hi_u32_b32 v39, vcc_hi, v39
	v_add_u32_e32 v39, s2, v39
	v_cmp_gt_i32_e64 s[4:5], s21, v39
	s_and_b64 s[4:5], vcc, s[4:5]
	s_and_saveexec_b64 s[0:1], s[4:5]
	v_lshl_add_u32 v39, v39, 2, s20
	ds_write_b32 v39, v154
	s_or_b64 exec, exec, s[0:1]
	s_bcnt1_i32_b64 s0, vcc
	v_cmp_eq_u32_e32 vcc, v38, v34
	s_add_i32 s2, s2, s0
	s_nop 0
	v_mbcnt_lo_u32_b32 v38, vcc_lo, 0
	v_mbcnt_hi_u32_b32 v38, vcc_hi, v38
	v_add_u32_e32 v38, s2, v38
	v_cmp_gt_i32_e64 s[4:5], s21, v38
	s_and_b64 s[4:5], vcc, s[4:5]
	s_and_saveexec_b64 s[0:1], s[4:5]
	v_lshl_add_u32 v38, v38, 2, s20
	ds_write_b32 v38, v155
	s_or_b64 exec, exec, s[0:1]
	s_bcnt1_i32_b64 s0, vcc
	v_cmp_eq_u32_e32 vcc, v37, v34
	s_add_i32 s2, s2, s0
	s_nop 0
	v_mbcnt_lo_u32_b32 v37, vcc_lo, 0
	v_mbcnt_hi_u32_b32 v37, vcc_hi, v37
	v_add_u32_e32 v37, s2, v37
	v_cmp_gt_i32_e64 s[4:5], s21, v37
	s_and_b64 s[4:5], vcc, s[4:5]
	s_and_saveexec_b64 s[0:1], s[4:5]
	v_lshl_add_u32 v37, v37, 2, s20
	ds_write_b32 v37, v156
	s_or_b64 exec, exec, s[0:1]
	s_bcnt1_i32_b64 s0, vcc
	v_cmp_eq_u32_e32 vcc, v36, v34
	s_add_i32 s2, s2, s0
	s_nop 0
	v_mbcnt_lo_u32_b32 v36, vcc_lo, 0
	v_mbcnt_hi_u32_b32 v36, vcc_hi, v36
	v_add_u32_e32 v36, s2, v36
	v_cmp_gt_i32_e64 s[4:5], s21, v36
	s_and_b64 s[4:5], vcc, s[4:5]
	s_and_saveexec_b64 s[0:1], s[4:5]
	v_lshl_add_u32 v36, v36, 2, s20
	ds_write_b32 v36, v157
	s_or_b64 exec, exec, s[0:1]
	s_bcnt1_i32_b64 s0, vcc
	v_cmp_eq_u32_e32 vcc, v35, v34
	s_add_i32 s2, s2, s0
	s_nop 0
	v_mbcnt_lo_u32_b32 v35, vcc_lo, 0
	v_mbcnt_hi_u32_b32 v35, vcc_hi, v35
	v_add_u32_e32 v35, s2, v35
	v_cmp_gt_i32_e64 s[4:5], s21, v35
	s_and_b64 s[4:5], vcc, s[4:5]
	s_and_saveexec_b64 s[0:1], s[4:5]
	v_lshl_add_u32 v35, v35, 2, s20
	ds_write_b32 v35, v158
	s_or_b64 exec, exec, s[0:1]
	s_bcnt1_i32_b64 s0, vcc
	v_cmp_eq_u32_e32 vcc, v0, v34
	s_add_i32 s2, s2, s0
	s_nop 0
	v_mbcnt_lo_u32_b32 v0, vcc_lo, 0
	v_mbcnt_hi_u32_b32 v0, vcc_hi, v0
	v_add_u32_e32 v0, s2, v0
	v_cmp_gt_i32_e64 s[4:5], s21, v0
	s_and_b64 s[0:1], vcc, s[4:5]
	v_mov_b32_e32 v34, v159
	s_branch .LBB0_2869
.Lp12_skip2_0:
	s_mov_b64 s[0:1], 0
	s_branch .LBB0_3257

; DI unsigned mbcnt64(unsigned long long m) { return __builtin_amdgcn_mbcnt_hi((unsigned)(m >> 32), __builtin_amdgcn_mbcnt_lo((unsigned)m, 0u)); }
; template <int NV>
; DI void topk_row(const float* row, int s, LAS int* lst, int lane) {
;     ...
;     int bgt = 0;
; #pragma unroll
;     for (int j = 0; j < NV; ++j) { const bool sg = key[j] > T; const unsigned long long mg = __ballot(sg); if (sg) lst[bgt + (int)mbcnt64(mg)] = j * 64 + lane; bgt += __builtin_popcountll(mg); }
; #pragma unroll
;     for (int j = 0; j < NV; ++j) { const bool se = key[j] == T; const unsigned long long me = __ballot(se); const int pe = bgt + (int)mbcnt64(me); if (se && pe < 256) lst[pe] = j * 64 + lane; bgt += __builtin_popcountll(me); }
.LBB0_2678:
	s_or_b64 exec, exec, s[0:1]
	s_bcnt1_i32_b64 s0, vcc
	v_cmp_eq_u32_e32 vcc, v221, v34
	s_add_i32 s2, s2, s0
	s_cmpk_eq_i32 s2, 0x100
	s_cbranch_scc1 .Lp12_skip2_1
	s_nop 0
	v_mbcnt_lo_u32_b32 v53, vcc_lo, 0
	v_mbcnt_hi_u32_b32 v53, vcc_hi, v53
	v_add_u32_e32 v53, s2, v53
	v_cmp_gt_i32_e64 s[4:5], s21, v53
	s_and_b64 s[4:5], vcc, s[4:5]
	s_and_saveexec_b64 s[0:1], s[4:5]
	v_lshl_add_u32 v53, v53, 2, s20
	ds_write_b32 v53, v2
	s_or_b64 exec, exec, s[0:1]
	s_bcnt1_i32_b64 s0, vcc
	v_cmp_eq_u32_e32 vcc, v220, v34
	s_add_i32 s2, s2, s0
	s_nop 0
	v_mbcnt_lo_u32_b32 v53, vcc_lo, 0
	v_mbcnt_hi_u32_b32 v53, vcc_hi, v53
	v_add_u32_e32 v53, s2, v53
	v_cmp_gt_i32_e64 s[4:5], s21, v53
	s_and_b64 s[4:5], vcc, s[4:5]
	s_and_saveexec_b64 s[0:1], s[4:5]
	v_lshl_add_u32 v53, v53, 2, s20
	ds_write_b32 v53, v4
	s_or_b64 exec, exec, s[0:1]
	s_bcnt1_i32_b64 s0, vcc
	v_cmp_eq_u32_e32 vcc, v219, v34
	s_add_i32 s2, s2, s0
	s_nop 0
	v_mbcnt_lo_u32_b32 v53, vcc_lo, 0
	v_mbcnt_hi_u32_b32 v53, vcc_hi, v53
	v_add_u32_e32 v53, s2, v53
	v_cmp_gt_i32_e64 s[4:5], s21, v53
	s_and_b64 s[4:5], vcc, s[4:5]
	s_and_saveexec_b64 s[0:1], s[4:5]
	v_lshl_add_u32 v53, v53, 2, s20
	ds_write_b32 v53, v6
	s_or_b64 exec, exec, s[0:1]
	s_bcnt1_i32_b64 s0, vcc
	v_cmp_eq_u32_e32 vcc, v218, v34
	s_add_i32 s2, s2, s0
	s_nop 0
	v_mbcnt_lo_u32_b32 v53, vcc_lo, 0
	v_mbcnt_hi_u32_b32 v53, vcc_hi, v53
	v_add_u32_e32 v53, s2, v53
	v_cmp_gt_i32_e64 s[4:5], s21, v53
	s_and_b64 s[4:5], vcc, s[4:5]
	s_and_saveexec_b64 s[0:1], s[4:5]
	v_lshl_add_u32 v53, v53, 2, s20
	ds_write_b32 v53, v8
	s_or_b64 exec, exec, s[0:1]
	s_bcnt1_i32_b64 s0, vcc
	v_cmp_eq_u32_e32 vcc, v217, v34
	s_add_i32 s2, s2, s0
	s_nop 0
	v_mbcnt_lo_u32_b32 v53, vcc_lo, 0
	v_mbcnt_hi_u32_b32 v53, vcc_hi, v53
	v_add_u32_e32 v53, s2, v53
	v_cmp_gt_i32_e64 s[4:5], s21, v53
	s_and_b64 s[4:5], vcc, s[4:5]
	s_and_saveexec_b64 s[0:1], s[4:5]
	v_lshl_add_u32 v53, v53, 2, s20
	ds_write_b32 v53, v10
	s_or_b64 exec, exec, s[0:1]
	s_bcnt1_i32_b64 s0, vcc
	v_cmp_eq_u32_e32 vcc, v216, v34
	s_add_i32 s2, s2, s0
	s_nop 0
	v_mbcnt_lo_u32_b32 v53, vcc_lo, 0
	v_mbcnt_hi_u32_b32 v53, vcc_hi, v53
	v_add_u32_e32 v53, s2, v53
	v_cmp_gt_i32_e64 s[4:5], s21, v53
	s_and_b64 s[4:5], vcc, s[4:5]
	s_and_saveexec_b64 s[0:1], s[4:5]
	v_lshl_add_u32 v53, v53, 2, s20
	ds_write_b32 v53, v12
	s_or_b64 exec, exec, s[0:1]
	s_bcnt1_i32_b64 s0, vcc
	v_cmp_eq_u32_e32 vcc, v215, v34
	s_add_i32 s2, s2, s0
	s_nop 0
	v_mbcnt_lo_u32_b32 v53, vcc_lo, 0
	v_mbcnt_hi_u32_b32 v53, vcc_hi, v53
	v_add_u32_e32 v53, s2, v53
	v_cmp_gt_i32_e64 s[4:5], s21, v53
	s_and_b64 s[4:5], vcc, s[4:5]
	s_and_saveexec_b64 s[0:1], s[4:5]
	v_lshl_add_u32 v53, v53, 2, s20
	ds_write_b32 v53, v14
	s_or_b64 exec, exec, s[0:1]
	s_bcnt1_i32_b64 s0, vcc
	v_cmp_eq_u32_e32 vcc, v214, v34
	s_add_i32 s2, s2, s0
	s_nop 0
	v_mbcnt_lo_u32_b32 v53, vcc_lo, 0
	v_mbcnt_hi_u32_b32 v53, vcc_hi, v53
	v_add_u32_e32 v53, s2, v53
	v_cmp_gt_i32_e64 s[4:5], s21, v53
	s_and_b64 s[4:5], vcc, s[4:5]
	s_and_saveexec_b64 s[0:1], s[4:5]
	v_lshl_add_u32 v53, v53, 2, s20
	ds_write_b32 v53, v16
	s_or_b64 exec, exec, s[0:1]
	s_bcnt1_i32_b64 s0, vcc
	v_cmp_eq_u32_e32 vcc, v213, v34
	s_add_i32 s2, s2, s0
	s_nop 0
	v_mbcnt_lo_u32_b32 v53, vcc_lo, 0
	v_mbcnt_hi_u32_b32 v53, vcc_hi, v53
	v_add_u32_e32 v53, s2, v53
	v_cmp_gt_i32_e64 s[4:5], s21, v53
	s_and_b64 s[4:5], vcc, s[4:5]
	s_and_saveexec_b64 s[0:1], s[4:5]
	v_lshl_add_u32 v53, v53, 2, s20
	ds_write_b32 v53, v18
	s_or_b64 exec, exec, s[0:1]
	s_bcnt1_i32_b64 s0, vcc
	v_cmp_eq_u32_e32 vcc, v211, v34
	s_add_i32 s2, s2, s0
	s_nop 0
	v_mbcnt_lo_u32_b32 v53, vcc_lo, 0
	v_mbcnt_hi_u32_b32 v53, vcc_hi, v53
	v_add_u32_e32 v53, s2, v53
	v_cmp_gt_i32_e64 s[4:5], s21, v53
	s_and_b64 s[4:5], vcc, s[4:5]
	s_and_saveexec_b64 s[0:1], s[4:5]
	v_lshl_add_u32 v53, v53, 2, s20
	ds_write_b32 v53, v20
	s_or_b64 exec, exec, s[0:1]
	s_bcnt1_i32_b64 s0, vcc
	v_cmp_eq_u32_e32 vcc, v206, v34
	s_add_i32 s2, s2, s0
	s_nop 0
	v_mbcnt_lo_u32_b32 v53, vcc_lo, 0
	v_mbcnt_hi_u32_b32 v53, vcc_hi, v53
	v_add_u32_e32 v53, s2, v53
	v_cmp_gt_i32_e64 s[4:5], s21, v53
	s_and_b64 s[4:5], vcc, s[4:5]
	s_and_saveexec_b64 s[0:1], s[4:5]
	v_lshl_add_u32 v53, v53, 2, s20
	ds_write_b32 v53, v22
	s_or_b64 exec, exec, s[0:1]
	s_bcnt1_i32_b64 s0, vcc
	v_cmp_eq_u32_e32 vcc, v203, v34
	s_add_i32 s2, s2, s0
	s_nop 0
	v_mbcnt_lo_u32_b32 v53, vcc_lo, 0
	v_mbcnt_hi_u32_b32 v53, vcc_hi, v53
	v_add_u32_e32 v53, s2, v53
	v_cmp_gt_i32_e64 s[4:5], s21, v53
	s_and_b64 s[4:5], vcc, s[4:5]
	s_and_saveexec_b64 s[0:1], s[4:5]
	v_lshl_add_u32 v53, v53, 2, s20
	ds_write_b32 v53, v24
	s_or_b64 exec, exec, s[0:1]
	s_bcnt1_i32_b64 s0, vcc
	v_cmp_eq_u32_e32 vcc, v200, v34
	s_add_i32 s2, s2, s0
	s_nop 0
	v_mbcnt_lo_u32_b32 v53, vcc_lo, 0
	v_mbcnt_hi_u32_b32 v53, vcc_hi, v53
	v_add_u32_e32 v53, s2, v53
	v_cmp_gt_i32_e64 s[4:5], s21, v53
	s_and_b64 s[4:5], vcc, s[4:5]
	s_and_saveexec_b64 s[0:1], s[4:5]
	v_lshl_add_u32 v53, v53, 2, s20
	ds_write_b32 v53, v26
	s_or_b64 exec, exec, s[0:1]
	s_bcnt1_i32_b64 s0, vcc
	v_cmp_eq_u32_e32 vcc, v202, v34
	s_add_i32 s2, s2, s0
	s_nop 0
	v_mbcnt_lo_u32_b32 v53, vcc_lo, 0
	v_mbcnt_hi_u32_b32 v53, vcc_hi, v53
	v_add_u32_e32 v53, s2, v53
	v_cmp_gt_i32_e64 s[4:5], s21, v53
	s_and_b64 s[4:5], vcc, s[4:5]
	s_and_saveexec_b64 s[0:1], s[4:5]
	v_lshl_add_u32 v53, v53, 2, s20
	ds_write_b32 v53, v28
	s_or_b64 exec, exec, s[0:1]
	s_bcnt1_i32_b64 s0, vcc
	v_cmp_eq_u32_e32 vcc, v204, v34
	s_add_i32 s2, s2, s0
	s_nop 0
	v_mbcnt_lo_u32_b32 v53, vcc_lo, 0
	v_mbcnt_hi_u32_b32 v53, vcc_hi, v53
	v_add_u32_e32 v53, s2, v53
	v_cmp_gt_i32_e64 s[4:5], s21, v53
	s_and_b64 s[4:5], vcc, s[4:5]
	s_and_saveexec_b64 s[0:1], s[4:5]
; DI unsigned mbcnt64(unsigned long long m) { return __builtin_amdgcn_mbcnt_hi((unsigned)(m >> 32), __builtin_amdgcn_mbcnt_lo((unsigned)m, 0u)); }
; template <int NV>
; DI void topk_row(const float* row, int s, LAS int* lst, int lane) {
;     ...
;     for (int j = 0; j < NV; ++j) { const bool sg = key[j] > T; const unsigned long long mg = __ballot(sg); if (sg) lst[bgt + (int)mbcnt64(mg)] = j * 64 + lane; bgt += __builtin_popcountll(mg); }
; #pragma unroll
;     for (int j = 0; j < NV; ++j) { const bool se = key[j] == T; const unsigned long long me = __ballot(se); const int pe = bgt + (int)mbcnt64(me); if (se && pe < 256) lst[pe] = j * 64 + lane; bgt += __builtin_popcountll(me); }
	v_lshl_add_u32 v53, v53, 2, s20
	ds_write_b32 v53, v30
	s_or_b64 exec, exec, s[0:1]
	s_bcnt1_i32_b64 s0, vcc
	v_cmp_eq_u32_e32 vcc, v207, v34
	s_add_i32 s2, s2, s0
	s_nop 0
	v_mbcnt_lo_u32_b32 v53, vcc_lo, 0
	v_mbcnt_hi_u32_b32 v53, vcc_hi, v53
	v_add_u32_e32 v53, s2, v53
	v_cmp_gt_i32_e64 s[4:5], s21, v53
	s_and_b64 s[4:5], vcc, s[4:5]
	s_and_saveexec_b64 s[0:1], s[4:5]
	v_lshl_add_u32 v53, v53, 2, s20
	ds_write_b32 v53, v32
	s_or_b64 exec, exec, s[0:1]
	s_bcnt1_i32_b64 s0, vcc
	v_cmp_eq_u32_e32 vcc, v208, v34
	s_add_i32 s2, s2, s0
	s_nop 0
	v_mbcnt_lo_u32_b32 v53, vcc_lo, 0
	v_mbcnt_hi_u32_b32 v53, vcc_hi, v53
	v_add_u32_e32 v53, s2, v53
	v_cmp_gt_i32_e64 s[4:5], s21, v53
	s_and_b64 s[4:5], vcc, s[4:5]
	s_and_saveexec_b64 s[0:1], s[4:5]
	v_lshl_add_u32 v53, v53, 2, s20
	ds_write_b32 v53, v3
	s_or_b64 exec, exec, s[0:1]
	s_bcnt1_i32_b64 s0, vcc
	v_cmp_eq_u32_e32 vcc, v212, v34
	s_add_i32 s2, s2, s0
	s_nop 0
	v_mbcnt_lo_u32_b32 v53, vcc_lo, 0
	v_mbcnt_hi_u32_b32 v53, vcc_hi, v53
	v_add_u32_e32 v53, s2, v53
	v_cmp_gt_i32_e64 s[4:5], s21, v53
	s_and_b64 s[4:5], vcc, s[4:5]
	s_and_saveexec_b64 s[0:1], s[4:5]
	v_lshl_add_u32 v53, v53, 2, s20
	ds_write_b32 v53, v5
	s_or_b64 exec, exec, s[0:1]
	s_bcnt1_i32_b64 s0, vcc
	v_cmp_eq_u32_e32 vcc, v210, v34
	s_add_i32 s2, s2, s0
	s_nop 0
	v_mbcnt_lo_u32_b32 v53, vcc_lo, 0
	v_mbcnt_hi_u32_b32 v53, vcc_hi, v53
	v_add_u32_e32 v53, s2, v53
	v_cmp_gt_i32_e64 s[4:5], s21, v53
	s_and_b64 s[4:5], vcc, s[4:5]
	s_and_saveexec_b64 s[0:1], s[4:5]
	v_lshl_add_u32 v53, v53, 2, s20
	ds_write_b32 v53, v7
	s_or_b64 exec, exec, s[0:1]
	s_bcnt1_i32_b64 s0, vcc
	v_cmp_eq_u32_e32 vcc, v209, v34
	s_add_i32 s2, s2, s0
	s_nop 0
	v_mbcnt_lo_u32_b32 v53, vcc_lo, 0
	v_mbcnt_hi_u32_b32 v53, vcc_hi, v53
	v_add_u32_e32 v53, s2, v53
	v_cmp_gt_i32_e64 s[4:5], s21, v53
	s_and_b64 s[4:5], vcc, s[4:5]
	s_and_saveexec_b64 s[0:1], s[4:5]
	v_lshl_add_u32 v53, v53, 2, s20
	ds_write_b32 v53, v9
	s_or_b64 exec, exec, s[0:1]
	s_bcnt1_i32_b64 s0, vcc
	v_cmp_eq_u32_e32 vcc, v205, v34
	s_add_i32 s2, s2, s0
	s_nop 0
	v_mbcnt_lo_u32_b32 v53, vcc_lo, 0
	v_mbcnt_hi_u32_b32 v53, vcc_hi, v53
	v_add_u32_e32 v53, s2, v53
	v_cmp_gt_i32_e64 s[4:5], s21, v53
	s_and_b64 s[4:5], vcc, s[4:5]
	s_and_saveexec_b64 s[0:1], s[4:5]
	v_lshl_add_u32 v53, v53, 2, s20
	ds_write_b32 v53, v11
	s_or_b64 exec, exec, s[0:1]
	s_bcnt1_i32_b64 s0, vcc
	v_cmp_eq_u32_e32 vcc, v201, v34
	s_add_i32 s2, s2, s0
	s_nop 0
	v_mbcnt_lo_u32_b32 v53, vcc_lo, 0
	v_mbcnt_hi_u32_b32 v53, vcc_hi, v53
	v_add_u32_e32 v53, s2, v53
	v_cmp_gt_i32_e64 s[4:5], s21, v53
	s_and_b64 s[4:5], vcc, s[4:5]
	s_and_saveexec_b64 s[0:1], s[4:5]
	v_lshl_add_u32 v53, v53, 2, s20
	ds_write_b32 v53, v13
	s_or_b64 exec, exec, s[0:1]
	s_bcnt1_i32_b64 s0, vcc
	v_cmp_eq_u32_e32 vcc, v199, v34
	s_add_i32 s2, s2, s0
	s_nop 0
	v_mbcnt_lo_u32_b32 v53, vcc_lo, 0
	v_mbcnt_hi_u32_b32 v53, vcc_hi, v53
	v_add_u32_e32 v53, s2, v53
	v_cmp_gt_i32_e64 s[4:5], s21, v53
	s_and_b64 s[4:5], vcc, s[4:5]
	s_and_saveexec_b64 s[0:1], s[4:5]
	v_lshl_add_u32 v53, v53, 2, s20
	ds_write_b32 v53, v15
	s_or_b64 exec, exec, s[0:1]
	s_bcnt1_i32_b64 s0, vcc
	v_cmp_eq_u32_e32 vcc, v198, v34
	s_add_i32 s2, s2, s0
	s_nop 0
	v_mbcnt_lo_u32_b32 v53, vcc_lo, 0
	v_mbcnt_hi_u32_b32 v53, vcc_hi, v53
	v_add_u32_e32 v53, s2, v53
	v_cmp_gt_i32_e64 s[4:5], s21, v53
	s_and_b64 s[4:5], vcc, s[4:5]
	s_and_saveexec_b64 s[0:1], s[4:5]
	v_lshl_add_u32 v53, v53, 2, s20
	ds_write_b32 v53, v17
	s_or_b64 exec, exec, s[0:1]
	s_bcnt1_i32_b64 s0, vcc
	v_cmp_eq_u32_e32 vcc, v197, v34
	s_add_i32 s2, s2, s0
	s_nop 0
	v_mbcnt_lo_u32_b32 v53, vcc_lo, 0
	v_mbcnt_hi_u32_b32 v53, vcc_hi, v53
	v_add_u32_e32 v53, s2, v53
	v_cmp_gt_i32_e64 s[4:5], s21, v53
	s_and_b64 s[4:5], vcc, s[4:5]
	s_and_saveexec_b64 s[0:1], s[4:5]
	v_lshl_add_u32 v53, v53, 2, s20
	ds_write_b32 v53, v19
	s_or_b64 exec, exec, s[0:1]
	s_bcnt1_i32_b64 s0, vcc
	v_cmp_eq_u32_e32 vcc, v196, v34
	s_add_i32 s2, s2, s0
	s_nop 0
	v_mbcnt_lo_u32_b32 v53, vcc_lo, 0
	v_mbcnt_hi_u32_b32 v53, vcc_hi, v53
	v_add_u32_e32 v53, s2, v53
	v_cmp_gt_i32_e64 s[4:5], s21, v53
	s_and_b64 s[4:5], vcc, s[4:5]
	s_and_saveexec_b64 s[0:1], s[4:5]
	v_lshl_add_u32 v53, v53, 2, s20
	ds_write_b32 v53, v21
	s_or_b64 exec, exec, s[0:1]
	s_bcnt1_i32_b64 s0, vcc
	v_cmp_eq_u32_e32 vcc, v195, v34
	s_add_i32 s2, s2, s0
	s_nop 0
	v_mbcnt_lo_u32_b32 v53, vcc_lo, 0
	v_mbcnt_hi_u32_b32 v53, vcc_hi, v53
	v_add_u32_e32 v53, s2, v53
	v_cmp_gt_i32_e64 s[4:5], s21, v53
	s_and_b64 s[4:5], vcc, s[4:5]
	s_and_saveexec_b64 s[0:1], s[4:5]
	v_lshl_add_u32 v53, v53, 2, s20
	ds_write_b32 v53, v23
	s_or_b64 exec, exec, s[0:1]
	s_bcnt1_i32_b64 s0, vcc
	v_cmp_eq_u32_e32 vcc, v194, v34
	s_add_i32 s2, s2, s0
	s_nop 0
	v_mbcnt_lo_u32_b32 v53, vcc_lo, 0
	v_mbcnt_hi_u32_b32 v53, vcc_hi, v53
	v_add_u32_e32 v53, s2, v53
	v_cmp_gt_i32_e64 s[4:5], s21, v53
	s_and_b64 s[4:5], vcc, s[4:5]
	s_and_saveexec_b64 s[0:1], s[4:5]
	v_lshl_add_u32 v53, v53, 2, s20
	ds_write_b32 v53, v25
	s_or_b64 exec, exec, s[0:1]
	s_bcnt1_i32_b64 s0, vcc
	v_cmp_eq_u32_e32 vcc, v193, v34
	s_add_i32 s2, s2, s0
	s_nop 0
	v_mbcnt_lo_u32_b32 v53, vcc_lo, 0
	v_mbcnt_hi_u32_b32 v53, vcc_hi, v53
	v_add_u32_e32 v53, s2, v53
	v_cmp_gt_i32_e64 s[4:5], s21, v53
	s_and_b64 s[4:5], vcc, s[4:5]
	s_and_saveexec_b64 s[0:1], s[4:5]
	v_lshl_add_u32 v53, v53, 2, s20
	ds_write_b32 v53, v27
	s_or_b64 exec, exec, s[0:1]
	s_bcnt1_i32_b64 s0, vcc
	v_cmp_eq_u32_e32 vcc, v192, v34
	s_add_i32 s2, s2, s0
	s_nop 0
	v_mbcnt_lo_u32_b32 v53, vcc_lo, 0
	v_mbcnt_hi_u32_b32 v53, vcc_hi, v53
	v_add_u32_e32 v53, s2, v53
	v_cmp_gt_i32_e64 s[4:5], s21, v53
	s_and_b64 s[4:5], vcc, s[4:5]
	s_and_saveexec_b64 s[0:1], s[4:5]
	v_lshl_add_u32 v53, v53, 2, s20
; DI unsigned mbcnt64(unsigned long long m) { return __builtin_amdgcn_mbcnt_hi((unsigned)(m >> 32), __builtin_amdgcn_mbcnt_lo((unsigned)m, 0u)); }
; template <int NV>
; DI void topk_row(const float* row, int s, LAS int* lst, int lane) {
;     ...
;     for (int j = 0; j < NV; ++j) { const bool sg = key[j] > T; const unsigned long long mg = __ballot(sg); if (sg) lst[bgt + (int)mbcnt64(mg)] = j * 64 + lane; bgt += __builtin_popcountll(mg); }
; #pragma unroll
;     for (int j = 0; j < NV; ++j) { const bool se = key[j] == T; const unsigned long long me = __ballot(se); const int pe = bgt + (int)mbcnt64(me); if (se && pe < 256) lst[pe] = j * 64 + lane; bgt += __builtin_popcountll(me); }
	ds_write_b32 v53, v29
	s_or_b64 exec, exec, s[0:1]
	s_bcnt1_i32_b64 s0, vcc
	v_cmp_eq_u32_e32 vcc, v191, v34
	s_add_i32 s2, s2, s0
	s_nop 0
	v_mbcnt_lo_u32_b32 v53, vcc_lo, 0
	v_mbcnt_hi_u32_b32 v53, vcc_hi, v53
	v_add_u32_e32 v53, s2, v53
	v_cmp_gt_i32_e64 s[4:5], s21, v53
	s_and_b64 s[4:5], vcc, s[4:5]
	s_and_saveexec_b64 s[0:1], s[4:5]
	v_lshl_add_u32 v53, v53, 2, s20
	ds_write_b32 v53, v31
	s_or_b64 exec, exec, s[0:1]
	s_bcnt1_i32_b64 s0, vcc
	v_cmp_eq_u32_e32 vcc, v190, v34
	s_add_i32 s2, s2, s0
	s_nop 0
	v_mbcnt_lo_u32_b32 v53, vcc_lo, 0
	v_mbcnt_hi_u32_b32 v53, vcc_hi, v53
	v_add_u32_e32 v53, s2, v53
	v_cmp_gt_i32_e64 s[4:5], s21, v53
	s_and_b64 s[4:5], vcc, s[4:5]
	s_and_saveexec_b64 s[0:1], s[4:5]
	v_lshl_add_u32 v53, v53, 2, s20
	ds_write_b32 v53, v33
	s_or_b64 exec, exec, s[0:1]
	s_bcnt1_i32_b64 s0, vcc
	v_cmp_eq_u32_e32 vcc, v189, v34
	s_add_i32 s2, s2, s0
	s_nop 0
	v_mbcnt_lo_u32_b32 v53, vcc_lo, 0
	v_mbcnt_hi_u32_b32 v53, vcc_hi, v53
	v_add_u32_e32 v53, s2, v53
	v_cmp_gt_i32_e64 s[4:5], s21, v53
	s_and_b64 s[4:5], vcc, s[4:5]
	s_and_saveexec_b64 s[0:1], s[4:5]
	v_lshl_add_u32 v53, v53, 2, s20
	ds_write_b32 v53, v64
	s_or_b64 exec, exec, s[0:1]
	s_bcnt1_i32_b64 s0, vcc
	v_cmp_eq_u32_e32 vcc, v188, v34
	s_add_i32 s2, s2, s0
	s_nop 0
	v_mbcnt_lo_u32_b32 v53, vcc_lo, 0
	v_mbcnt_hi_u32_b32 v53, vcc_hi, v53
	v_add_u32_e32 v53, s2, v53
	v_cmp_gt_i32_e64 s[4:5], s21, v53
	s_and_b64 s[4:5], vcc, s[4:5]
	s_and_saveexec_b64 s[0:1], s[4:5]
	v_lshl_add_u32 v53, v53, 2, s20
	ds_write_b32 v53, v65
	s_or_b64 exec, exec, s[0:1]
	s_bcnt1_i32_b64 s0, vcc
	v_cmp_eq_u32_e32 vcc, v187, v34
	s_add_i32 s2, s2, s0
	s_nop 0
	v_mbcnt_lo_u32_b32 v53, vcc_lo, 0
	v_mbcnt_hi_u32_b32 v53, vcc_hi, v53
	v_add_u32_e32 v53, s2, v53
	v_cmp_gt_i32_e64 s[4:5], s21, v53
	s_and_b64 s[4:5], vcc, s[4:5]
	s_and_saveexec_b64 s[0:1], s[4:5]
	v_lshl_add_u32 v53, v53, 2, s20
	ds_write_b32 v53, v66
	s_or_b64 exec, exec, s[0:1]
	s_bcnt1_i32_b64 s0, vcc
	v_cmp_eq_u32_e32 vcc, v186, v34
	s_add_i32 s2, s2, s0
	s_nop 0
	v_mbcnt_lo_u32_b32 v53, vcc_lo, 0
	v_mbcnt_hi_u32_b32 v53, vcc_hi, v53
	v_add_u32_e32 v53, s2, v53
	v_cmp_gt_i32_e64 s[4:5], s21, v53
	s_and_b64 s[4:5], vcc, s[4:5]
	s_and_saveexec_b64 s[0:1], s[4:5]
	v_lshl_add_u32 v53, v53, 2, s20
	ds_write_b32 v53, v67
	s_or_b64 exec, exec, s[0:1]
	s_bcnt1_i32_b64 s0, vcc
	v_cmp_eq_u32_e32 vcc, v185, v34
	s_add_i32 s2, s2, s0
	s_nop 0
	v_mbcnt_lo_u32_b32 v53, vcc_lo, 0
	v_mbcnt_hi_u32_b32 v53, vcc_hi, v53
	v_add_u32_e32 v53, s2, v53
	v_cmp_gt_i32_e64 s[4:5], s21, v53
	s_and_b64 s[4:5], vcc, s[4:5]
	s_and_saveexec_b64 s[0:1], s[4:5]
	v_lshl_add_u32 v53, v53, 2, s20
	ds_write_b32 v53, v68
	s_or_b64 exec, exec, s[0:1]
	s_bcnt1_i32_b64 s0, vcc
	v_cmp_eq_u32_e32 vcc, v184, v34
	s_add_i32 s2, s2, s0
	s_nop 0
	v_mbcnt_lo_u32_b32 v53, vcc_lo, 0
	v_mbcnt_hi_u32_b32 v53, vcc_hi, v53
	v_add_u32_e32 v53, s2, v53
	v_cmp_gt_i32_e64 s[4:5], s21, v53
	s_and_b64 s[4:5], vcc, s[4:5]
	s_and_saveexec_b64 s[0:1], s[4:5]
	v_lshl_add_u32 v53, v53, 2, s20
	ds_write_b32 v53, v69
	s_or_b64 exec, exec, s[0:1]
	s_bcnt1_i32_b64 s0, vcc
	v_cmp_eq_u32_e32 vcc, v183, v34
	s_add_i32 s2, s2, s0
	s_nop 0
	v_mbcnt_lo_u32_b32 v53, vcc_lo, 0
	v_mbcnt_hi_u32_b32 v53, vcc_hi, v53
	v_add_u32_e32 v53, s2, v53
	v_cmp_gt_i32_e64 s[4:5], s21, v53
	s_and_b64 s[4:5], vcc, s[4:5]
	s_and_saveexec_b64 s[0:1], s[4:5]
	v_lshl_add_u32 v53, v53, 2, s20
	ds_write_b32 v53, v70
	s_or_b64 exec, exec, s[0:1]
	s_bcnt1_i32_b64 s0, vcc
	v_cmp_eq_u32_e32 vcc, v182, v34
	s_add_i32 s2, s2, s0
	s_nop 0
	v_mbcnt_lo_u32_b32 v53, vcc_lo, 0
	v_mbcnt_hi_u32_b32 v53, vcc_hi, v53
	v_add_u32_e32 v53, s2, v53
	v_cmp_gt_i32_e64 s[4:5], s21, v53
	s_and_b64 s[4:5], vcc, s[4:5]
	s_and_saveexec_b64 s[0:1], s[4:5]
	v_lshl_add_u32 v53, v53, 2, s20
	ds_write_b32 v53, v71
	s_or_b64 exec, exec, s[0:1]
	s_bcnt1_i32_b64 s0, vcc
	v_cmp_eq_u32_e32 vcc, v181, v34
	s_add_i32 s2, s2, s0
	s_nop 0
	v_mbcnt_lo_u32_b32 v53, vcc_lo, 0
	v_mbcnt_hi_u32_b32 v53, vcc_hi, v53
	v_add_u32_e32 v53, s2, v53
	v_cmp_gt_i32_e64 s[4:5], s21, v53
	s_and_b64 s[4:5], vcc, s[4:5]
	s_and_saveexec_b64 s[0:1], s[4:5]
	v_lshl_add_u32 v53, v53, 2, s20
	ds_write_b32 v53, v72
	s_or_b64 exec, exec, s[0:1]
	s_bcnt1_i32_b64 s0, vcc
	v_cmp_eq_u32_e32 vcc, v180, v34
	s_add_i32 s2, s2, s0
	s_nop 0
	v_mbcnt_lo_u32_b32 v53, vcc_lo, 0
	v_mbcnt_hi_u32_b32 v53, vcc_hi, v53
	v_add_u32_e32 v53, s2, v53
	v_cmp_gt_i32_e64 s[4:5], s21, v53
	s_and_b64 s[4:5], vcc, s[4:5]
	s_and_saveexec_b64 s[0:1], s[4:5]
	v_lshl_add_u32 v53, v53, 2, s20
	ds_write_b32 v53, v73
	s_or_b64 exec, exec, s[0:1]
	s_bcnt1_i32_b64 s0, vcc
	v_cmp_eq_u32_e32 vcc, v179, v34
	s_add_i32 s2, s2, s0
	s_nop 0
	v_mbcnt_lo_u32_b32 v53, vcc_lo, 0
	v_mbcnt_hi_u32_b32 v53, vcc_hi, v53
	v_add_u32_e32 v53, s2, v53
	v_cmp_gt_i32_e64 s[4:5], s21, v53
	s_and_b64 s[4:5], vcc, s[4:5]
	s_and_saveexec_b64 s[0:1], s[4:5]
	v_lshl_add_u32 v53, v53, 2, s20
	ds_write_b32 v53, v74
	s_or_b64 exec, exec, s[0:1]
	s_bcnt1_i32_b64 s0, vcc
	v_cmp_eq_u32_e32 vcc, v178, v34
	s_add_i32 s2, s2, s0
	s_nop 0
	v_mbcnt_lo_u32_b32 v53, vcc_lo, 0
	v_mbcnt_hi_u32_b32 v53, vcc_hi, v53
	v_add_u32_e32 v53, s2, v53
	v_cmp_gt_i32_e64 s[4:5], s21, v53
	s_and_b64 s[4:5], vcc, s[4:5]
	s_and_saveexec_b64 s[0:1], s[4:5]
	v_lshl_add_u32 v53, v53, 2, s20
	ds_write_b32 v53, v75
	s_or_b64 exec, exec, s[0:1]
	s_bcnt1_i32_b64 s0, vcc
	v_cmp_eq_u32_e32 vcc, v177, v34
	s_add_i32 s2, s2, s0
	s_nop 0
	v_mbcnt_lo_u32_b32 v53, vcc_lo, 0
	v_mbcnt_hi_u32_b32 v53, vcc_hi, v53
	v_add_u32_e32 v53, s2, v53
	v_cmp_gt_i32_e64 s[4:5], s21, v53
	s_and_b64 s[4:5], vcc, s[4:5]
	s_and_saveexec_b64 s[0:1], s[4:5]
	v_lshl_add_u32 v53, v53, 2, s20
	ds_write_b32 v53, v76
; DI unsigned mbcnt64(unsigned long long m) { return __builtin_amdgcn_mbcnt_hi((unsigned)(m >> 32), __builtin_amdgcn_mbcnt_lo((unsigned)m, 0u)); }
; template <int NV>
; DI void topk_row(const float* row, int s, LAS int* lst, int lane) {
;     ...
;     for (int j = 0; j < NV; ++j) { const bool sg = key[j] > T; const unsigned long long mg = __ballot(sg); if (sg) lst[bgt + (int)mbcnt64(mg)] = j * 64 + lane; bgt += __builtin_popcountll(mg); }
; #pragma unroll
;     for (int j = 0; j < NV; ++j) { const bool se = key[j] == T; const unsigned long long me = __ballot(se); const int pe = bgt + (int)mbcnt64(me); if (se && pe < 256) lst[pe] = j * 64 + lane; bgt += __builtin_popcountll(me); }
	s_or_b64 exec, exec, s[0:1]
	s_bcnt1_i32_b64 s0, vcc
	v_cmp_eq_u32_e32 vcc, v176, v34
	s_add_i32 s2, s2, s0
	s_nop 0
	v_mbcnt_lo_u32_b32 v53, vcc_lo, 0
	v_mbcnt_hi_u32_b32 v53, vcc_hi, v53
	v_add_u32_e32 v53, s2, v53
	v_cmp_gt_i32_e64 s[4:5], s21, v53
	s_and_b64 s[4:5], vcc, s[4:5]
	s_and_saveexec_b64 s[0:1], s[4:5]
	v_lshl_add_u32 v53, v53, 2, s20
	ds_write_b32 v53, v77
	s_or_b64 exec, exec, s[0:1]
	s_bcnt1_i32_b64 s0, vcc
	v_cmp_eq_u32_e32 vcc, v175, v34
	s_add_i32 s2, s2, s0
	s_nop 0
	v_mbcnt_lo_u32_b32 v53, vcc_lo, 0
	v_mbcnt_hi_u32_b32 v53, vcc_hi, v53
	v_add_u32_e32 v53, s2, v53
	v_cmp_gt_i32_e64 s[4:5], s21, v53
	s_and_b64 s[4:5], vcc, s[4:5]
	s_and_saveexec_b64 s[0:1], s[4:5]
	v_lshl_add_u32 v53, v53, 2, s20
	ds_write_b32 v53, v78
	s_or_b64 exec, exec, s[0:1]
	s_bcnt1_i32_b64 s0, vcc
	v_cmp_eq_u32_e32 vcc, v173, v34
	s_add_i32 s2, s2, s0
	s_nop 0
	v_mbcnt_lo_u32_b32 v53, vcc_lo, 0
	v_mbcnt_hi_u32_b32 v53, vcc_hi, v53
	v_add_u32_e32 v53, s2, v53
	v_cmp_gt_i32_e64 s[4:5], s21, v53
	s_and_b64 s[4:5], vcc, s[4:5]
	s_and_saveexec_b64 s[0:1], s[4:5]
	v_lshl_add_u32 v53, v53, 2, s20
	ds_write_b32 v53, v79
	s_or_b64 exec, exec, s[0:1]
	s_bcnt1_i32_b64 s0, vcc
	v_cmp_eq_u32_e32 vcc, v174, v34
	s_add_i32 s2, s2, s0
	s_nop 0
	v_mbcnt_lo_u32_b32 v53, vcc_lo, 0
	v_mbcnt_hi_u32_b32 v53, vcc_hi, v53
	v_add_u32_e32 v53, s2, v53
	v_cmp_gt_i32_e64 s[4:5], s21, v53
	s_and_b64 s[4:5], vcc, s[4:5]
	s_and_saveexec_b64 s[0:1], s[4:5]
	v_lshl_add_u32 v53, v53, 2, s20
	ds_write_b32 v53, v80
	s_or_b64 exec, exec, s[0:1]
	s_bcnt1_i32_b64 s0, vcc
	v_cmp_eq_u32_e32 vcc, v172, v34
	s_add_i32 s2, s2, s0
	s_nop 0
	v_mbcnt_lo_u32_b32 v53, vcc_lo, 0
	v_mbcnt_hi_u32_b32 v53, vcc_hi, v53
	v_add_u32_e32 v53, s2, v53
	v_cmp_gt_i32_e64 s[4:5], s21, v53
	s_and_b64 s[4:5], vcc, s[4:5]
	s_and_saveexec_b64 s[0:1], s[4:5]
	v_lshl_add_u32 v53, v53, 2, s20
	ds_write_b32 v53, v81
	s_or_b64 exec, exec, s[0:1]
	s_bcnt1_i32_b64 s0, vcc
	v_cmp_eq_u32_e32 vcc, v171, v34
	s_add_i32 s2, s2, s0
	s_nop 0
	v_mbcnt_lo_u32_b32 v53, vcc_lo, 0
	v_mbcnt_hi_u32_b32 v53, vcc_hi, v53
	v_add_u32_e32 v53, s2, v53
	v_cmp_gt_i32_e64 s[4:5], s21, v53
	s_and_b64 s[4:5], vcc, s[4:5]
	s_and_saveexec_b64 s[0:1], s[4:5]
	v_lshl_add_u32 v53, v53, 2, s20
	ds_write_b32 v53, v82
	s_or_b64 exec, exec, s[0:1]
	s_bcnt1_i32_b64 s0, vcc
	v_cmp_eq_u32_e32 vcc, v170, v34
	s_add_i32 s2, s2, s0
	s_nop 0
	v_mbcnt_lo_u32_b32 v53, vcc_lo, 0
	v_mbcnt_hi_u32_b32 v53, vcc_hi, v53
	v_add_u32_e32 v53, s2, v53
	v_cmp_gt_i32_e64 s[4:5], s21, v53
	s_and_b64 s[4:5], vcc, s[4:5]
	s_and_saveexec_b64 s[0:1], s[4:5]
	v_lshl_add_u32 v53, v53, 2, s20
	ds_write_b32 v53, v83
	s_or_b64 exec, exec, s[0:1]
	s_bcnt1_i32_b64 s0, vcc
	v_cmp_eq_u32_e32 vcc, v169, v34
	s_add_i32 s2, s2, s0
	s_nop 0
	v_mbcnt_lo_u32_b32 v53, vcc_lo, 0
	v_mbcnt_hi_u32_b32 v53, vcc_hi, v53
	v_add_u32_e32 v53, s2, v53
	v_cmp_gt_i32_e64 s[4:5], s21, v53
	s_and_b64 s[4:5], vcc, s[4:5]
	s_and_saveexec_b64 s[0:1], s[4:5]
	v_lshl_add_u32 v53, v53, 2, s20
	ds_write_b32 v53, v84
	s_or_b64 exec, exec, s[0:1]
	s_bcnt1_i32_b64 s0, vcc
	v_cmp_eq_u32_e32 vcc, v168, v34
	s_add_i32 s2, s2, s0
	s_nop 0
	v_mbcnt_lo_u32_b32 v53, vcc_lo, 0
	v_mbcnt_hi_u32_b32 v53, vcc_hi, v53
	v_add_u32_e32 v53, s2, v53
	v_cmp_gt_i32_e64 s[4:5], s21, v53
	s_and_b64 s[4:5], vcc, s[4:5]
	s_and_saveexec_b64 s[0:1], s[4:5]
	v_lshl_add_u32 v53, v53, 2, s20
	ds_write_b32 v53, v85
	s_or_b64 exec, exec, s[0:1]
	s_bcnt1_i32_b64 s0, vcc
	v_cmp_eq_u32_e32 vcc, v167, v34
	s_add_i32 s2, s2, s0
	s_nop 0
	v_mbcnt_lo_u32_b32 v53, vcc_lo, 0
	v_mbcnt_hi_u32_b32 v53, vcc_hi, v53
	v_add_u32_e32 v53, s2, v53
	v_cmp_gt_i32_e64 s[4:5], s21, v53
	s_and_b64 s[4:5], vcc, s[4:5]
	s_and_saveexec_b64 s[0:1], s[4:5]
	v_lshl_add_u32 v53, v53, 2, s20
	ds_write_b32 v53, v86
	s_or_b64 exec, exec, s[0:1]
	s_bcnt1_i32_b64 s0, vcc
	v_cmp_eq_u32_e32 vcc, v166, v34
	s_add_i32 s2, s2, s0
	s_nop 0
	v_mbcnt_lo_u32_b32 v53, vcc_lo, 0
	v_mbcnt_hi_u32_b32 v53, vcc_hi, v53
	v_add_u32_e32 v53, s2, v53
	v_cmp_gt_i32_e64 s[4:5], s21, v53
	s_and_b64 s[4:5], vcc, s[4:5]
	s_and_saveexec_b64 s[0:1], s[4:5]
	v_lshl_add_u32 v53, v53, 2, s20
	ds_write_b32 v53, v87
	s_or_b64 exec, exec, s[0:1]
	s_bcnt1_i32_b64 s0, vcc
	v_cmp_eq_u32_e32 vcc, v165, v34
	s_add_i32 s2, s2, s0
	s_nop 0
	v_mbcnt_lo_u32_b32 v53, vcc_lo, 0
	v_mbcnt_hi_u32_b32 v53, vcc_hi, v53
	v_add_u32_e32 v53, s2, v53
	v_cmp_gt_i32_e64 s[4:5], s21, v53
	s_and_b64 s[4:5], vcc, s[4:5]
	s_and_saveexec_b64 s[0:1], s[4:5]
	v_lshl_add_u32 v53, v53, 2, s20
	ds_write_b32 v53, v88
	s_or_b64 exec, exec, s[0:1]
	s_bcnt1_i32_b64 s0, vcc
	v_cmp_eq_u32_e32 vcc, v164, v34
	s_add_i32 s2, s2, s0
	s_nop 0
	v_mbcnt_lo_u32_b32 v53, vcc_lo, 0
	v_mbcnt_hi_u32_b32 v53, vcc_hi, v53
	v_add_u32_e32 v53, s2, v53
	v_cmp_gt_i32_e64 s[4:5], s21, v53
	s_and_b64 s[4:5], vcc, s[4:5]
	s_and_saveexec_b64 s[0:1], s[4:5]
	v_lshl_add_u32 v53, v53, 2, s20
	ds_write_b32 v53, v89
	s_or_b64 exec, exec, s[0:1]
	s_bcnt1_i32_b64 s0, vcc
	v_cmp_eq_u32_e32 vcc, v163, v34
	s_add_i32 s2, s2, s0
	s_nop 0
	v_mbcnt_lo_u32_b32 v53, vcc_lo, 0
	v_mbcnt_hi_u32_b32 v53, vcc_hi, v53
	v_add_u32_e32 v53, s2, v53
	v_cmp_gt_i32_e64 s[4:5], s21, v53
	s_and_b64 s[4:5], vcc, s[4:5]
	s_and_saveexec_b64 s[0:1], s[4:5]
	v_lshl_add_u32 v53, v53, 2, s20
	ds_write_b32 v53, v90
	s_or_b64 exec, exec, s[0:1]
	s_bcnt1_i32_b64 s0, vcc
	v_cmp_eq_u32_e32 vcc, v162, v34
	s_add_i32 s2, s2, s0
	s_nop 0
	v_mbcnt_lo_u32_b32 v53, vcc_lo, 0
	v_mbcnt_hi_u32_b32 v53, vcc_hi, v53
	v_add_u32_e32 v53, s2, v53
	v_cmp_gt_i32_e64 s[4:5], s21, v53
	s_and_b64 s[4:5], vcc, s[4:5]
	s_and_saveexec_b64 s[0:1], s[4:5]
	v_lshl_add_u32 v53, v53, 2, s20
	ds_write_b32 v53, v91
	s_or_b64 exec, exec, s[0:1]
; DI unsigned mbcnt64(unsigned long long m) { return __builtin_amdgcn_mbcnt_hi((unsigned)(m >> 32), __builtin_amdgcn_mbcnt_lo((unsigned)m, 0u)); }
; template <int NV>
; DI void topk_row(const float* row, int s, LAS int* lst, int lane) {
;     ...
;     for (int j = 0; j < NV; ++j) { const bool sg = key[j] > T; const unsigned long long mg = __ballot(sg); if (sg) lst[bgt + (int)mbcnt64(mg)] = j * 64 + lane; bgt += __builtin_popcountll(mg); }
; #pragma unroll
;     for (int j = 0; j < NV; ++j) { const bool se = key[j] == T; const unsigned long long me = __ballot(se); const int pe = bgt + (int)mbcnt64(me); if (se && pe < 256) lst[pe] = j * 64 + lane; bgt += __builtin_popcountll(me); }
	s_bcnt1_i32_b64 s0, vcc
	v_cmp_eq_u32_e32 vcc, v141, v34
	s_add_i32 s2, s2, s0
	s_nop 0
	v_mbcnt_lo_u32_b32 v53, vcc_lo, 0
	v_mbcnt_hi_u32_b32 v53, vcc_hi, v53
	v_add_u32_e32 v53, s2, v53
	v_cmp_gt_i32_e64 s[4:5], s21, v53
	s_and_b64 s[4:5], vcc, s[4:5]
	s_and_saveexec_b64 s[0:1], s[4:5]
	v_lshl_add_u32 v53, v53, 2, s20
	ds_write_b32 v53, v92
	s_or_b64 exec, exec, s[0:1]
	s_bcnt1_i32_b64 s0, vcc
	v_cmp_eq_u32_e32 vcc, v140, v34
	s_add_i32 s2, s2, s0
	s_nop 0
	v_mbcnt_lo_u32_b32 v53, vcc_lo, 0
	v_mbcnt_hi_u32_b32 v53, vcc_hi, v53
	v_add_u32_e32 v53, s2, v53
	v_cmp_gt_i32_e64 s[4:5], s21, v53
	s_and_b64 s[4:5], vcc, s[4:5]
	s_and_saveexec_b64 s[0:1], s[4:5]
	v_lshl_add_u32 v53, v53, 2, s20
	ds_write_b32 v53, v93
	s_or_b64 exec, exec, s[0:1]
	s_bcnt1_i32_b64 s0, vcc
	v_cmp_eq_u32_e32 vcc, v139, v34
	s_add_i32 s2, s2, s0
	s_nop 0
	v_mbcnt_lo_u32_b32 v53, vcc_lo, 0
	v_mbcnt_hi_u32_b32 v53, vcc_hi, v53
	v_add_u32_e32 v53, s2, v53
	v_cmp_gt_i32_e64 s[4:5], s21, v53
	s_and_b64 s[4:5], vcc, s[4:5]
	s_and_saveexec_b64 s[0:1], s[4:5]
	v_lshl_add_u32 v53, v53, 2, s20
	ds_write_b32 v53, v94
	s_or_b64 exec, exec, s[0:1]
	s_bcnt1_i32_b64 s0, vcc
	v_cmp_eq_u32_e32 vcc, v138, v34
	s_add_i32 s2, s2, s0
	s_nop 0
	v_mbcnt_lo_u32_b32 v53, vcc_lo, 0
	v_mbcnt_hi_u32_b32 v53, vcc_hi, v53
	v_add_u32_e32 v53, s2, v53
	v_cmp_gt_i32_e64 s[4:5], s21, v53
	s_and_b64 s[4:5], vcc, s[4:5]
	s_and_saveexec_b64 s[0:1], s[4:5]
	v_lshl_add_u32 v53, v53, 2, s20
	ds_write_b32 v53, v95
	s_or_b64 exec, exec, s[0:1]
	s_bcnt1_i32_b64 s0, vcc
	v_cmp_eq_u32_e32 vcc, v137, v34
	s_add_i32 s2, s2, s0
	s_nop 0
	v_mbcnt_lo_u32_b32 v53, vcc_lo, 0
	v_mbcnt_hi_u32_b32 v53, vcc_hi, v53
	v_add_u32_e32 v53, s2, v53
	v_cmp_gt_i32_e64 s[4:5], s21, v53
	s_and_b64 s[4:5], vcc, s[4:5]
	s_and_saveexec_b64 s[0:1], s[4:5]
	v_lshl_add_u32 v53, v53, 2, s20
	ds_write_b32 v53, v96
	s_or_b64 exec, exec, s[0:1]
	s_bcnt1_i32_b64 s0, vcc
	v_cmp_eq_u32_e32 vcc, v136, v34
	s_add_i32 s2, s2, s0
	s_nop 0
	v_mbcnt_lo_u32_b32 v53, vcc_lo, 0
	v_mbcnt_hi_u32_b32 v53, vcc_hi, v53
	v_add_u32_e32 v53, s2, v53
	v_cmp_gt_i32_e64 s[4:5], s21, v53
	s_and_b64 s[4:5], vcc, s[4:5]
	s_and_saveexec_b64 s[0:1], s[4:5]
	v_lshl_add_u32 v53, v53, 2, s20
	ds_write_b32 v53, v97
	s_or_b64 exec, exec, s[0:1]
	s_bcnt1_i32_b64 s0, vcc
	v_cmp_eq_u32_e32 vcc, v135, v34
	s_add_i32 s2, s2, s0
	s_nop 0
	v_mbcnt_lo_u32_b32 v53, vcc_lo, 0
	v_mbcnt_hi_u32_b32 v53, vcc_hi, v53
	v_add_u32_e32 v53, s2, v53
	v_cmp_gt_i32_e64 s[4:5], s21, v53
	s_and_b64 s[4:5], vcc, s[4:5]
	s_and_saveexec_b64 s[0:1], s[4:5]
	v_lshl_add_u32 v53, v53, 2, s20
	ds_write_b32 v53, v98
	s_or_b64 exec, exec, s[0:1]
	s_bcnt1_i32_b64 s0, vcc
	v_cmp_eq_u32_e32 vcc, v134, v34
	s_add_i32 s2, s2, s0
	s_nop 0
	v_mbcnt_lo_u32_b32 v53, vcc_lo, 0
	v_mbcnt_hi_u32_b32 v53, vcc_hi, v53
	v_add_u32_e32 v53, s2, v53
	v_cmp_gt_i32_e64 s[4:5], s21, v53
	s_and_b64 s[4:5], vcc, s[4:5]
	s_and_saveexec_b64 s[0:1], s[4:5]
	v_lshl_add_u32 v53, v53, 2, s20
	ds_write_b32 v53, v99
	s_or_b64 exec, exec, s[0:1]
	s_bcnt1_i32_b64 s0, vcc
	v_cmp_eq_u32_e32 vcc, v132, v34
	s_add_i32 s2, s2, s0
	s_nop 0
	v_mbcnt_lo_u32_b32 v53, vcc_lo, 0
	v_mbcnt_hi_u32_b32 v53, vcc_hi, v53
	v_add_u32_e32 v53, s2, v53
	v_cmp_gt_i32_e64 s[4:5], s21, v53
	s_and_b64 s[4:5], vcc, s[4:5]
	s_and_saveexec_b64 s[0:1], s[4:5]
	v_lshl_add_u32 v53, v53, 2, s20
	ds_write_b32 v53, v100
	s_or_b64 exec, exec, s[0:1]
	s_bcnt1_i32_b64 s0, vcc
	v_cmp_eq_u32_e32 vcc, v130, v34
	s_add_i32 s2, s2, s0
	s_nop 0
	v_mbcnt_lo_u32_b32 v53, vcc_lo, 0
	v_mbcnt_hi_u32_b32 v53, vcc_hi, v53
	v_add_u32_e32 v53, s2, v53
	v_cmp_gt_i32_e64 s[4:5], s21, v53
	s_and_b64 s[4:5], vcc, s[4:5]
	s_and_saveexec_b64 s[0:1], s[4:5]
	v_lshl_add_u32 v53, v53, 2, s20
	ds_write_b32 v53, v101
	s_or_b64 exec, exec, s[0:1]
	s_bcnt1_i32_b64 s0, vcc
	v_cmp_eq_u32_e32 vcc, v133, v34
	s_add_i32 s2, s2, s0
	s_nop 0
	v_mbcnt_lo_u32_b32 v53, vcc_lo, 0
	v_mbcnt_hi_u32_b32 v53, vcc_hi, v53
	v_add_u32_e32 v53, s2, v53
	v_cmp_gt_i32_e64 s[4:5], s21, v53
	s_and_b64 s[4:5], vcc, s[4:5]
	s_and_saveexec_b64 s[0:1], s[4:5]
	v_lshl_add_u32 v53, v53, 2, s20
	ds_write_b32 v53, v102
	s_or_b64 exec, exec, s[0:1]
	s_bcnt1_i32_b64 s0, vcc
	v_cmp_eq_u32_e32 vcc, v131, v34
	s_add_i32 s2, s2, s0
	s_nop 0
	v_mbcnt_lo_u32_b32 v53, vcc_lo, 0
	v_mbcnt_hi_u32_b32 v53, vcc_hi, v53
	v_add_u32_e32 v53, s2, v53
	v_cmp_gt_i32_e64 s[4:5], s21, v53
	s_and_b64 s[4:5], vcc, s[4:5]
	s_and_saveexec_b64 s[0:1], s[4:5]
	v_lshl_add_u32 v53, v53, 2, s20
	ds_write_b32 v53, v103
	s_or_b64 exec, exec, s[0:1]
	s_bcnt1_i32_b64 s0, vcc
	v_cmp_eq_u32_e32 vcc, v128, v34
	s_add_i32 s2, s2, s0
	s_nop 0
	v_mbcnt_lo_u32_b32 v53, vcc_lo, 0
	v_mbcnt_hi_u32_b32 v53, vcc_hi, v53
	v_add_u32_e32 v53, s2, v53
	v_cmp_gt_i32_e64 s[4:5], s21, v53
	s_and_b64 s[4:5], vcc, s[4:5]
	s_and_saveexec_b64 s[0:1], s[4:5]
	v_lshl_add_u32 v53, v53, 2, s20
	ds_write_b32 v53, v104
	s_or_b64 exec, exec, s[0:1]
	s_bcnt1_i32_b64 s0, vcc
	v_cmp_eq_u32_e32 vcc, v129, v34
	s_add_i32 s2, s2, s0
	s_nop 0
	v_mbcnt_lo_u32_b32 v53, vcc_lo, 0
	v_mbcnt_hi_u32_b32 v53, vcc_hi, v53
	v_add_u32_e32 v53, s2, v53
	v_cmp_gt_i32_e64 s[4:5], s21, v53
	s_and_b64 s[4:5], vcc, s[4:5]
	s_and_saveexec_b64 s[0:1], s[4:5]
	v_lshl_add_u32 v53, v53, 2, s20
	ds_write_b32 v53, v105
	s_or_b64 exec, exec, s[0:1]
	s_bcnt1_i32_b64 s0, vcc
	v_cmp_eq_u32_e32 vcc, v62, v34
	s_add_i32 s2, s2, s0
	s_nop 0
	v_mbcnt_lo_u32_b32 v53, vcc_lo, 0
	v_mbcnt_hi_u32_b32 v53, vcc_hi, v53
	v_add_u32_e32 v53, s2, v53
	v_cmp_gt_i32_e64 s[4:5], s21, v53
	s_and_b64 s[4:5], vcc, s[4:5]
	s_and_saveexec_b64 s[0:1], s[4:5]
	v_lshl_add_u32 v53, v53, 2, s20
	ds_write_b32 v53, v106
	s_or_b64 exec, exec, s[0:1]
; DI unsigned mbcnt64(unsigned long long m) { return __builtin_amdgcn_mbcnt_hi((unsigned)(m >> 32), __builtin_amdgcn_mbcnt_lo((unsigned)m, 0u)); }
; template <int NV>
; DI void topk_row(const float* row, int s, LAS int* lst, int lane) {
;     ...
;     for (int j = 0; j < NV; ++j) { const bool sg = key[j] > T; const unsigned long long mg = __ballot(sg); if (sg) lst[bgt + (int)mbcnt64(mg)] = j * 64 + lane; bgt += __builtin_popcountll(mg); }
; #pragma unroll
;     for (int j = 0; j < NV; ++j) { const bool se = key[j] == T; const unsigned long long me = __ballot(se); const int pe = bgt + (int)mbcnt64(me); if (se && pe < 256) lst[pe] = j * 64 + lane; bgt += __builtin_popcountll(me); }
	s_bcnt1_i32_b64 s0, vcc
	v_cmp_eq_u32_e32 vcc, v58, v34
	s_add_i32 s2, s2, s0
	s_nop 0
	v_mbcnt_lo_u32_b32 v53, vcc_lo, 0
	v_mbcnt_hi_u32_b32 v53, vcc_hi, v53
	v_add_u32_e32 v53, s2, v53
	v_cmp_gt_i32_e64 s[4:5], s21, v53
	s_and_b64 s[4:5], vcc, s[4:5]
	s_and_saveexec_b64 s[0:1], s[4:5]
	v_lshl_add_u32 v53, v53, 2, s20
	ds_write_b32 v53, v107
	s_or_b64 exec, exec, s[0:1]
	s_bcnt1_i32_b64 s0, vcc
	v_cmp_eq_u32_e32 vcc, v56, v34
	s_add_i32 s2, s2, s0
	s_nop 0
	v_mbcnt_lo_u32_b32 v53, vcc_lo, 0
	v_mbcnt_hi_u32_b32 v53, vcc_hi, v53
	v_add_u32_e32 v53, s2, v53
	v_cmp_gt_i32_e64 s[4:5], s21, v53
	s_and_b64 s[4:5], vcc, s[4:5]
	s_and_saveexec_b64 s[0:1], s[4:5]
	v_lshl_add_u32 v53, v53, 2, s20
	ds_write_b32 v53, v108
	s_or_b64 exec, exec, s[0:1]
	s_bcnt1_i32_b64 s0, vcc
	v_cmp_eq_u32_e32 vcc, v52, v34
	s_add_i32 s2, s2, s0
	s_nop 0
	v_mbcnt_lo_u32_b32 v52, vcc_lo, 0
	v_mbcnt_hi_u32_b32 v52, vcc_hi, v52
	v_add_u32_e32 v52, s2, v52
	v_cmp_gt_i32_e64 s[4:5], s21, v52
	s_and_b64 s[4:5], vcc, s[4:5]
	s_and_saveexec_b64 s[0:1], s[4:5]
	v_lshl_add_u32 v52, v52, 2, s20
	ds_write_b32 v52, v109
	s_or_b64 exec, exec, s[0:1]
	s_bcnt1_i32_b64 s0, vcc
	v_cmp_eq_u32_e32 vcc, v50, v34
	s_add_i32 s2, s2, s0
	s_nop 0
	v_mbcnt_lo_u32_b32 v50, vcc_lo, 0
	v_mbcnt_hi_u32_b32 v50, vcc_hi, v50
	v_add_u32_e32 v50, s2, v50
	v_cmp_gt_i32_e64 s[4:5], s21, v50
	s_and_b64 s[4:5], vcc, s[4:5]
	s_and_saveexec_b64 s[0:1], s[4:5]
	v_lshl_add_u32 v50, v50, 2, s20
	ds_write_b32 v50, v110
	s_or_b64 exec, exec, s[0:1]
	s_bcnt1_i32_b64 s0, vcc
	v_cmp_eq_u32_e32 vcc, v49, v34
	s_add_i32 s2, s2, s0
	s_nop 0
	v_mbcnt_lo_u32_b32 v49, vcc_lo, 0
	v_mbcnt_hi_u32_b32 v49, vcc_hi, v49
	v_add_u32_e32 v49, s2, v49
	v_cmp_gt_i32_e64 s[4:5], s21, v49
	s_and_b64 s[4:5], vcc, s[4:5]
	s_and_saveexec_b64 s[0:1], s[4:5]
	v_lshl_add_u32 v49, v49, 2, s20
	ds_write_b32 v49, v111
	s_or_b64 exec, exec, s[0:1]
	s_bcnt1_i32_b64 s0, vcc
	v_cmp_eq_u32_e32 vcc, v48, v34
	s_add_i32 s2, s2, s0
	s_nop 0
	v_mbcnt_lo_u32_b32 v48, vcc_lo, 0
	v_mbcnt_hi_u32_b32 v48, vcc_hi, v48
	v_add_u32_e32 v48, s2, v48
	v_cmp_gt_i32_e64 s[4:5], s21, v48
	s_and_b64 s[4:5], vcc, s[4:5]
	s_and_saveexec_b64 s[0:1], s[4:5]
	v_lshl_add_u32 v48, v48, 2, s20
	ds_write_b32 v48, v112
	s_or_b64 exec, exec, s[0:1]
	s_bcnt1_i32_b64 s0, vcc
	v_cmp_eq_u32_e32 vcc, v51, v34
	s_add_i32 s2, s2, s0
	s_nop 0
	v_mbcnt_lo_u32_b32 v48, vcc_lo, 0
	v_mbcnt_hi_u32_b32 v48, vcc_hi, v48
	v_add_u32_e32 v48, s2, v48
	v_cmp_gt_i32_e64 s[4:5], s21, v48
	s_and_b64 s[4:5], vcc, s[4:5]
	s_and_saveexec_b64 s[0:1], s[4:5]
	v_lshl_add_u32 v48, v48, 2, s20
	ds_write_b32 v48, v113
	s_or_b64 exec, exec, s[0:1]
	s_bcnt1_i32_b64 s0, vcc
	v_cmp_eq_u32_e32 vcc, v47, v34
	s_add_i32 s2, s2, s0
	s_nop 0
	v_mbcnt_lo_u32_b32 v47, vcc_lo, 0
	v_mbcnt_hi_u32_b32 v47, vcc_hi, v47
	v_add_u32_e32 v47, s2, v47
	v_cmp_gt_i32_e64 s[4:5], s21, v47
	s_and_b64 s[4:5], vcc, s[4:5]
	s_and_saveexec_b64 s[0:1], s[4:5]
	v_lshl_add_u32 v47, v47, 2, s20
	ds_write_b32 v47, v114
	s_or_b64 exec, exec, s[0:1]
	s_bcnt1_i32_b64 s0, vcc
	v_cmp_eq_u32_e32 vcc, v46, v34
	s_add_i32 s2, s2, s0
	s_nop 0
	v_mbcnt_lo_u32_b32 v46, vcc_lo, 0
	v_mbcnt_hi_u32_b32 v46, vcc_hi, v46
	v_add_u32_e32 v46, s2, v46
	v_cmp_gt_i32_e64 s[4:5], s21, v46
	s_and_b64 s[4:5], vcc, s[4:5]
	s_and_saveexec_b64 s[0:1], s[4:5]
	v_lshl_add_u32 v46, v46, 2, s20
	ds_write_b32 v46, v115
	s_or_b64 exec, exec, s[0:1]
	s_bcnt1_i32_b64 s0, vcc
	v_cmp_eq_u32_e32 vcc, v45, v34
	s_add_i32 s2, s2, s0
	s_nop 0
	v_mbcnt_lo_u32_b32 v45, vcc_lo, 0
	v_mbcnt_hi_u32_b32 v45, vcc_hi, v45
	v_add_u32_e32 v45, s2, v45
	v_cmp_gt_i32_e64 s[4:5], s21, v45
	s_and_b64 s[4:5], vcc, s[4:5]
	s_and_saveexec_b64 s[0:1], s[4:5]
	v_lshl_add_u32 v45, v45, 2, s20
	ds_write_b32 v45, v116
	s_or_b64 exec, exec, s[0:1]
	s_bcnt1_i32_b64 s0, vcc
	v_cmp_eq_u32_e32 vcc, v44, v34
	s_add_i32 s2, s2, s0
	s_nop 0
	v_mbcnt_lo_u32_b32 v44, vcc_lo, 0
; DI unsigned mbcnt64(unsigned long long m) { return __builtin_amdgcn_mbcnt_hi((unsigned)(m >> 32), __builtin_amdgcn_mbcnt_lo((unsigned)m, 0u)); }
; template <int NV>
; DI void topk_row(const float* row, int s, LAS int* lst, int lane) {
;     ...
;     for (int j = 0; j < NV; ++j) { const bool sg = key[j] > T; const unsigned long long mg = __ballot(sg); if (sg) lst[bgt + (int)mbcnt64(mg)] = j * 64 + lane; bgt += __builtin_popcountll(mg); }
; #pragma unroll
;     for (int j = 0; j < NV; ++j) { const bool se = key[j] == T; const unsigned long long me = __ballot(se); const int pe = bgt + (int)mbcnt64(me); if (se && pe < 256) lst[pe] = j * 64 + lane; bgt += __builtin_popcountll(me); }
	v_mbcnt_hi_u32_b32 v44, vcc_hi, v44
	v_add_u32_e32 v44, s2, v44
	v_cmp_gt_i32_e64 s[4:5], s21, v44
	s_and_b64 s[4:5], vcc, s[4:5]
	s_and_saveexec_b64 s[0:1], s[4:5]
	v_lshl_add_u32 v44, v44, 2, s20
	ds_write_b32 v44, v117
	s_or_b64 exec, exec, s[0:1]
	s_bcnt1_i32_b64 s0, vcc
	v_cmp_eq_u32_e32 vcc, v43, v34
	s_add_i32 s2, s2, s0
	s_nop 0
	v_mbcnt_lo_u32_b32 v43, vcc_lo, 0
	v_mbcnt_hi_u32_b32 v43, vcc_hi, v43
	v_add_u32_e32 v43, s2, v43
	v_cmp_gt_i32_e64 s[4:5], s21, v43
	s_and_b64 s[4:5], vcc, s[4:5]
	s_and_saveexec_b64 s[0:1], s[4:5]
	v_lshl_add_u32 v43, v43, 2, s20
	ds_write_b32 v43, v118
	s_or_b64 exec, exec, s[0:1]
	s_bcnt1_i32_b64 s0, vcc
	v_cmp_eq_u32_e32 vcc, v42, v34
	s_add_i32 s2, s2, s0
	s_nop 0
	v_mbcnt_lo_u32_b32 v42, vcc_lo, 0
	v_mbcnt_hi_u32_b32 v42, vcc_hi, v42
	v_add_u32_e32 v42, s2, v42
	v_cmp_gt_i32_e64 s[4:5], s21, v42
	s_and_b64 s[4:5], vcc, s[4:5]
	s_and_saveexec_b64 s[0:1], s[4:5]
	v_lshl_add_u32 v42, v42, 2, s20
	ds_write_b32 v42, v119
	s_or_b64 exec, exec, s[0:1]
	s_bcnt1_i32_b64 s0, vcc
	v_cmp_eq_u32_e32 vcc, v41, v34
	s_add_i32 s2, s2, s0
	s_nop 0
	v_mbcnt_lo_u32_b32 v41, vcc_lo, 0
	v_mbcnt_hi_u32_b32 v41, vcc_hi, v41
	v_add_u32_e32 v41, s2, v41
	v_cmp_gt_i32_e64 s[4:5], s21, v41
	s_and_b64 s[4:5], vcc, s[4:5]
	s_and_saveexec_b64 s[0:1], s[4:5]
	v_lshl_add_u32 v41, v41, 2, s20
	ds_write_b32 v41, v120
	s_or_b64 exec, exec, s[0:1]
	s_bcnt1_i32_b64 s0, vcc
	v_cmp_eq_u32_e32 vcc, v40, v34
	s_add_i32 s2, s2, s0
	s_nop 0
	v_mbcnt_lo_u32_b32 v40, vcc_lo, 0
	v_mbcnt_hi_u32_b32 v40, vcc_hi, v40
	v_add_u32_e32 v40, s2, v40
	v_cmp_gt_i32_e64 s[4:5], s21, v40
	s_and_b64 s[4:5], vcc, s[4:5]
	s_and_saveexec_b64 s[0:1], s[4:5]
	v_lshl_add_u32 v40, v40, 2, s20
	ds_write_b32 v40, v121
	s_or_b64 exec, exec, s[0:1]
	s_bcnt1_i32_b64 s0, vcc
	v_cmp_eq_u32_e32 vcc, v39, v34
	s_add_i32 s2, s2, s0
	s_nop 0
	v_mbcnt_lo_u32_b32 v39, vcc_lo, 0
	v_mbcnt_hi_u32_b32 v39, vcc_hi, v39
	v_add_u32_e32 v39, s2, v39
	v_cmp_gt_i32_e64 s[4:5], s21, v39
	s_and_b64 s[4:5], vcc, s[4:5]
	s_and_saveexec_b64 s[0:1], s[4:5]
	v_lshl_add_u32 v39, v39, 2, s20
	ds_write_b32 v39, v122
	s_or_b64 exec, exec, s[0:1]
	s_bcnt1_i32_b64 s0, vcc
	v_cmp_eq_u32_e32 vcc, v38, v34
	s_add_i32 s2, s2, s0
	s_nop 0
	v_mbcnt_lo_u32_b32 v38, vcc_lo, 0
	v_mbcnt_hi_u32_b32 v38, vcc_hi, v38
	v_add_u32_e32 v38, s2, v38
	v_cmp_gt_i32_e64 s[4:5], s21, v38
	s_and_b64 s[4:5], vcc, s[4:5]
	s_and_saveexec_b64 s[0:1], s[4:5]
	v_lshl_add_u32 v38, v38, 2, s20
	ds_write_b32 v38, v123
	s_or_b64 exec, exec, s[0:1]
	s_bcnt1_i32_b64 s0, vcc
	v_cmp_eq_u32_e32 vcc, v37, v34
	s_add_i32 s2, s2, s0
	s_nop 0
	v_mbcnt_lo_u32_b32 v37, vcc_lo, 0
	v_mbcnt_hi_u32_b32 v37, vcc_hi, v37
	v_add_u32_e32 v37, s2, v37
	v_cmp_gt_i32_e64 s[4:5], s21, v37
	s_and_b64 s[4:5], vcc, s[4:5]
	s_and_saveexec_b64 s[0:1], s[4:5]
	v_lshl_add_u32 v37, v37, 2, s20
	ds_write_b32 v37, v124
	s_or_b64 exec, exec, s[0:1]
	s_bcnt1_i32_b64 s0, vcc
	v_cmp_eq_u32_e32 vcc, v36, v34
	s_add_i32 s2, s2, s0
	s_nop 0
	v_mbcnt_lo_u32_b32 v36, vcc_lo, 0
	v_mbcnt_hi_u32_b32 v36, vcc_hi, v36
	v_add_u32_e32 v36, s2, v36
	v_cmp_gt_i32_e64 s[4:5], s21, v36
	s_and_b64 s[4:5], vcc, s[4:5]
	s_and_saveexec_b64 s[0:1], s[4:5]
	v_lshl_add_u32 v36, v36, 2, s20
	ds_write_b32 v36, v125
	s_or_b64 exec, exec, s[0:1]
	s_bcnt1_i32_b64 s0, vcc
	v_cmp_eq_u32_e32 vcc, v35, v34
	s_add_i32 s2, s2, s0
	s_nop 0
	v_mbcnt_lo_u32_b32 v35, vcc_lo, 0
	v_mbcnt_hi_u32_b32 v35, vcc_hi, v35
	v_add_u32_e32 v35, s2, v35
	v_cmp_gt_i32_e64 s[4:5], s21, v35
	s_and_b64 s[4:5], vcc, s[4:5]
	s_and_saveexec_b64 s[0:1], s[4:5]
	v_lshl_add_u32 v35, v35, 2, s20
	ds_write_b32 v35, v126
	s_or_b64 exec, exec, s[0:1]
	s_bcnt1_i32_b64 s0, vcc
	v_cmp_eq_u32_e32 vcc, v0, v34
	s_add_i32 s2, s2, s0
	v_mov_b32_e32 v34, v127
	v_mbcnt_lo_u32_b32 v0, vcc_lo, 0
	v_mbcnt_hi_u32_b32 v0, vcc_hi, v0
	v_add_u32_e32 v0, s2, v0
	v_cmp_gt_i32_e64 s[4:5], s21, v0
	s_and_b64 s[0:1], vcc, s[4:5]

; DI unsigned mbcnt64(unsigned long long m) { return __builtin_amdgcn_mbcnt_hi((unsigned)(m >> 32), __builtin_amdgcn_mbcnt_lo((unsigned)m, 0u)); }
; template <int NV>
; DI void topk_row(const float* row, int s, LAS int* lst, int lane) {
;     ...
;     int bgt = 0;
; #pragma unroll
;     for (int j = 0; j < NV; ++j) { const bool sg = key[j] > T; const unsigned long long mg = __ballot(sg); if (sg) lst[bgt + (int)mbcnt64(mg)] = j * 64 + lane; bgt += __builtin_popcountll(mg); }
; #pragma unroll
;     for (int j = 0; j < NV; ++j) { const bool se = key[j] == T; const unsigned long long me = __ballot(se); const int pe = bgt + (int)mbcnt64(me); if (se && pe < 256) lst[pe] = j * 64 + lane; bgt += __builtin_popcountll(me); }
.LBB0_3000:
	s_or_b64 exec, exec, s[0:1]
	s_bcnt1_i32_b64 s0, vcc
	v_cmp_eq_u32_e32 vcc, v189, v34
	s_add_i32 s2, s2, s0
	s_cmpk_eq_i32 s2, 0x100
	s_cbranch_scc1 .Lp12_skip2_2
	s_nop 0
	v_mbcnt_lo_u32_b32 v53, vcc_lo, 0
	v_mbcnt_hi_u32_b32 v53, vcc_hi, v53
	v_add_u32_e32 v53, s2, v53
	v_cmp_gt_i32_e64 s[4:5], s21, v53
	s_and_b64 s[4:5], vcc, s[4:5]
	s_and_saveexec_b64 s[0:1], s[4:5]
	v_lshl_add_u32 v53, v53, 2, s20
	ds_write_b32 v53, v2
	s_or_b64 exec, exec, s[0:1]
	s_bcnt1_i32_b64 s0, vcc
	v_cmp_eq_u32_e32 vcc, v188, v34
	s_add_i32 s2, s2, s0
	s_nop 0
	v_mbcnt_lo_u32_b32 v53, vcc_lo, 0
	v_mbcnt_hi_u32_b32 v53, vcc_hi, v53
	v_add_u32_e32 v53, s2, v53
	v_cmp_gt_i32_e64 s[4:5], s21, v53
	s_and_b64 s[4:5], vcc, s[4:5]
	s_and_saveexec_b64 s[0:1], s[4:5]
	v_lshl_add_u32 v53, v53, 2, s20
	ds_write_b32 v53, v4
	s_or_b64 exec, exec, s[0:1]
	s_bcnt1_i32_b64 s0, vcc
	v_cmp_eq_u32_e32 vcc, v187, v34
	s_add_i32 s2, s2, s0
	s_nop 0
	v_mbcnt_lo_u32_b32 v53, vcc_lo, 0
	v_mbcnt_hi_u32_b32 v53, vcc_hi, v53
	v_add_u32_e32 v53, s2, v53
	v_cmp_gt_i32_e64 s[4:5], s21, v53
	s_and_b64 s[4:5], vcc, s[4:5]
	s_and_saveexec_b64 s[0:1], s[4:5]
	v_lshl_add_u32 v53, v53, 2, s20
	ds_write_b32 v53, v6
	s_or_b64 exec, exec, s[0:1]
	s_bcnt1_i32_b64 s0, vcc
	v_cmp_eq_u32_e32 vcc, v186, v34
	s_add_i32 s2, s2, s0
	s_nop 0
	v_mbcnt_lo_u32_b32 v53, vcc_lo, 0
	v_mbcnt_hi_u32_b32 v53, vcc_hi, v53
	v_add_u32_e32 v53, s2, v53
	v_cmp_gt_i32_e64 s[4:5], s21, v53
	s_and_b64 s[4:5], vcc, s[4:5]
	s_and_saveexec_b64 s[0:1], s[4:5]
	v_lshl_add_u32 v53, v53, 2, s20
	ds_write_b32 v53, v8
	s_or_b64 exec, exec, s[0:1]
	s_bcnt1_i32_b64 s0, vcc
	v_cmp_eq_u32_e32 vcc, v185, v34
	s_add_i32 s2, s2, s0
	s_nop 0
	v_mbcnt_lo_u32_b32 v53, vcc_lo, 0
	v_mbcnt_hi_u32_b32 v53, vcc_hi, v53
	v_add_u32_e32 v53, s2, v53
	v_cmp_gt_i32_e64 s[4:5], s21, v53
	s_and_b64 s[4:5], vcc, s[4:5]
	s_and_saveexec_b64 s[0:1], s[4:5]
	v_lshl_add_u32 v53, v53, 2, s20
	ds_write_b32 v53, v10
	s_or_b64 exec, exec, s[0:1]
	s_bcnt1_i32_b64 s0, vcc
	v_cmp_eq_u32_e32 vcc, v184, v34
	s_add_i32 s2, s2, s0
	s_nop 0
	v_mbcnt_lo_u32_b32 v53, vcc_lo, 0
	v_mbcnt_hi_u32_b32 v53, vcc_hi, v53
	v_add_u32_e32 v53, s2, v53
	v_cmp_gt_i32_e64 s[4:5], s21, v53
	s_and_b64 s[4:5], vcc, s[4:5]
	s_and_saveexec_b64 s[0:1], s[4:5]
	v_lshl_add_u32 v53, v53, 2, s20
	ds_write_b32 v53, v12
	s_or_b64 exec, exec, s[0:1]
	s_bcnt1_i32_b64 s0, vcc
	v_cmp_eq_u32_e32 vcc, v183, v34
	s_add_i32 s2, s2, s0
	s_nop 0
	v_mbcnt_lo_u32_b32 v53, vcc_lo, 0
	v_mbcnt_hi_u32_b32 v53, vcc_hi, v53
	v_add_u32_e32 v53, s2, v53
	v_cmp_gt_i32_e64 s[4:5], s21, v53
	s_and_b64 s[4:5], vcc, s[4:5]
	s_and_saveexec_b64 s[0:1], s[4:5]
	v_lshl_add_u32 v53, v53, 2, s20
	ds_write_b32 v53, v14
	s_or_b64 exec, exec, s[0:1]
	s_bcnt1_i32_b64 s0, vcc
	v_cmp_eq_u32_e32 vcc, v182, v34
	s_add_i32 s2, s2, s0
	s_nop 0
	v_mbcnt_lo_u32_b32 v53, vcc_lo, 0
	v_mbcnt_hi_u32_b32 v53, vcc_hi, v53
	v_add_u32_e32 v53, s2, v53
	v_cmp_gt_i32_e64 s[4:5], s21, v53
	s_and_b64 s[4:5], vcc, s[4:5]
	s_and_saveexec_b64 s[0:1], s[4:5]
	v_lshl_add_u32 v53, v53, 2, s20
	ds_write_b32 v53, v16
	s_or_b64 exec, exec, s[0:1]
	s_bcnt1_i32_b64 s0, vcc
	v_cmp_eq_u32_e32 vcc, v179, v34
	s_add_i32 s2, s2, s0
	s_nop 0
	v_mbcnt_lo_u32_b32 v53, vcc_lo, 0
	v_mbcnt_hi_u32_b32 v53, vcc_hi, v53
	v_add_u32_e32 v53, s2, v53
	v_cmp_gt_i32_e64 s[4:5], s21, v53
	s_and_b64 s[4:5], vcc, s[4:5]
	s_and_saveexec_b64 s[0:1], s[4:5]
	v_lshl_add_u32 v53, v53, 2, s20
	ds_write_b32 v53, v18
	s_or_b64 exec, exec, s[0:1]
	s_bcnt1_i32_b64 s0, vcc
	v_cmp_eq_u32_e32 vcc, v175, v34
	s_add_i32 s2, s2, s0
	s_nop 0
	v_mbcnt_lo_u32_b32 v53, vcc_lo, 0
	v_mbcnt_hi_u32_b32 v53, vcc_hi, v53
	v_add_u32_e32 v53, s2, v53
	v_cmp_gt_i32_e64 s[4:5], s21, v53
	s_and_b64 s[4:5], vcc, s[4:5]
	s_and_saveexec_b64 s[0:1], s[4:5]
	v_lshl_add_u32 v53, v53, 2, s20
	ds_write_b32 v53, v20
	s_or_b64 exec, exec, s[0:1]
	s_bcnt1_i32_b64 s0, vcc
	v_cmp_eq_u32_e32 vcc, v172, v34
	s_add_i32 s2, s2, s0
	s_nop 0
	v_mbcnt_lo_u32_b32 v53, vcc_lo, 0
	v_mbcnt_hi_u32_b32 v53, vcc_hi, v53
	v_add_u32_e32 v53, s2, v53
	v_cmp_gt_i32_e64 s[4:5], s21, v53
	s_and_b64 s[4:5], vcc, s[4:5]
	s_and_saveexec_b64 s[0:1], s[4:5]
	v_lshl_add_u32 v53, v53, 2, s20
	ds_write_b32 v53, v22
	s_or_b64 exec, exec, s[0:1]
	s_bcnt1_i32_b64 s0, vcc
	v_cmp_eq_u32_e32 vcc, v170, v34
	s_add_i32 s2, s2, s0
	s_nop 0
	v_mbcnt_lo_u32_b32 v53, vcc_lo, 0
	v_mbcnt_hi_u32_b32 v53, vcc_hi, v53
	v_add_u32_e32 v53, s2, v53
	v_cmp_gt_i32_e64 s[4:5], s21, v53
	s_and_b64 s[4:5], vcc, s[4:5]
	s_and_saveexec_b64 s[0:1], s[4:5]
	v_lshl_add_u32 v53, v53, 2, s20
	ds_write_b32 v53, v24
	s_or_b64 exec, exec, s[0:1]
	s_bcnt1_i32_b64 s0, vcc
	v_cmp_eq_u32_e32 vcc, v167, v34
	s_add_i32 s2, s2, s0
	s_nop 0
	v_mbcnt_lo_u32_b32 v53, vcc_lo, 0
	v_mbcnt_hi_u32_b32 v53, vcc_hi, v53
	v_add_u32_e32 v53, s2, v53
	v_cmp_gt_i32_e64 s[4:5], s21, v53
	s_and_b64 s[4:5], vcc, s[4:5]
	s_and_saveexec_b64 s[0:1], s[4:5]
	v_lshl_add_u32 v53, v53, 2, s20
	ds_write_b32 v53, v26
	s_or_b64 exec, exec, s[0:1]
	s_bcnt1_i32_b64 s0, vcc
	v_cmp_eq_u32_e32 vcc, v169, v34
	s_add_i32 s2, s2, s0
	s_nop 0
	v_mbcnt_lo_u32_b32 v53, vcc_lo, 0
	v_mbcnt_hi_u32_b32 v53, vcc_hi, v53
	v_add_u32_e32 v53, s2, v53
	v_cmp_gt_i32_e64 s[4:5], s21, v53
	s_and_b64 s[4:5], vcc, s[4:5]
	s_and_saveexec_b64 s[0:1], s[4:5]
	v_lshl_add_u32 v53, v53, 2, s20
	ds_write_b32 v53, v28
	s_or_b64 exec, exec, s[0:1]
	s_bcnt1_i32_b64 s0, vcc
	v_cmp_eq_u32_e32 vcc, v174, v34
	s_add_i32 s2, s2, s0
	s_nop 0
	v_mbcnt_lo_u32_b32 v53, vcc_lo, 0
	v_mbcnt_hi_u32_b32 v53, vcc_hi, v53
	v_add_u32_e32 v53, s2, v53
	v_cmp_gt_i32_e64 s[4:5], s21, v53
	s_and_b64 s[4:5], vcc, s[4:5]
	s_and_saveexec_b64 s[0:1], s[4:5]
; DI unsigned mbcnt64(unsigned long long m) { return __builtin_amdgcn_mbcnt_hi((unsigned)(m >> 32), __builtin_amdgcn_mbcnt_lo((unsigned)m, 0u)); }
; template <int NV>
; DI void topk_row(const float* row, int s, LAS int* lst, int lane) {
;     ...
;     for (int j = 0; j < NV; ++j) { const bool sg = key[j] > T; const unsigned long long mg = __ballot(sg); if (sg) lst[bgt + (int)mbcnt64(mg)] = j * 64 + lane; bgt += __builtin_popcountll(mg); }
; #pragma unroll
;     for (int j = 0; j < NV; ++j) { const bool se = key[j] == T; const unsigned long long me = __ballot(se); const int pe = bgt + (int)mbcnt64(me); if (se && pe < 256) lst[pe] = j * 64 + lane; bgt += __builtin_popcountll(me); }
	v_lshl_add_u32 v53, v53, 2, s20
	ds_write_b32 v53, v30
	s_or_b64 exec, exec, s[0:1]
	s_bcnt1_i32_b64 s0, vcc
	v_cmp_eq_u32_e32 vcc, v178, v34
	s_add_i32 s2, s2, s0
	s_nop 0
	v_mbcnt_lo_u32_b32 v53, vcc_lo, 0
	v_mbcnt_hi_u32_b32 v53, vcc_hi, v53
	v_add_u32_e32 v53, s2, v53
	v_cmp_gt_i32_e64 s[4:5], s21, v53
	s_and_b64 s[4:5], vcc, s[4:5]
	s_and_saveexec_b64 s[0:1], s[4:5]
	v_lshl_add_u32 v53, v53, 2, s20
	ds_write_b32 v53, v32
	s_or_b64 exec, exec, s[0:1]
	s_bcnt1_i32_b64 s0, vcc
	v_cmp_eq_u32_e32 vcc, v181, v34
	s_add_i32 s2, s2, s0
	s_nop 0
	v_mbcnt_lo_u32_b32 v53, vcc_lo, 0
	v_mbcnt_hi_u32_b32 v53, vcc_hi, v53
	v_add_u32_e32 v53, s2, v53
	v_cmp_gt_i32_e64 s[4:5], s21, v53
	s_and_b64 s[4:5], vcc, s[4:5]
	s_and_saveexec_b64 s[0:1], s[4:5]
	v_lshl_add_u32 v53, v53, 2, s20
	ds_write_b32 v53, v3
	s_or_b64 exec, exec, s[0:1]
	s_bcnt1_i32_b64 s0, vcc
	v_cmp_eq_u32_e32 vcc, v180, v34
	s_add_i32 s2, s2, s0
	s_nop 0
	v_mbcnt_lo_u32_b32 v53, vcc_lo, 0
	v_mbcnt_hi_u32_b32 v53, vcc_hi, v53
	v_add_u32_e32 v53, s2, v53
	v_cmp_gt_i32_e64 s[4:5], s21, v53
	s_and_b64 s[4:5], vcc, s[4:5]
	s_and_saveexec_b64 s[0:1], s[4:5]
	v_lshl_add_u32 v53, v53, 2, s20
	ds_write_b32 v53, v5
	s_or_b64 exec, exec, s[0:1]
	s_bcnt1_i32_b64 s0, vcc
	v_cmp_eq_u32_e32 vcc, v177, v34
	s_add_i32 s2, s2, s0
	s_nop 0
	v_mbcnt_lo_u32_b32 v53, vcc_lo, 0
	v_mbcnt_hi_u32_b32 v53, vcc_hi, v53
	v_add_u32_e32 v53, s2, v53
	v_cmp_gt_i32_e64 s[4:5], s21, v53
	s_and_b64 s[4:5], vcc, s[4:5]
	s_and_saveexec_b64 s[0:1], s[4:5]
	v_lshl_add_u32 v53, v53, 2, s20
	ds_write_b32 v53, v7
	s_or_b64 exec, exec, s[0:1]
	s_bcnt1_i32_b64 s0, vcc
	v_cmp_eq_u32_e32 vcc, v176, v34
	s_add_i32 s2, s2, s0
	s_nop 0
	v_mbcnt_lo_u32_b32 v53, vcc_lo, 0
	v_mbcnt_hi_u32_b32 v53, vcc_hi, v53
	v_add_u32_e32 v53, s2, v53
	v_cmp_gt_i32_e64 s[4:5], s21, v53
	s_and_b64 s[4:5], vcc, s[4:5]
	s_and_saveexec_b64 s[0:1], s[4:5]
	v_lshl_add_u32 v53, v53, 2, s20
	ds_write_b32 v53, v9
	s_or_b64 exec, exec, s[0:1]
	s_bcnt1_i32_b64 s0, vcc
	v_cmp_eq_u32_e32 vcc, v173, v34
	s_add_i32 s2, s2, s0
	s_nop 0
	v_mbcnt_lo_u32_b32 v53, vcc_lo, 0
	v_mbcnt_hi_u32_b32 v53, vcc_hi, v53
	v_add_u32_e32 v53, s2, v53
	v_cmp_gt_i32_e64 s[4:5], s21, v53
	s_and_b64 s[4:5], vcc, s[4:5]
	s_and_saveexec_b64 s[0:1], s[4:5]
	v_lshl_add_u32 v53, v53, 2, s20
	ds_write_b32 v53, v11
	s_or_b64 exec, exec, s[0:1]
	s_bcnt1_i32_b64 s0, vcc
	v_cmp_eq_u32_e32 vcc, v171, v34
	s_add_i32 s2, s2, s0
	s_nop 0
	v_mbcnt_lo_u32_b32 v53, vcc_lo, 0
	v_mbcnt_hi_u32_b32 v53, vcc_hi, v53
	v_add_u32_e32 v53, s2, v53
	v_cmp_gt_i32_e64 s[4:5], s21, v53
	s_and_b64 s[4:5], vcc, s[4:5]
	s_and_saveexec_b64 s[0:1], s[4:5]
	v_lshl_add_u32 v53, v53, 2, s20
	ds_write_b32 v53, v13
	s_or_b64 exec, exec, s[0:1]
	s_bcnt1_i32_b64 s0, vcc
	v_cmp_eq_u32_e32 vcc, v168, v34
	s_add_i32 s2, s2, s0
	s_nop 0
	v_mbcnt_lo_u32_b32 v53, vcc_lo, 0
	v_mbcnt_hi_u32_b32 v53, vcc_hi, v53
	v_add_u32_e32 v53, s2, v53
	v_cmp_gt_i32_e64 s[4:5], s21, v53
	s_and_b64 s[4:5], vcc, s[4:5]
	s_and_saveexec_b64 s[0:1], s[4:5]
	v_lshl_add_u32 v53, v53, 2, s20
	ds_write_b32 v53, v15
	s_or_b64 exec, exec, s[0:1]
	s_bcnt1_i32_b64 s0, vcc
	v_cmp_eq_u32_e32 vcc, v166, v34
	s_add_i32 s2, s2, s0
	s_nop 0
	v_mbcnt_lo_u32_b32 v53, vcc_lo, 0
	v_mbcnt_hi_u32_b32 v53, vcc_hi, v53
	v_add_u32_e32 v53, s2, v53
	v_cmp_gt_i32_e64 s[4:5], s21, v53
	s_and_b64 s[4:5], vcc, s[4:5]
	s_and_saveexec_b64 s[0:1], s[4:5]
	v_lshl_add_u32 v53, v53, 2, s20
	ds_write_b32 v53, v17
	s_or_b64 exec, exec, s[0:1]
	s_bcnt1_i32_b64 s0, vcc
	v_cmp_eq_u32_e32 vcc, v165, v34
	s_add_i32 s2, s2, s0
	s_nop 0
	v_mbcnt_lo_u32_b32 v53, vcc_lo, 0
	v_mbcnt_hi_u32_b32 v53, vcc_hi, v53
	v_add_u32_e32 v53, s2, v53
	v_cmp_gt_i32_e64 s[4:5], s21, v53
	s_and_b64 s[4:5], vcc, s[4:5]
	s_and_saveexec_b64 s[0:1], s[4:5]
	v_lshl_add_u32 v53, v53, 2, s20
	ds_write_b32 v53, v19
	s_or_b64 exec, exec, s[0:1]
	s_bcnt1_i32_b64 s0, vcc
	v_cmp_eq_u32_e32 vcc, v164, v34
	s_add_i32 s2, s2, s0
	s_nop 0
	v_mbcnt_lo_u32_b32 v53, vcc_lo, 0
	v_mbcnt_hi_u32_b32 v53, vcc_hi, v53
	v_add_u32_e32 v53, s2, v53
	v_cmp_gt_i32_e64 s[4:5], s21, v53
	s_and_b64 s[4:5], vcc, s[4:5]
	s_and_saveexec_b64 s[0:1], s[4:5]
	v_lshl_add_u32 v53, v53, 2, s20
	ds_write_b32 v53, v21
	s_or_b64 exec, exec, s[0:1]
	s_bcnt1_i32_b64 s0, vcc
	v_cmp_eq_u32_e32 vcc, v163, v34
	s_add_i32 s2, s2, s0
	s_nop 0
	v_mbcnt_lo_u32_b32 v53, vcc_lo, 0
	v_mbcnt_hi_u32_b32 v53, vcc_hi, v53
	v_add_u32_e32 v53, s2, v53
	v_cmp_gt_i32_e64 s[4:5], s21, v53
	s_and_b64 s[4:5], vcc, s[4:5]
	s_and_saveexec_b64 s[0:1], s[4:5]
	v_lshl_add_u32 v53, v53, 2, s20
	ds_write_b32 v53, v23
	s_or_b64 exec, exec, s[0:1]
	s_bcnt1_i32_b64 s0, vcc
	v_cmp_eq_u32_e32 vcc, v162, v34
	s_add_i32 s2, s2, s0
	s_nop 0
	v_mbcnt_lo_u32_b32 v53, vcc_lo, 0
	v_mbcnt_hi_u32_b32 v53, vcc_hi, v53
	v_add_u32_e32 v53, s2, v53
	v_cmp_gt_i32_e64 s[4:5], s21, v53
	s_and_b64 s[4:5], vcc, s[4:5]
	s_and_saveexec_b64 s[0:1], s[4:5]
	v_lshl_add_u32 v53, v53, 2, s20
	ds_write_b32 v53, v25
	s_or_b64 exec, exec, s[0:1]
	s_bcnt1_i32_b64 s0, vcc
	v_cmp_eq_u32_e32 vcc, v141, v34
	s_add_i32 s2, s2, s0
	s_nop 0
	v_mbcnt_lo_u32_b32 v53, vcc_lo, 0
	v_mbcnt_hi_u32_b32 v53, vcc_hi, v53
	v_add_u32_e32 v53, s2, v53
	v_cmp_gt_i32_e64 s[4:5], s21, v53
	s_and_b64 s[4:5], vcc, s[4:5]
	s_and_saveexec_b64 s[0:1], s[4:5]
	v_lshl_add_u32 v53, v53, 2, s20
	ds_write_b32 v53, v27
	s_or_b64 exec, exec, s[0:1]
	s_bcnt1_i32_b64 s0, vcc
	v_cmp_eq_u32_e32 vcc, v140, v34
	s_add_i32 s2, s2, s0
	s_nop 0
	v_mbcnt_lo_u32_b32 v53, vcc_lo, 0
	v_mbcnt_hi_u32_b32 v53, vcc_hi, v53
	v_add_u32_e32 v53, s2, v53
	v_cmp_gt_i32_e64 s[4:5], s21, v53
	s_and_b64 s[4:5], vcc, s[4:5]
	s_and_saveexec_b64 s[0:1], s[4:5]
	v_lshl_add_u32 v53, v53, 2, s20
; DI unsigned mbcnt64(unsigned long long m) { return __builtin_amdgcn_mbcnt_hi((unsigned)(m >> 32), __builtin_amdgcn_mbcnt_lo((unsigned)m, 0u)); }
; template <int NV>
; DI void topk_row(const float* row, int s, LAS int* lst, int lane) {
;     ...
;     for (int j = 0; j < NV; ++j) { const bool sg = key[j] > T; const unsigned long long mg = __ballot(sg); if (sg) lst[bgt + (int)mbcnt64(mg)] = j * 64 + lane; bgt += __builtin_popcountll(mg); }
; #pragma unroll
;     for (int j = 0; j < NV; ++j) { const bool se = key[j] == T; const unsigned long long me = __ballot(se); const int pe = bgt + (int)mbcnt64(me); if (se && pe < 256) lst[pe] = j * 64 + lane; bgt += __builtin_popcountll(me); }
	ds_write_b32 v53, v29
	s_or_b64 exec, exec, s[0:1]
	s_bcnt1_i32_b64 s0, vcc
	v_cmp_eq_u32_e32 vcc, v139, v34
	s_add_i32 s2, s2, s0
	s_nop 0
	v_mbcnt_lo_u32_b32 v53, vcc_lo, 0
	v_mbcnt_hi_u32_b32 v53, vcc_hi, v53
	v_add_u32_e32 v53, s2, v53
	v_cmp_gt_i32_e64 s[4:5], s21, v53
	s_and_b64 s[4:5], vcc, s[4:5]
	s_and_saveexec_b64 s[0:1], s[4:5]
	v_lshl_add_u32 v53, v53, 2, s20
	ds_write_b32 v53, v31
	s_or_b64 exec, exec, s[0:1]
	s_bcnt1_i32_b64 s0, vcc
	v_cmp_eq_u32_e32 vcc, v138, v34
	s_add_i32 s2, s2, s0
	s_nop 0
	v_mbcnt_lo_u32_b32 v53, vcc_lo, 0
	v_mbcnt_hi_u32_b32 v53, vcc_hi, v53
	v_add_u32_e32 v53, s2, v53
	v_cmp_gt_i32_e64 s[4:5], s21, v53
	s_and_b64 s[4:5], vcc, s[4:5]
	s_and_saveexec_b64 s[0:1], s[4:5]
	v_lshl_add_u32 v53, v53, 2, s20
	ds_write_b32 v53, v33
	s_or_b64 exec, exec, s[0:1]
	s_bcnt1_i32_b64 s0, vcc
	v_cmp_eq_u32_e32 vcc, v137, v34
	s_add_i32 s2, s2, s0
	s_nop 0
	v_mbcnt_lo_u32_b32 v53, vcc_lo, 0
	v_mbcnt_hi_u32_b32 v53, vcc_hi, v53
	v_add_u32_e32 v53, s2, v53
	v_cmp_gt_i32_e64 s[4:5], s21, v53
	s_and_b64 s[4:5], vcc, s[4:5]
	s_and_saveexec_b64 s[0:1], s[4:5]
	v_lshl_add_u32 v53, v53, 2, s20
	ds_write_b32 v53, v64
	s_or_b64 exec, exec, s[0:1]
	s_bcnt1_i32_b64 s0, vcc
	v_cmp_eq_u32_e32 vcc, v136, v34
	s_add_i32 s2, s2, s0
	s_nop 0
	v_mbcnt_lo_u32_b32 v53, vcc_lo, 0
	v_mbcnt_hi_u32_b32 v53, vcc_hi, v53
	v_add_u32_e32 v53, s2, v53
	v_cmp_gt_i32_e64 s[4:5], s21, v53
	s_and_b64 s[4:5], vcc, s[4:5]
	s_and_saveexec_b64 s[0:1], s[4:5]
	v_lshl_add_u32 v53, v53, 2, s20
	ds_write_b32 v53, v65
	s_or_b64 exec, exec, s[0:1]
	s_bcnt1_i32_b64 s0, vcc
	v_cmp_eq_u32_e32 vcc, v135, v34
	s_add_i32 s2, s2, s0
	s_nop 0
	v_mbcnt_lo_u32_b32 v53, vcc_lo, 0
	v_mbcnt_hi_u32_b32 v53, vcc_hi, v53
	v_add_u32_e32 v53, s2, v53
	v_cmp_gt_i32_e64 s[4:5], s21, v53
	s_and_b64 s[4:5], vcc, s[4:5]
	s_and_saveexec_b64 s[0:1], s[4:5]
	v_lshl_add_u32 v53, v53, 2, s20
	ds_write_b32 v53, v66
	s_or_b64 exec, exec, s[0:1]
	s_bcnt1_i32_b64 s0, vcc
	v_cmp_eq_u32_e32 vcc, v134, v34
	s_add_i32 s2, s2, s0
	s_nop 0
	v_mbcnt_lo_u32_b32 v53, vcc_lo, 0
	v_mbcnt_hi_u32_b32 v53, vcc_hi, v53
	v_add_u32_e32 v53, s2, v53
	v_cmp_gt_i32_e64 s[4:5], s21, v53
	s_and_b64 s[4:5], vcc, s[4:5]
	s_and_saveexec_b64 s[0:1], s[4:5]
	v_lshl_add_u32 v53, v53, 2, s20
	ds_write_b32 v53, v67
	s_or_b64 exec, exec, s[0:1]
	s_bcnt1_i32_b64 s0, vcc
	v_cmp_eq_u32_e32 vcc, v133, v34
	s_add_i32 s2, s2, s0
	s_nop 0
	v_mbcnt_lo_u32_b32 v53, vcc_lo, 0
	v_mbcnt_hi_u32_b32 v53, vcc_hi, v53
	v_add_u32_e32 v53, s2, v53
	v_cmp_gt_i32_e64 s[4:5], s21, v53
	s_and_b64 s[4:5], vcc, s[4:5]
	s_and_saveexec_b64 s[0:1], s[4:5]
	v_lshl_add_u32 v53, v53, 2, s20
	ds_write_b32 v53, v68
	s_or_b64 exec, exec, s[0:1]
	s_bcnt1_i32_b64 s0, vcc
	v_cmp_eq_u32_e32 vcc, v131, v34
	s_add_i32 s2, s2, s0
	s_nop 0
	v_mbcnt_lo_u32_b32 v53, vcc_lo, 0
	v_mbcnt_hi_u32_b32 v53, vcc_hi, v53
	v_add_u32_e32 v53, s2, v53
	v_cmp_gt_i32_e64 s[4:5], s21, v53
	s_and_b64 s[4:5], vcc, s[4:5]
	s_and_saveexec_b64 s[0:1], s[4:5]
	v_lshl_add_u32 v53, v53, 2, s20
	ds_write_b32 v53, v69
	s_or_b64 exec, exec, s[0:1]
	s_bcnt1_i32_b64 s0, vcc
	v_cmp_eq_u32_e32 vcc, v132, v34
	s_add_i32 s2, s2, s0
	s_nop 0
	v_mbcnt_lo_u32_b32 v53, vcc_lo, 0
	v_mbcnt_hi_u32_b32 v53, vcc_hi, v53
	v_add_u32_e32 v53, s2, v53
	v_cmp_gt_i32_e64 s[4:5], s21, v53
	s_and_b64 s[4:5], vcc, s[4:5]
	s_and_saveexec_b64 s[0:1], s[4:5]
	v_lshl_add_u32 v53, v53, 2, s20
	ds_write_b32 v53, v70
	s_or_b64 exec, exec, s[0:1]
	s_bcnt1_i32_b64 s0, vcc
	v_cmp_eq_u32_e32 vcc, v130, v34
	s_add_i32 s2, s2, s0
	s_nop 0
	v_mbcnt_lo_u32_b32 v53, vcc_lo, 0
	v_mbcnt_hi_u32_b32 v53, vcc_hi, v53
	v_add_u32_e32 v53, s2, v53
	v_cmp_gt_i32_e64 s[4:5], s21, v53
	s_and_b64 s[4:5], vcc, s[4:5]
	s_and_saveexec_b64 s[0:1], s[4:5]
	v_lshl_add_u32 v53, v53, 2, s20
	ds_write_b32 v53, v71
	s_or_b64 exec, exec, s[0:1]
	s_bcnt1_i32_b64 s0, vcc
	v_cmp_eq_u32_e32 vcc, v128, v34
	s_add_i32 s2, s2, s0
	s_nop 0
	v_mbcnt_lo_u32_b32 v53, vcc_lo, 0
	v_mbcnt_hi_u32_b32 v53, vcc_hi, v53
	v_add_u32_e32 v53, s2, v53
	v_cmp_gt_i32_e64 s[4:5], s21, v53
	s_and_b64 s[4:5], vcc, s[4:5]
	s_and_saveexec_b64 s[0:1], s[4:5]
	v_lshl_add_u32 v53, v53, 2, s20
	ds_write_b32 v53, v72
	s_or_b64 exec, exec, s[0:1]
	s_bcnt1_i32_b64 s0, vcc
	v_cmp_eq_u32_e32 vcc, v129, v34
	s_add_i32 s2, s2, s0
	s_nop 0
	v_mbcnt_lo_u32_b32 v53, vcc_lo, 0
	v_mbcnt_hi_u32_b32 v53, vcc_hi, v53
	v_add_u32_e32 v53, s2, v53
	v_cmp_gt_i32_e64 s[4:5], s21, v53
	s_and_b64 s[4:5], vcc, s[4:5]
	s_and_saveexec_b64 s[0:1], s[4:5]
	v_lshl_add_u32 v53, v53, 2, s20
	ds_write_b32 v53, v73
	s_or_b64 exec, exec, s[0:1]
	s_bcnt1_i32_b64 s0, vcc
	v_cmp_eq_u32_e32 vcc, v62, v34
	s_add_i32 s2, s2, s0
	s_nop 0
	v_mbcnt_lo_u32_b32 v53, vcc_lo, 0
	v_mbcnt_hi_u32_b32 v53, vcc_hi, v53
	v_add_u32_e32 v53, s2, v53
	v_cmp_gt_i32_e64 s[4:5], s21, v53
	s_and_b64 s[4:5], vcc, s[4:5]
	s_and_saveexec_b64 s[0:1], s[4:5]
	v_lshl_add_u32 v53, v53, 2, s20
	ds_write_b32 v53, v74
	s_or_b64 exec, exec, s[0:1]
	s_bcnt1_i32_b64 s0, vcc
	v_cmp_eq_u32_e32 vcc, v58, v34
	s_add_i32 s2, s2, s0
	s_nop 0
	v_mbcnt_lo_u32_b32 v53, vcc_lo, 0
	v_mbcnt_hi_u32_b32 v53, vcc_hi, v53
	v_add_u32_e32 v53, s2, v53
	v_cmp_gt_i32_e64 s[4:5], s21, v53
	s_and_b64 s[4:5], vcc, s[4:5]
	s_and_saveexec_b64 s[0:1], s[4:5]
	v_lshl_add_u32 v53, v53, 2, s20
	ds_write_b32 v53, v75
	s_or_b64 exec, exec, s[0:1]
	s_bcnt1_i32_b64 s0, vcc
	v_cmp_eq_u32_e32 vcc, v56, v34
	s_add_i32 s2, s2, s0
	s_nop 0
	v_mbcnt_lo_u32_b32 v53, vcc_lo, 0
	v_mbcnt_hi_u32_b32 v53, vcc_hi, v53
	v_add_u32_e32 v53, s2, v53
	v_cmp_gt_i32_e64 s[4:5], s21, v53
	s_and_b64 s[4:5], vcc, s[4:5]
	s_and_saveexec_b64 s[0:1], s[4:5]
	v_lshl_add_u32 v53, v53, 2, s20
	ds_write_b32 v53, v76
; DI unsigned mbcnt64(unsigned long long m) { return __builtin_amdgcn_mbcnt_hi((unsigned)(m >> 32), __builtin_amdgcn_mbcnt_lo((unsigned)m, 0u)); }
; template <int NV>
; DI void topk_row(const float* row, int s, LAS int* lst, int lane) {
;     ...
;     for (int j = 0; j < NV; ++j) { const bool sg = key[j] > T; const unsigned long long mg = __ballot(sg); if (sg) lst[bgt + (int)mbcnt64(mg)] = j * 64 + lane; bgt += __builtin_popcountll(mg); }
; #pragma unroll
;     for (int j = 0; j < NV; ++j) { const bool se = key[j] == T; const unsigned long long me = __ballot(se); const int pe = bgt + (int)mbcnt64(me); if (se && pe < 256) lst[pe] = j * 64 + lane; bgt += __builtin_popcountll(me); }
	s_or_b64 exec, exec, s[0:1]
	s_bcnt1_i32_b64 s0, vcc
	v_cmp_eq_u32_e32 vcc, v52, v34
	s_add_i32 s2, s2, s0
	s_nop 0
	v_mbcnt_lo_u32_b32 v52, vcc_lo, 0
	v_mbcnt_hi_u32_b32 v52, vcc_hi, v52
	v_add_u32_e32 v52, s2, v52
	v_cmp_gt_i32_e64 s[4:5], s21, v52
	s_and_b64 s[4:5], vcc, s[4:5]
	s_and_saveexec_b64 s[0:1], s[4:5]
	v_lshl_add_u32 v52, v52, 2, s20
	ds_write_b32 v52, v77
	s_or_b64 exec, exec, s[0:1]
	s_bcnt1_i32_b64 s0, vcc
	v_cmp_eq_u32_e32 vcc, v50, v34
	s_add_i32 s2, s2, s0
	s_nop 0
	v_mbcnt_lo_u32_b32 v50, vcc_lo, 0
	v_mbcnt_hi_u32_b32 v50, vcc_hi, v50
	v_add_u32_e32 v50, s2, v50
	v_cmp_gt_i32_e64 s[4:5], s21, v50
	s_and_b64 s[4:5], vcc, s[4:5]
	s_and_saveexec_b64 s[0:1], s[4:5]
	v_lshl_add_u32 v50, v50, 2, s20
	ds_write_b32 v50, v78
	s_or_b64 exec, exec, s[0:1]
	s_bcnt1_i32_b64 s0, vcc
	v_cmp_eq_u32_e32 vcc, v49, v34
	s_add_i32 s2, s2, s0
	s_nop 0
	v_mbcnt_lo_u32_b32 v49, vcc_lo, 0
	v_mbcnt_hi_u32_b32 v49, vcc_hi, v49
	v_add_u32_e32 v49, s2, v49
	v_cmp_gt_i32_e64 s[4:5], s21, v49
	s_and_b64 s[4:5], vcc, s[4:5]
	s_and_saveexec_b64 s[0:1], s[4:5]
	v_lshl_add_u32 v49, v49, 2, s20
	ds_write_b32 v49, v79
	s_or_b64 exec, exec, s[0:1]
	s_bcnt1_i32_b64 s0, vcc
	v_cmp_eq_u32_e32 vcc, v48, v34
	s_add_i32 s2, s2, s0
	s_nop 0
	v_mbcnt_lo_u32_b32 v48, vcc_lo, 0
	v_mbcnt_hi_u32_b32 v48, vcc_hi, v48
	v_add_u32_e32 v48, s2, v48
	v_cmp_gt_i32_e64 s[4:5], s21, v48
	s_and_b64 s[4:5], vcc, s[4:5]
	s_and_saveexec_b64 s[0:1], s[4:5]
	v_lshl_add_u32 v48, v48, 2, s20
	ds_write_b32 v48, v80
	s_or_b64 exec, exec, s[0:1]
	s_bcnt1_i32_b64 s0, vcc
	v_cmp_eq_u32_e32 vcc, v51, v34
	s_add_i32 s2, s2, s0
	s_nop 0
	v_mbcnt_lo_u32_b32 v48, vcc_lo, 0
	v_mbcnt_hi_u32_b32 v48, vcc_hi, v48
	v_add_u32_e32 v48, s2, v48
	v_cmp_gt_i32_e64 s[4:5], s21, v48
	s_and_b64 s[4:5], vcc, s[4:5]
	s_and_saveexec_b64 s[0:1], s[4:5]
	v_lshl_add_u32 v48, v48, 2, s20
	ds_write_b32 v48, v81
	s_or_b64 exec, exec, s[0:1]
	s_bcnt1_i32_b64 s0, vcc
	v_cmp_eq_u32_e32 vcc, v47, v34
	s_add_i32 s2, s2, s0
	s_nop 0
	v_mbcnt_lo_u32_b32 v47, vcc_lo, 0
	v_mbcnt_hi_u32_b32 v47, vcc_hi, v47
	v_add_u32_e32 v47, s2, v47
	v_cmp_gt_i32_e64 s[4:5], s21, v47
	s_and_b64 s[4:5], vcc, s[4:5]
	s_and_saveexec_b64 s[0:1], s[4:5]
	v_lshl_add_u32 v47, v47, 2, s20
	ds_write_b32 v47, v82
	s_or_b64 exec, exec, s[0:1]
	s_bcnt1_i32_b64 s0, vcc
	v_cmp_eq_u32_e32 vcc, v46, v34
	s_add_i32 s2, s2, s0
	s_nop 0
	v_mbcnt_lo_u32_b32 v46, vcc_lo, 0
	v_mbcnt_hi_u32_b32 v46, vcc_hi, v46
	v_add_u32_e32 v46, s2, v46
	v_cmp_gt_i32_e64 s[4:5], s21, v46
	s_and_b64 s[4:5], vcc, s[4:5]
	s_and_saveexec_b64 s[0:1], s[4:5]
	v_lshl_add_u32 v46, v46, 2, s20
	ds_write_b32 v46, v83
	s_or_b64 exec, exec, s[0:1]
	s_bcnt1_i32_b64 s0, vcc
	v_cmp_eq_u32_e32 vcc, v45, v34
	s_add_i32 s2, s2, s0
	s_nop 0
	v_mbcnt_lo_u32_b32 v45, vcc_lo, 0
	v_mbcnt_hi_u32_b32 v45, vcc_hi, v45
	v_add_u32_e32 v45, s2, v45
	v_cmp_gt_i32_e64 s[4:5], s21, v45
	s_and_b64 s[4:5], vcc, s[4:5]
	s_and_saveexec_b64 s[0:1], s[4:5]
	v_lshl_add_u32 v45, v45, 2, s20
	ds_write_b32 v45, v84
	s_or_b64 exec, exec, s[0:1]
	s_bcnt1_i32_b64 s0, vcc
	v_cmp_eq_u32_e32 vcc, v44, v34
	s_add_i32 s2, s2, s0
	s_nop 0
	v_mbcnt_lo_u32_b32 v44, vcc_lo, 0
	v_mbcnt_hi_u32_b32 v44, vcc_hi, v44
	v_add_u32_e32 v44, s2, v44
	v_cmp_gt_i32_e64 s[4:5], s21, v44
	s_and_b64 s[4:5], vcc, s[4:5]
	s_and_saveexec_b64 s[0:1], s[4:5]
	v_lshl_add_u32 v44, v44, 2, s20
	ds_write_b32 v44, v85
	s_or_b64 exec, exec, s[0:1]
	s_bcnt1_i32_b64 s0, vcc
	v_cmp_eq_u32_e32 vcc, v43, v34
	s_add_i32 s2, s2, s0
	s_nop 0
	v_mbcnt_lo_u32_b32 v43, vcc_lo, 0
	v_mbcnt_hi_u32_b32 v43, vcc_hi, v43
	v_add_u32_e32 v43, s2, v43
	v_cmp_gt_i32_e64 s[4:5], s21, v43
	s_and_b64 s[4:5], vcc, s[4:5]
	s_and_saveexec_b64 s[0:1], s[4:5]
	v_lshl_add_u32 v43, v43, 2, s20
	ds_write_b32 v43, v86
	s_or_b64 exec, exec, s[0:1]
	s_bcnt1_i32_b64 s0, vcc
	v_cmp_eq_u32_e32 vcc, v42, v34
	s_add_i32 s2, s2, s0
	s_nop 0
	v_mbcnt_lo_u32_b32 v42, vcc_lo, 0
	v_mbcnt_hi_u32_b32 v42, vcc_hi, v42
	v_add_u32_e32 v42, s2, v42
	v_cmp_gt_i32_e64 s[4:5], s21, v42
	s_and_b64 s[4:5], vcc, s[4:5]
	s_and_saveexec_b64 s[0:1], s[4:5]
	v_lshl_add_u32 v42, v42, 2, s20
	ds_write_b32 v42, v87
	s_or_b64 exec, exec, s[0:1]
	s_bcnt1_i32_b64 s0, vcc
	v_cmp_eq_u32_e32 vcc, v41, v34
	s_add_i32 s2, s2, s0
	s_nop 0
	v_mbcnt_lo_u32_b32 v41, vcc_lo, 0
	v_mbcnt_hi_u32_b32 v41, vcc_hi, v41
	v_add_u32_e32 v41, s2, v41
	v_cmp_gt_i32_e64 s[4:5], s21, v41
	s_and_b64 s[4:5], vcc, s[4:5]
	s_and_saveexec_b64 s[0:1], s[4:5]
	v_lshl_add_u32 v41, v41, 2, s20
	ds_write_b32 v41, v88
	s_or_b64 exec, exec, s[0:1]
	s_bcnt1_i32_b64 s0, vcc
	v_cmp_eq_u32_e32 vcc, v40, v34
	s_add_i32 s2, s2, s0
	s_nop 0
	v_mbcnt_lo_u32_b32 v40, vcc_lo, 0
	v_mbcnt_hi_u32_b32 v40, vcc_hi, v40
	v_add_u32_e32 v40, s2, v40
	v_cmp_gt_i32_e64 s[4:5], s21, v40
	s_and_b64 s[4:5], vcc, s[4:5]
	s_and_saveexec_b64 s[0:1], s[4:5]
	v_lshl_add_u32 v40, v40, 2, s20
	ds_write_b32 v40, v89
	s_or_b64 exec, exec, s[0:1]
	s_bcnt1_i32_b64 s0, vcc
	v_cmp_eq_u32_e32 vcc, v39, v34
	s_add_i32 s2, s2, s0
	s_nop 0
	v_mbcnt_lo_u32_b32 v39, vcc_lo, 0
	v_mbcnt_hi_u32_b32 v39, vcc_hi, v39
	v_add_u32_e32 v39, s2, v39
	v_cmp_gt_i32_e64 s[4:5], s21, v39
	s_and_b64 s[4:5], vcc, s[4:5]
	s_and_saveexec_b64 s[0:1], s[4:5]
	v_lshl_add_u32 v39, v39, 2, s20
	ds_write_b32 v39, v90
	s_or_b64 exec, exec, s[0:1]
	s_bcnt1_i32_b64 s0, vcc
	v_cmp_eq_u32_e32 vcc, v38, v34
	s_add_i32 s2, s2, s0
	s_nop 0
	v_mbcnt_lo_u32_b32 v38, vcc_lo, 0
	v_mbcnt_hi_u32_b32 v38, vcc_hi, v38
	v_add_u32_e32 v38, s2, v38
	v_cmp_gt_i32_e64 s[4:5], s21, v38
	s_and_b64 s[4:5], vcc, s[4:5]
	s_and_saveexec_b64 s[0:1], s[4:5]
	v_lshl_add_u32 v38, v38, 2, s20
	ds_write_b32 v38, v91
	s_or_b64 exec, exec, s[0:1]
	s_bcnt1_i32_b64 s0, vcc
	v_cmp_eq_u32_e32 vcc, v37, v34
	s_add_i32 s2, s2, s0
	s_nop 0
	v_mbcnt_lo_u32_b32 v37, vcc_lo, 0
	v_mbcnt_hi_u32_b32 v37, vcc_hi, v37
	v_add_u32_e32 v37, s2, v37
	v_cmp_gt_i32_e64 s[4:5], s21, v37
	s_and_b64 s[4:5], vcc, s[4:5]
	s_and_saveexec_b64 s[0:1], s[4:5]
	v_lshl_add_u32 v37, v37, 2, s20
	ds_write_b32 v37, v92
	s_or_b64 exec, exec, s[0:1]
	s_bcnt1_i32_b64 s0, vcc
	v_cmp_eq_u32_e32 vcc, v36, v34
	s_add_i32 s2, s2, s0
	s_nop 0
	v_mbcnt_lo_u32_b32 v36, vcc_lo, 0
	v_mbcnt_hi_u32_b32 v36, vcc_hi, v36
	v_add_u32_e32 v36, s2, v36
	v_cmp_gt_i32_e64 s[4:5], s21, v36
	s_and_b64 s[4:5], vcc, s[4:5]
	s_and_saveexec_b64 s[0:1], s[4:5]
	v_lshl_add_u32 v36, v36, 2, s20
	ds_write_b32 v36, v93
	s_or_b64 exec, exec, s[0:1]
	s_bcnt1_i32_b64 s0, vcc
	v_cmp_eq_u32_e32 vcc, v35, v34
	s_add_i32 s2, s2, s0
	s_nop 0
	v_mbcnt_lo_u32_b32 v35, vcc_lo, 0
	v_mbcnt_hi_u32_b32 v35, vcc_hi, v35
	v_add_u32_e32 v35, s2, v35
	v_cmp_gt_i32_e64 s[4:5], s21, v35
	s_and_b64 s[4:5], vcc, s[4:5]
	s_and_saveexec_b64 s[0:1], s[4:5]
	v_lshl_add_u32 v35, v35, 2, s20
	ds_write_b32 v35, v94
	s_or_b64 exec, exec, s[0:1]
	s_bcnt1_i32_b64 s0, vcc
	v_cmp_eq_u32_e32 vcc, v0, v34
	s_add_i32 s2, s2, s0
	v_mov_b32_e32 v34, v95
	v_mbcnt_lo_u32_b32 v0, vcc_lo, 0
	v_mbcnt_hi_u32_b32 v0, vcc_hi, v0
	v_add_u32_e32 v0, s2, v0
	v_cmp_gt_i32_e64 s[4:5], s21, v0
	s_and_b64 s[0:1], vcc, s[4:5]

; DI unsigned mbcnt64(unsigned long long m) { return __builtin_amdgcn_mbcnt_hi((unsigned)(m >> 32), __builtin_amdgcn_mbcnt_lo((unsigned)m, 0u)); }
; template <int NV>
; DI void topk_row(const float* row, int s, LAS int* lst, int lane) {
;     ...
;     int bgt = 0;
; #pragma unroll
;     for (int j = 0; j < NV; ++j) { const bool sg = key[j] > T; const unsigned long long mg = __ballot(sg); if (sg) lst[bgt + (int)mbcnt64(mg)] = j * 64 + lane; bgt += __builtin_popcountll(mg); }
; #pragma unroll
;     for (int j = 0; j < NV; ++j) { const bool se = key[j] == T; const unsigned long long me = __ballot(se); const int pe = bgt + (int)mbcnt64(me); if (se && pe < 256) lst[pe] = j * 64 + lane; bgt += __builtin_popcountll(me); }
.LBB0_3194:
	s_or_b64 exec, exec, s[0:1]
	s_bcnt1_i32_b64 s0, vcc
	v_cmp_eq_u32_e32 vcc, v44, v129
	s_add_i32 s2, s2, s0
	s_cmpk_eq_i32 s2, 0x100
	s_cbranch_scc1 .Lp12_skip2_3
	s_nop 0
	v_mbcnt_lo_u32_b32 v44, vcc_lo, 0
	v_mbcnt_hi_u32_b32 v44, vcc_hi, v44
	v_add_u32_e32 v44, s2, v44
	v_cmp_gt_i32_e64 s[4:5], s21, v44
	s_and_b64 s[4:5], vcc, s[4:5]
	s_and_saveexec_b64 s[0:1], s[4:5]
	v_lshl_add_u32 v44, v44, 2, s20
	ds_write_b32 v44, v2
	s_or_b64 exec, exec, s[0:1]
	s_bcnt1_i32_b64 s0, vcc
	v_cmp_eq_u32_e32 vcc, v43, v129
	s_add_i32 s2, s2, s0
	s_nop 0
	v_mbcnt_lo_u32_b32 v43, vcc_lo, 0
	v_mbcnt_hi_u32_b32 v43, vcc_hi, v43
	v_add_u32_e32 v43, s2, v43
	v_cmp_gt_i32_e64 s[4:5], s21, v43
	s_and_b64 s[4:5], vcc, s[4:5]
	s_and_saveexec_b64 s[0:1], s[4:5]
	v_lshl_add_u32 v43, v43, 2, s20
	ds_write_b32 v43, v4
	s_or_b64 exec, exec, s[0:1]
	s_bcnt1_i32_b64 s0, vcc
	v_cmp_eq_u32_e32 vcc, v42, v129
	s_add_i32 s2, s2, s0
	s_nop 0
	v_mbcnt_lo_u32_b32 v42, vcc_lo, 0
	v_mbcnt_hi_u32_b32 v42, vcc_hi, v42
	v_add_u32_e32 v42, s2, v42
	v_cmp_gt_i32_e64 s[4:5], s21, v42
	s_and_b64 s[4:5], vcc, s[4:5]
	s_and_saveexec_b64 s[0:1], s[4:5]
	v_lshl_add_u32 v42, v42, 2, s20
	ds_write_b32 v42, v6
	s_or_b64 exec, exec, s[0:1]
	s_bcnt1_i32_b64 s0, vcc
	v_cmp_eq_u32_e32 vcc, v41, v129
	s_add_i32 s2, s2, s0
	s_nop 0
	v_mbcnt_lo_u32_b32 v41, vcc_lo, 0
	v_mbcnt_hi_u32_b32 v41, vcc_hi, v41
	v_add_u32_e32 v41, s2, v41
	v_cmp_gt_i32_e64 s[4:5], s21, v41
	s_and_b64 s[4:5], vcc, s[4:5]
	s_and_saveexec_b64 s[0:1], s[4:5]
	v_lshl_add_u32 v41, v41, 2, s20
	ds_write_b32 v41, v8
	s_or_b64 exec, exec, s[0:1]
	s_bcnt1_i32_b64 s0, vcc
	v_cmp_eq_u32_e32 vcc, v40, v129
	s_add_i32 s2, s2, s0
	s_nop 0
	v_mbcnt_lo_u32_b32 v40, vcc_lo, 0
	v_mbcnt_hi_u32_b32 v40, vcc_hi, v40
	v_add_u32_e32 v40, s2, v40
	v_cmp_gt_i32_e64 s[4:5], s21, v40
	s_and_b64 s[4:5], vcc, s[4:5]
	s_and_saveexec_b64 s[0:1], s[4:5]
	v_lshl_add_u32 v40, v40, 2, s20
	ds_write_b32 v40, v10
	s_or_b64 exec, exec, s[0:1]
	s_bcnt1_i32_b64 s0, vcc
	v_cmp_eq_u32_e32 vcc, v39, v129
	s_add_i32 s2, s2, s0
	s_nop 0
	v_mbcnt_lo_u32_b32 v39, vcc_lo, 0
	v_mbcnt_hi_u32_b32 v39, vcc_hi, v39
	v_add_u32_e32 v39, s2, v39
	v_cmp_gt_i32_e64 s[4:5], s21, v39
	s_and_b64 s[4:5], vcc, s[4:5]
	s_and_saveexec_b64 s[0:1], s[4:5]
	v_lshl_add_u32 v39, v39, 2, s20
	ds_write_b32 v39, v12
	s_or_b64 exec, exec, s[0:1]
	s_bcnt1_i32_b64 s0, vcc
	v_cmp_eq_u32_e32 vcc, v38, v129
	s_add_i32 s2, s2, s0
	s_nop 0
	v_mbcnt_lo_u32_b32 v38, vcc_lo, 0
	v_mbcnt_hi_u32_b32 v38, vcc_hi, v38
	v_add_u32_e32 v38, s2, v38
	v_cmp_gt_i32_e64 s[4:5], s21, v38
	s_and_b64 s[4:5], vcc, s[4:5]
	s_and_saveexec_b64 s[0:1], s[4:5]
	v_lshl_add_u32 v38, v38, 2, s20
	ds_write_b32 v38, v14
	s_or_b64 exec, exec, s[0:1]
	s_bcnt1_i32_b64 s0, vcc
	v_cmp_eq_u32_e32 vcc, v37, v129
	s_add_i32 s2, s2, s0
	s_nop 0
	v_mbcnt_lo_u32_b32 v37, vcc_lo, 0
	v_mbcnt_hi_u32_b32 v37, vcc_hi, v37
	v_add_u32_e32 v37, s2, v37
	v_cmp_gt_i32_e64 s[4:5], s21, v37
	s_and_b64 s[4:5], vcc, s[4:5]
	s_and_saveexec_b64 s[0:1], s[4:5]
	v_lshl_add_u32 v37, v37, 2, s20
	ds_write_b32 v37, v16
	s_or_b64 exec, exec, s[0:1]
	s_bcnt1_i32_b64 s0, vcc
	v_cmp_eq_u32_e32 vcc, v36, v129
	s_add_i32 s2, s2, s0
	s_nop 0
	v_mbcnt_lo_u32_b32 v36, vcc_lo, 0
	v_mbcnt_hi_u32_b32 v36, vcc_hi, v36
	v_add_u32_e32 v36, s2, v36
	v_cmp_gt_i32_e64 s[4:5], s21, v36
	s_and_b64 s[4:5], vcc, s[4:5]
	s_and_saveexec_b64 s[0:1], s[4:5]
	v_lshl_add_u32 v36, v36, 2, s20
	ds_write_b32 v36, v18
	s_or_b64 exec, exec, s[0:1]
	s_bcnt1_i32_b64 s0, vcc
	v_cmp_eq_u32_e32 vcc, v35, v129
	s_add_i32 s2, s2, s0
	s_nop 0
	v_mbcnt_lo_u32_b32 v35, vcc_lo, 0
	v_mbcnt_hi_u32_b32 v35, vcc_hi, v35
	v_add_u32_e32 v35, s2, v35
	v_cmp_gt_i32_e64 s[4:5], s21, v35
	s_and_b64 s[4:5], vcc, s[4:5]
	s_and_saveexec_b64 s[0:1], s[4:5]
	v_lshl_add_u32 v35, v35, 2, s20
	ds_write_b32 v35, v20
	s_or_b64 exec, exec, s[0:1]
	s_bcnt1_i32_b64 s0, vcc
	v_cmp_eq_u32_e32 vcc, v34, v129
	s_add_i32 s2, s2, s0
	s_nop 0
	v_mbcnt_lo_u32_b32 v34, vcc_lo, 0
	v_mbcnt_hi_u32_b32 v34, vcc_hi, v34
	v_add_u32_e32 v34, s2, v34
	v_cmp_gt_i32_e64 s[4:5], s21, v34
	s_and_b64 s[4:5], vcc, s[4:5]
	s_and_saveexec_b64 s[0:1], s[4:5]
	v_lshl_add_u32 v34, v34, 2, s20
	ds_write_b32 v34, v22
	s_or_b64 exec, exec, s[0:1]
	s_bcnt1_i32_b64 s0, vcc
	v_cmp_eq_u32_e32 vcc, v45, v129
	s_add_i32 s2, s2, s0
	s_nop 0
	v_mbcnt_lo_u32_b32 v34, vcc_lo, 0
	v_mbcnt_hi_u32_b32 v34, vcc_hi, v34
	v_add_u32_e32 v34, s2, v34
	v_cmp_gt_i32_e64 s[4:5], s21, v34
	s_and_b64 s[4:5], vcc, s[4:5]
	s_and_saveexec_b64 s[0:1], s[4:5]
	v_lshl_add_u32 v34, v34, 2, s20
	ds_write_b32 v34, v24
	s_or_b64 exec, exec, s[0:1]
	s_bcnt1_i32_b64 s0, vcc
	v_cmp_eq_u32_e32 vcc, v46, v129
	s_add_i32 s2, s2, s0
	s_nop 0
	v_mbcnt_lo_u32_b32 v34, vcc_lo, 0
	v_mbcnt_hi_u32_b32 v34, vcc_hi, v34
	v_add_u32_e32 v34, s2, v34
	v_cmp_gt_i32_e64 s[4:5], s21, v34
	s_and_b64 s[4:5], vcc, s[4:5]
	s_and_saveexec_b64 s[0:1], s[4:5]
	v_lshl_add_u32 v34, v34, 2, s20
	ds_write_b32 v34, v26
	s_or_b64 exec, exec, s[0:1]
	s_bcnt1_i32_b64 s0, vcc
	v_cmp_eq_u32_e32 vcc, v47, v129
	s_add_i32 s2, s2, s0
	s_nop 0
	v_mbcnt_lo_u32_b32 v34, vcc_lo, 0
	v_mbcnt_hi_u32_b32 v34, vcc_hi, v34
	v_add_u32_e32 v34, s2, v34
	v_cmp_gt_i32_e64 s[4:5], s21, v34
	s_and_b64 s[4:5], vcc, s[4:5]
	s_and_saveexec_b64 s[0:1], s[4:5]
	v_lshl_add_u32 v34, v34, 2, s20
	ds_write_b32 v34, v28
	s_or_b64 exec, exec, s[0:1]
	s_bcnt1_i32_b64 s0, vcc
	v_cmp_eq_u32_e32 vcc, v48, v129
	s_add_i32 s2, s2, s0
	s_nop 0
	v_mbcnt_lo_u32_b32 v34, vcc_lo, 0
	v_mbcnt_hi_u32_b32 v34, vcc_hi, v34
	v_add_u32_e32 v34, s2, v34
	v_cmp_gt_i32_e64 s[4:5], s21, v34
	s_and_b64 s[4:5], vcc, s[4:5]
	s_and_saveexec_b64 s[0:1], s[4:5]
; DI unsigned mbcnt64(unsigned long long m) { return __builtin_amdgcn_mbcnt_hi((unsigned)(m >> 32), __builtin_amdgcn_mbcnt_lo((unsigned)m, 0u)); }
; template <int NV>
; DI void topk_row(const float* row, int s, LAS int* lst, int lane) {
;     ...
;     for (int j = 0; j < NV; ++j) { const bool se = key[j] == T; const unsigned long long me = __ballot(se); const int pe = bgt + (int)mbcnt64(me); if (se && pe < 256) lst[pe] = j * 64 + lane; bgt += __builtin_popcountll(me); }
	v_lshl_add_u32 v34, v34, 2, s20
	ds_write_b32 v34, v30
	s_or_b64 exec, exec, s[0:1]
	s_bcnt1_i32_b64 s0, vcc
	v_cmp_eq_u32_e32 vcc, v51, v129
	s_add_i32 s2, s2, s0
	s_nop 0
	v_mbcnt_lo_u32_b32 v34, vcc_lo, 0
	v_mbcnt_hi_u32_b32 v34, vcc_hi, v34
	v_add_u32_e32 v34, s2, v34
	v_cmp_gt_i32_e64 s[4:5], s21, v34
	s_and_b64 s[4:5], vcc, s[4:5]
	s_and_saveexec_b64 s[0:1], s[4:5]
	v_lshl_add_u32 v34, v34, 2, s20
	ds_write_b32 v34, v32
	s_or_b64 exec, exec, s[0:1]
	s_bcnt1_i32_b64 s0, vcc
	v_cmp_eq_u32_e32 vcc, v57, v129
	s_add_i32 s2, s2, s0
	s_nop 0
	v_mbcnt_lo_u32_b32 v34, vcc_lo, 0
	v_mbcnt_hi_u32_b32 v34, vcc_hi, v34
	v_add_u32_e32 v34, s2, v34
	v_cmp_gt_i32_e64 s[4:5], s21, v34
	s_and_b64 s[4:5], vcc, s[4:5]
	s_and_saveexec_b64 s[0:1], s[4:5]
	v_lshl_add_u32 v34, v34, 2, s20
	ds_write_b32 v34, v3
	s_or_b64 exec, exec, s[0:1]
	s_bcnt1_i32_b64 s0, vcc
	v_cmp_eq_u32_e32 vcc, v63, v129
	s_add_i32 s2, s2, s0
	s_nop 0
	v_mbcnt_lo_u32_b32 v34, vcc_lo, 0
	v_mbcnt_hi_u32_b32 v34, vcc_hi, v34
	v_add_u32_e32 v34, s2, v34
	v_cmp_gt_i32_e64 s[4:5], s21, v34
	s_and_b64 s[4:5], vcc, s[4:5]
	s_and_saveexec_b64 s[0:1], s[4:5]
	v_lshl_add_u32 v34, v34, 2, s20
	ds_write_b32 v34, v5
	s_or_b64 exec, exec, s[0:1]
	s_bcnt1_i32_b64 s0, vcc
	v_cmp_eq_u32_e32 vcc, v62, v129
	s_add_i32 s2, s2, s0
	s_nop 0
	v_mbcnt_lo_u32_b32 v34, vcc_lo, 0
	v_mbcnt_hi_u32_b32 v34, vcc_hi, v34
	v_add_u32_e32 v34, s2, v34
	v_cmp_gt_i32_e64 s[4:5], s21, v34
	s_and_b64 s[4:5], vcc, s[4:5]
	s_and_saveexec_b64 s[0:1], s[4:5]
	v_lshl_add_u32 v34, v34, 2, s20
	ds_write_b32 v34, v7
	s_or_b64 exec, exec, s[0:1]
	s_bcnt1_i32_b64 s0, vcc
	v_cmp_eq_u32_e32 vcc, v61, v129
	s_add_i32 s2, s2, s0
	s_nop 0
	v_mbcnt_lo_u32_b32 v34, vcc_lo, 0
	v_mbcnt_hi_u32_b32 v34, vcc_hi, v34
	v_add_u32_e32 v34, s2, v34
	v_cmp_gt_i32_e64 s[4:5], s21, v34
	s_and_b64 s[4:5], vcc, s[4:5]
	s_and_saveexec_b64 s[0:1], s[4:5]
	v_lshl_add_u32 v34, v34, 2, s20
	ds_write_b32 v34, v9
	s_or_b64 exec, exec, s[0:1]
	s_bcnt1_i32_b64 s0, vcc
	v_cmp_eq_u32_e32 vcc, v60, v129
	s_add_i32 s2, s2, s0
	s_nop 0
	v_mbcnt_lo_u32_b32 v34, vcc_lo, 0
	v_mbcnt_hi_u32_b32 v34, vcc_hi, v34
	v_add_u32_e32 v34, s2, v34
	v_cmp_gt_i32_e64 s[4:5], s21, v34
	s_and_b64 s[4:5], vcc, s[4:5]
	s_and_saveexec_b64 s[0:1], s[4:5]
	v_lshl_add_u32 v34, v34, 2, s20
	ds_write_b32 v34, v11
	s_or_b64 exec, exec, s[0:1]
	s_bcnt1_i32_b64 s0, vcc
	v_cmp_eq_u32_e32 vcc, v59, v129
	s_add_i32 s2, s2, s0
	s_nop 0
	v_mbcnt_lo_u32_b32 v34, vcc_lo, 0
	v_mbcnt_hi_u32_b32 v34, vcc_hi, v34
	v_add_u32_e32 v34, s2, v34
	v_cmp_gt_i32_e64 s[4:5], s21, v34
	s_and_b64 s[4:5], vcc, s[4:5]
	s_and_saveexec_b64 s[0:1], s[4:5]
	v_lshl_add_u32 v34, v34, 2, s20
	ds_write_b32 v34, v13
	s_or_b64 exec, exec, s[0:1]
	s_bcnt1_i32_b64 s0, vcc
	v_cmp_eq_u32_e32 vcc, v58, v129
	s_add_i32 s2, s2, s0
	s_nop 0
	v_mbcnt_lo_u32_b32 v34, vcc_lo, 0
	v_mbcnt_hi_u32_b32 v34, vcc_hi, v34
	v_add_u32_e32 v34, s2, v34
	v_cmp_gt_i32_e64 s[4:5], s21, v34
	s_and_b64 s[4:5], vcc, s[4:5]
	s_and_saveexec_b64 s[0:1], s[4:5]
	v_lshl_add_u32 v34, v34, 2, s20
	ds_write_b32 v34, v15
	s_or_b64 exec, exec, s[0:1]
	s_bcnt1_i32_b64 s0, vcc
	v_cmp_eq_u32_e32 vcc, v56, v129
	s_add_i32 s2, s2, s0
	s_nop 0
	v_mbcnt_lo_u32_b32 v34, vcc_lo, 0
	v_mbcnt_hi_u32_b32 v34, vcc_hi, v34
	v_add_u32_e32 v34, s2, v34
	v_cmp_gt_i32_e64 s[4:5], s21, v34
	s_and_b64 s[4:5], vcc, s[4:5]
	s_and_saveexec_b64 s[0:1], s[4:5]
	v_lshl_add_u32 v34, v34, 2, s20
	ds_write_b32 v34, v17
	s_or_b64 exec, exec, s[0:1]
	s_bcnt1_i32_b64 s0, vcc
	v_cmp_eq_u32_e32 vcc, v55, v129
	s_add_i32 s2, s2, s0
	s_nop 0
	v_mbcnt_lo_u32_b32 v34, vcc_lo, 0
	v_mbcnt_hi_u32_b32 v34, vcc_hi, v34
	v_add_u32_e32 v34, s2, v34
	v_cmp_gt_i32_e64 s[4:5], s21, v34
	s_and_b64 s[4:5], vcc, s[4:5]
	s_and_saveexec_b64 s[0:1], s[4:5]
	v_lshl_add_u32 v34, v34, 2, s20
	ds_write_b32 v34, v19
	s_or_b64 exec, exec, s[0:1]
	s_bcnt1_i32_b64 s0, vcc
	v_cmp_eq_u32_e32 vcc, v54, v129
	s_add_i32 s2, s2, s0
	s_nop 0
	v_mbcnt_lo_u32_b32 v34, vcc_lo, 0
	v_mbcnt_hi_u32_b32 v34, vcc_hi, v34
	v_add_u32_e32 v34, s2, v34
	v_cmp_gt_i32_e64 s[4:5], s21, v34
	s_and_b64 s[4:5], vcc, s[4:5]
	s_and_saveexec_b64 s[0:1], s[4:5]
	v_lshl_add_u32 v34, v34, 2, s20
	ds_write_b32 v34, v21
	s_or_b64 exec, exec, s[0:1]
	s_bcnt1_i32_b64 s0, vcc
	v_cmp_eq_u32_e32 vcc, v53, v129
	s_add_i32 s2, s2, s0
	s_nop 0
	v_mbcnt_lo_u32_b32 v34, vcc_lo, 0
	v_mbcnt_hi_u32_b32 v34, vcc_hi, v34
	v_add_u32_e32 v34, s2, v34
	v_cmp_gt_i32_e64 s[4:5], s21, v34
	s_and_b64 s[4:5], vcc, s[4:5]
	s_and_saveexec_b64 s[0:1], s[4:5]
	v_lshl_add_u32 v34, v34, 2, s20
	ds_write_b32 v34, v23
	s_or_b64 exec, exec, s[0:1]
	s_bcnt1_i32_b64 s0, vcc
	v_cmp_eq_u32_e32 vcc, v52, v129
	s_add_i32 s2, s2, s0
	s_nop 0
	v_mbcnt_lo_u32_b32 v34, vcc_lo, 0
	v_mbcnt_hi_u32_b32 v34, vcc_hi, v34
	v_add_u32_e32 v34, s2, v34
	v_cmp_gt_i32_e64 s[4:5], s21, v34
	s_and_b64 s[4:5], vcc, s[4:5]
	s_and_saveexec_b64 s[0:1], s[4:5]
	v_lshl_add_u32 v34, v34, 2, s20
	ds_write_b32 v34, v25
	s_or_b64 exec, exec, s[0:1]
	s_bcnt1_i32_b64 s0, vcc
	v_cmp_eq_u32_e32 vcc, v50, v129
	s_add_i32 s2, s2, s0
	s_nop 0
	v_mbcnt_lo_u32_b32 v34, vcc_lo, 0
	v_mbcnt_hi_u32_b32 v34, vcc_hi, v34
	v_add_u32_e32 v34, s2, v34
	v_cmp_gt_i32_e64 s[4:5], s21, v34
	s_and_b64 s[4:5], vcc, s[4:5]
	s_and_saveexec_b64 s[0:1], s[4:5]
	v_lshl_add_u32 v34, v34, 2, s20
	ds_write_b32 v34, v27
	s_or_b64 exec, exec, s[0:1]
	s_bcnt1_i32_b64 s0, vcc
	v_cmp_eq_u32_e32 vcc, v49, v129
	s_add_i32 s2, s2, s0
	s_nop 0
	v_mbcnt_lo_u32_b32 v34, vcc_lo, 0
	v_mbcnt_hi_u32_b32 v34, vcc_hi, v34
	v_add_u32_e32 v34, s2, v34
	v_cmp_gt_i32_e64 s[4:5], s21, v34
	s_and_b64 s[4:5], vcc, s[4:5]
	s_and_saveexec_b64 s[0:1], s[4:5]
	v_lshl_add_u32 v34, v34, 2, s20
	ds_write_b32 v34, v29
	s_or_b64 exec, exec, s[0:1]
	s_bcnt1_i32_b64 s0, vcc
	v_cmp_eq_u32_e32 vcc, v0, v129
	s_add_i32 s2, s2, s0
	s_nop 0
	v_mbcnt_lo_u32_b32 v0, vcc_lo, 0
	v_mbcnt_hi_u32_b32 v0, vcc_hi, v0
	v_add_u32_e32 v0, s2, v0
	v_cmp_gt_i32_e64 s[4:5], s21, v0
	s_and_b64 s[4:5], vcc, s[4:5]
	s_and_saveexec_b64 s[0:1], s[4:5]
	v_lshl_add_u32 v0, v0, 2, s20
	ds_write_b32 v0, v31
	s_or_b64 exec, exec, s[0:1]
	s_bcnt1_i32_b64 s0, vcc
	v_cmp_eq_u32_e32 vcc, v128, v129
	s_add_i32 s2, s2, s0
	v_mov_b32_e32 v34, v33
	v_mbcnt_lo_u32_b32 v0, vcc_lo, 0
	v_mbcnt_hi_u32_b32 v0, vcc_hi, v0
	v_add_u32_e32 v0, s2, v0
	v_cmp_gt_i32_e64 s[4:5], s21, v0
	s_and_b64 s[0:1], vcc, s[4:5]
